# GEMM K-loops: per-phase s_setprio toggles removed; one static s_setprio 1 for the wr==1 (younger) wave half per GEMM phase
# speedup vs baseline: 1.0075x; 1.0075x over previous
; #define LAS __attribute__((address_space(3)))
; DI unsigned char* ARGWS(const Ctx& C) { return (unsigned char*)ARGP(C, 22); }
; DI unsigned xb_ld(unsigned* p)              { return __hip_atomic_load(p, __ATOMIC_RELAXED, __HIP_MEMORY_SCOPE_AGENT); }
; DI unsigned xb_xcc_id() { return (unsigned)__builtin_amdgcn_s_getreg((3 << 11) | 20) & 0xFu; }
; #define REFRESH_CTX() do { int l_, w_ = wave_s, b_ = blockIdx.x, g_ = gridDim.x; \
;         asm volatile("v_mbcnt_lo_u32_b32 %0, -1, 0\n\tv_mbcnt_hi_u32_b32 %0, -1, %0" : "=v"(l_)); asm volatile("" : "+s"(w_), "+s"(b_), "+s"(g_)); \
;         C.tid = w_ * 64 + l_; C.lane = l_; C.wave = w_; C.G = g_; C.bid = b_; } while (0)
; DI void xcd_barrier_complete(unsigned* bar, unsigned x, unsigned G, unsigned& nloc, unsigned& nx) {
;     unsigned sum, cnt, mine, sp = 0u;
;     for (;;) {
;         sum = 0u; cnt = 0u; mine = 0u;
; #pragma unroll
;         for (unsigned j = 0; j < 16; ++j) { const unsigned c = xb_ld(&bar[XB_XCNT(j)]); sum += c; cnt += (c > 0u) ? 1u : 0u; mine = (j == x) ? c : mine; }
;         if (sum == G) break;
;         __builtin_amdgcn_s_sleep(1);
;         if ((++sp & 255u) == 0u) { if (xb_ld(&bar[XB_TMO])) break; if (sp > XB_SPIN_CAP) { atomicAdd(&bar[XB_TMO], 1u); break; } }
;     }
;     nloc = mine > 0u ? mine : 1u; nx = cnt > 0u ? cnt : 1u;
; }
; DI void grid_barrier(const Ctx& C, unsigned* bar, volatile LAS unsigned* st) {
;     asm volatile("s_waitcnt vmcnt(0)" ::: "memory");
;     __syncthreads();
;     if (C.tid == 0) {
;         const unsigned x = xb_xcc_id();
;         __builtin_amdgcn_s_waitcnt(0);
;         unsigned nloc = st[0], nx = st[1];
;         if (nloc == 0u) { xcd_barrier_complete(bar, x, (unsigned)C.G, nloc, nx); st[0] = nloc; st[1] = nx; }
; __global__ void __launch_bounds__(NTHREADS, 2) fwd_kernel(Args A) {
;     ...
;     for (int ph = ph_lo; ph < ph_hi; ++ph) {
;         REFRESH_CTX();
;         if (ph > ph_lo) grid_barrier(C, (unsigned*)(ARGWS(C) + WS_BAR), (volatile LAS unsigned*)(C.lds + ARG_OFF + 512));
.LBB0_22:
	s_setprio 0
	s_mov_b32 s46, s65
	s_mov_b32 s33, s63
	s_mov_b32 s2, s97
	v_mbcnt_lo_u32_b32 v204, -1, 0
	v_mbcnt_hi_u32_b32 v204, -1, v204
	s_cmp_le_i32 s79, s64
	v_lshl_add_u32 v202, s46, 6, v204
	s_cbranch_scc1 .LBB0_68
	v_mov_b32_e32 v0, s66
	v_mov_b32_e32 v2, s96
	ds_read_b32 v0, v0
	ds_read_b32 v2, v2
	s_waitcnt vmcnt(0)
	v_cmp_eq_u32_e32 vcc, 0, v202
	s_waitcnt lgkmcnt(0)
	v_readfirstlane_b32 s34, v0
	v_readfirstlane_b32 s35, v2
	s_barrier
	s_and_saveexec_b64 s[80:81], vcc
	s_cbranch_execz .LBB0_67
	v_readlane_b32 s1, v249, 5
	s_getreg_b32 s0, hwreg(HW_REG_XCC_ID, 0, 4)
	s_waitcnt vmcnt(0) expcnt(0) lgkmcnt(0)
	v_mov_b32_e32 v0, s1
	ds_read_b32 v2, v0
	v_readlane_b32 s1, v249, 6
	s_and_b32 s36, s0, 15
	s_waitcnt lgkmcnt(0)
	v_cmp_ne_u32_e32 vcc, 0, v2
	v_mov_b32_e32 v0, s1
	ds_read_b32 v0, v0
	s_cbranch_vccnz .LBB0_38
	s_add_u32 s0, s34, 0x180200
	s_addc_u32 s1, s35, 0
	s_add_u32 s6, s34, 0x180400
	s_addc_u32 s7, s35, 0
	s_add_u32 s8, s34, 0x180500
	s_addc_u32 s9, s35, 0
	s_add_u32 s10, s34, 0x180600
	s_addc_u32 s11, s35, 0
	s_add_u32 s12, s34, 0x180700
	s_addc_u32 s13, s35, 0
	s_add_u32 s14, s34, 0x180800
	s_addc_u32 s15, s35, 0
	s_add_u32 s16, s34, 0x180900
	s_addc_u32 s17, s35, 0
	s_add_u32 s18, s34, 0x180a00
	s_addc_u32 s19, s35, 0
	s_add_u32 s20, s34, 0x180b00
	s_addc_u32 s21, s35, 0
	s_add_u32 s24, s34, 0x180c00
	s_addc_u32 s25, s35, 0
	s_add_u32 s26, s34, 0x180d00
	s_addc_u32 s27, s35, 0
	s_add_u32 s28, s34, 0x180e00
	s_addc_u32 s29, s35, 0
	s_add_u32 s30, s34, 0x180f00
	s_addc_u32 s31, s35, 0
	s_add_u32 s48, s34, 0x181000
	s_addc_u32 s49, s35, 0
	s_add_u32 s54, s34, 0x181100
	s_addc_u32 s55, s35, 0
	s_add_u32 s56, s34, 0x181200
	s_addc_u32 s57, s35, 0
	s_add_u32 s60, s34, 0x181300
	s_addc_u32 s61, s35, 0
	s_mov_b32 s22, 1
	s_mov_b64 s[4:5], 0
	v_mov_b64_e32 v[2:3], s[6:7]
	v_mov_b64_e32 v[4:5], s[8:9]
	v_mov_b64_e32 v[6:7], s[10:11]
	v_mov_b64_e32 v[8:9], s[12:13]
	v_mov_b64_e32 v[10:11], s[14:15]
	v_mov_b64_e32 v[12:13], s[16:17]
	v_mov_b64_e32 v[14:15], s[18:19]
	v_mov_b64_e32 v[16:17], s[20:21]
	v_mov_b64_e32 v[18:19], s[24:25]
	v_mov_b64_e32 v[20:21], s[26:27]
	v_mov_b64_e32 v[22:23], s[28:29]
	v_mov_b64_e32 v[24:25], s[30:31]
	v_mov_b64_e32 v[26:27], s[48:49]
	v_mov_b64_e32 v[28:29], s[54:55]
	v_mov_b64_e32 v[30:31], s[56:57]
	v_mov_b64_e32 v[32:33], s[60:61]
	s_branch .LBB0_28

; #define PG8_STAGE(bufoff, gbase, voff) do { _Pragma("unroll") for (int _i = 0; _i < 2; ++_i) \
;         __builtin_amdgcn_global_load_lds((const unsigned*)((const char*)(gbase) + (voff)[_i]), (LAS unsigned*)(lds + (bufoff) + ldsw + _i * 8192), 16, 0, 0); } while (0)
; #define PG8_WAIT_V(n) asm volatile("s_waitcnt vmcnt(" #n ")" ::: "memory")
; #define PG8_BAR __builtin_amdgcn_s_barrier()
; template <class Epi, bool ALIGN_EPI>
; __device__ __forceinline__ void gemm_phase(LAS unsigned char* lds, const int tid, const Gemm g, const StaticOrder& S, const Epi& E) {
;     ...
;     const char* cA = (const char*)g.A + (size_t)cur.pm * tstepA + PG8_KOFFA(cur); const char* cB = (const char*)g.Bt + (size_t)cur.pn * tstepB + PG8_KOFFB(cur);
;     PG8_STAGE(PG8_SB(0, 0), cB, voffB); PG8_STAGE(PG8_SB(0, 1), cB + hstepB, voffB); PG8_STAGE(PG8_SA(0, 0), cA, voffA); PG8_STAGE(PG8_SA(0, 1), cA + hstepA, voffA);
;     if (wr == 1) PG8_BAR;
;     PG8_WAIT_V(2); PG8_BAR;
; __global__ void __launch_bounds__(NTHREADS, 2) fwd_kernel(Args A) {
;     ...
;         case 8: if (PMASK & 256) { pg8::Gemm g{(const bf16_t*)(ws + WS_U), wl + WT_F2, Mx, DM, DFF, MROWS, DM};        if (last) S.init(NLAT, DM, C.G, C.bid); else S.init(NLAT, DM, C.G, C.bid, NCTX, KSPLIT);
;                   pg8::EpiRes E{xs, xs + (size_t)NLAT * DM, last ? (float*)ARGP(C, 21) : xs, modl + 5 * DM, (float*)(ws + WS_PB)};
;                   pg8::gemm_phase<pg8::EpiRes, true>(C.lds, C.tid, g, S, E); } break;
.LBB0_90:
	v_ashrrev_i32_e32 v0, 31, v208
	v_lshrrev_b32_e32 v0, 26, v0
	v_add_u32_e32 v0, v208, v0
	v_ashrrev_i32_e32 v2, 6, v0
	v_bfe_i32 v0, v208, 27, 1
	v_lshlrev_b32_e32 v5, 4, v208
	v_lshrrev_b32_e32 v0, 22, v0
	v_add_u32_e32 v0, v5, v0
	v_and_b32_e32 v0, 0xfffffc00, v0
	v_sub_u32_e32 v0, v5, v0
	v_lshrrev_b32_e32 v3, 4, v0
	v_bitop3_b32 v0, v3, v0, 32 bitop3:0x6c
	v_lshlrev_b32_e32 v3, 3, v2
	v_and_b32_e32 v6, 0x1fffff0, v3
	v_ashrrev_i32_e32 v3, 31, v0
	v_lshrrev_b32_e32 v3, 26, v3
	s_ashr_i32 s29, s28, 31
	v_add_u32_e32 v4, v0, v3
	s_lshl_b64 s[18:19], s[28:29], 15
	v_ashrrev_i32_e32 v3, 6, v4
	v_and_b32_e32 v4, 0xc0, v4
	s_add_u32 s18, s86, s18
	v_sub_u32_e32 v0, v0, v4
	s_addc_u32 s19, s87, s19
	s_ashr_i32 s17, s14, 6
	v_lshlrev_b32_e32 v7, 5, v2
	v_ashrrev_i16_sdwa v0, v226, sext(v0) dst_sel:DWORD dst_unused:UNUSED_PAD src0_sel:DWORD src1_sel:BYTE_0
	s_ashr_i32 s15, s14, 8
	v_and_b32_e32 v7, 32, v7
	v_bfe_i32 v4, v0, 0, 16
	s_lshl_b32 s29, s17, 10
	v_readlane_b32 s20, v249, 59
	v_add_u32_e32 v0, v7, v4
	v_add_lshl_u32 v6, v3, v6, 7
	s_add_u32 s41, s20, 0x6100000
	v_readlane_b32 s20, v249, 60
	v_lshl_add_u32 v0, v0, 1, v6
	v_add_u32_e32 v6, 0x2000, v5
	s_addc_u32 s47, s20, 0
	v_ashrrev_i32_e32 v5, 31, v6
	s_add_u32 s30, s18, s12
	v_lshrrev_b32_e32 v5, 22, v5
	s_addc_u32 s31, s19, s13
	s_ashr_i32 s27, s26, 31
	v_add_u32_e32 v5, v6, v5
	s_lshl_b64 s[12:13], s[26:27], 15
	v_ashrrev_i32_e32 v5, 10, v5
	s_add_u32 s18, s41, s12
	v_mul_i32_i24_e32 v7, 0x400, v5
	s_addc_u32 s19, s47, s13
	s_sub_i32 s12, 25, s72
	v_sub_u32_e32 v6, v6, v7
	s_and_b32 s20, s12, 0xff
	v_readlane_b32 s12, v249, 57
	v_lshrrev_b32_e32 v7, 4, v6
	v_readlane_b32 s13, v249, 58
	v_bitop3_b32 v7, v7, v6, 32 bitop3:0x6c
	v_lshlrev_b32_e32 v6, 3, v5
	s_and_b64 s[12:13], s[12:13], exec
	v_and_b32_e32 v8, 0x1fffff0, v6
	v_ashrrev_i32_e32 v6, 31, v7
	s_cselect_b32 s52, s20, 25
	v_lshrrev_b32_e32 v6, 26, v6
	s_lshl_b64 s[12:13], s[36:37], s52
	v_add_u32_e32 v9, v7, v6
	s_and_b64 s[0:1], exec, s[0:1]
	v_ashrrev_i32_e32 v6, 6, v9
	v_and_b32_e32 v9, 0xc0, v9
	s_cselect_b32 s1, s12, 0
	v_sub_u32_e32 v7, v7, v9
	s_cselect_b32 s0, s13, 0
	s_add_u32 s92, s18, s1
	v_lshlrev_b32_e32 v10, 5, v5
	v_ashrrev_i16_sdwa v7, v226, sext(v7) dst_sel:DWORD dst_unused:UNUSED_PAD src0_sel:DWORD src1_sel:BYTE_0
	s_addc_u32 s93, s19, s0
	s_add_i32 s56, s29, 0
	v_and_b32_e32 v10, 32, v10
	v_bfe_i32 v7, v7, 0, 16
	s_add_i32 m0, s56, 0x10000
	v_add_u32_e32 v9, v10, v7
	v_add_lshl_u32 v8, v6, v8, 7
	global_load_lds_dwordx4 v0, s[92:93]
	s_add_i32 m0, s56, 0x12000
	v_lshl_add_u32 v130, v9, 1, v8
	s_add_u32 s0, s92, 0x4000
	global_load_lds_dwordx4 v130, s[92:93]
	s_addc_u32 s1, s93, 0
	s_add_i32 m0, s56, 0x14000
	s_add_i32 s58, s56, 0x2000
	global_load_lds_dwordx4 v0, s[0:1]
	s_add_i32 m0, s56, 0x16000
	v_writelane_b32 v248, s73, 8
	global_load_lds_dwordx4 v130, s[0:1]
	s_mov_b32 m0, s56
	s_add_u32 s0, s30, 0x4000
	global_load_lds_dwordx4 v0, s[30:31]
	s_mov_b32 m0, s58
	s_addc_u32 s1, s31, 0
	s_add_i32 s63, s56, 0x4000
	global_load_lds_dwordx4 v130, s[30:31]
	s_mov_b32 m0, s63
	s_add_i32 s64, s56, 0x6000
	global_load_lds_dwordx4 v0, s[0:1]
	s_mov_b32 m0, s64
	s_cmp_eq_u32 s15, 1
	global_load_lds_dwordx4 v130, s[0:1]
	s_cselect_b64 s[12:13], -1, 0
	s_cmp_lg_u32 s15, 1
	s_cbranch_scc1 .LBB0_92
	s_setprio 1
	s_barrier

; #define PG8_STAGE(bufoff, gbase, voff) do { _Pragma("unroll") for (int _i = 0; _i < 2; ++_i) \
;         __builtin_amdgcn_global_load_lds((const unsigned*)((const char*)(gbase) + (voff)[_i]), (LAS unsigned*)(lds + (bufoff) + ldsw + _i * 8192), 16, 0, 0); } while (0)
; #define PG8_LDA(dst, b, h) do { _Pragma("unroll") for (int m = 0; m < 4; ++m) _Pragma("unroll") for (int k = 0; k < 2; ++k) dst[m][k] = *(const LAS bf16x8*)(lds + PG8_SA(b, h) + aoff + m * 2048 + k * 1024); } while (0)
; #define PG8_LDB(dst, b, h) do { _Pragma("unroll") for (int n = 0; n < 2; ++n) _Pragma("unroll") for (int k = 0; k < 2; ++k) dst[n][k] = *(const LAS bf16x8*)(lds + PG8_SB(b, h) + boff + n * 2048 + k * 1024); } while (0)
; #define PG8_MMA(ai, bj, At, Bt) do { __builtin_amdgcn_s_setprio(1); _Pragma("unroll") for (int m = 0; m < 4; ++m) _Pragma("unroll") for (int n = 0; n < 2; ++n) _Pragma("unroll") for (int k = 0; k < 2; ++k) \
;         acc[ai][bj][m][n] = __builtin_amdgcn_mfma_f32_16x16x32_bf16(Bt[n][k], At[m][k], acc[ai][bj][m][n], 0, 0, 0); __builtin_amdgcn_s_setprio(0); } while (0)
; #define PG8_WAIT_V(n) asm volatile("s_waitcnt vmcnt(" #n ")" ::: "memory")
; #define PG8_BAR __builtin_amdgcn_s_barrier()
; template <class Epi, bool ALIGN_EPI>
; __device__ __forceinline__ void gemm_phase(LAS unsigned char* lds, const int tid, const Gemm g, const StaticOrder& S, const Epi& E) {
;     ...
;         for (int t = 0; t < nt; t += 2) {
;             if constexpr (Epi::HOOK) { if (t != 0 && (t & 7) == 0) E.hook(acc, cur, (t >> 3) - 1, wr, wc, fr, fq); }
;             const bool last = (t == nt - 2);
;             const char* a1 = cA + (size_t)(t + 1) * kstepA;
;             const char* a2 = last ? nA : cA + (size_t)(t + 2) * kstepA; const char* b2 = last ? nB : cB + (size_t)(t + 2) * kstepB;
;             const char* a3 = a2 + kstepA; const char* b3 = b2 + kstepB;
;             PG8_LDB(B0, 0, 0); PG8_LDB(B1, 0, 1); PG8_SCHED; PG8_LDA(At, 0, 0); PG8_STAGE(PG8_SA(1, 1), a1 + hstepA, voffA);
;             PG8_WAIT_V(8); PG8_WAIT_L(0); PG8_BAR; PG8_MMA(0, 0, At, B0); PG8_MMA(0, 1, At, B1); PG8_BAR; PG8_SCHED;
;             PG8_LDA(At, 0, 1); PG8_STAGE(PG8_SB(0, 0), b2, voffB); PG8_STAGE(PG8_SB(0, 1), b2 + hstepB, voffB); PG8_STAGE(PG8_SA(0, 0), a2, voffA);
;             PG8_WAIT_V(8); PG8_WAIT_L(0); PG8_BAR; PG8_MMA(1, 0, At, B0); PG8_MMA(1, 1, At, B1); PG8_BAR; PG8_SCHED;
.LBB0_113:
	s_add_i32 s90, s90, 2
	s_and_b64 s[34:35], exec, s[34:35]
	s_cselect_b32 s55, s23, s27
	s_cselect_b32 s54, s22, s25
	s_add_u32 s34, s92, 0x120000
	s_addc_u32 s35, s93, 0
	s_add_i32 s91, 0, 0x10000
	s_add_i32 s96, 0, 0x14000
	v_add_u32_e32 v148, s91, v175
	v_add_u32_e32 v164, s96, v175
	ds_read_b128 v[136:139], v148
	ds_read_b128 v[140:143], v148 offset:1024
	ds_read_b128 v[144:147], v148 offset:2048
	ds_read_b128 v[148:151], v148 offset:3072
	ds_read_b128 v[152:155], v164
	ds_read_b128 v[156:159], v164 offset:1024
	ds_read_b128 v[160:163], v164 offset:2048
	ds_read_b128 v[164:167], v164 offset:3072
	v_lshl_add_u64 v[172:173], s[30:31], 0, v[134:135]
	s_add_i32 m0, s56, 0xc000
	ds_read_b128 v[168:171], v177
	ds_read_b128 v[178:181], v177 offset:1024
	ds_read_b128 v[182:185], v177 offset:2048
	ds_read_b128 v[186:189], v177 offset:3072
	ds_read_b128 v[190:193], v177 offset:4096
	ds_read_b128 v[210:213], v177 offset:5120
	ds_read_b128 v[214:217], v177 offset:6144
	ds_read_b128 v[218:221], v177 offset:7168
	global_load_lds_dwordx4 v[172:173], off
	v_lshl_add_u64 v[172:173], s[30:31], 0, v[132:133]
	s_add_i32 m0, s56, 0xe000
	s_nop 0
	global_load_lds_dwordx4 v[172:173], off
	s_sub_u32 s98, s30, 0x4000
	s_subb_u32 s99, s31, 0
	v_lshl_add_u64 v[172:173], s[98:99], 0, v[134:135]
	s_mov_b32 m0, s70
	s_nop 0
	global_load_lds_dwordx4 v[172:173], off
	v_lshl_add_u64 v[172:173], s[98:99], 0, v[132:133]
	s_mov_b32 m0, s71
	s_nop 0
	global_load_lds_dwordx4 v[172:173], off
	s_waitcnt vmcnt(8)
	s_waitcnt lgkmcnt(0)
	s_barrier
	s_waitcnt lgkmcnt(0)
	v_mfma_f32_16x16x32_bf16 v[126:129], v[136:139], v[168:171], v[126:129]
	v_mfma_f32_16x16x32_bf16 v[94:97], v[144:147], v[168:171], v[94:97]
	v_mfma_f32_16x16x32_bf16 v[122:125], v[136:139], v[182:185], v[122:125]
	v_mfma_f32_16x16x32_bf16 v[90:93], v[144:147], v[182:185], v[90:93]
	v_mfma_f32_16x16x32_bf16 v[118:121], v[136:139], v[190:193], v[118:121]
	v_mfma_f32_16x16x32_bf16 v[86:89], v[144:147], v[190:193], v[86:89]
	v_mfma_f32_16x16x32_bf16 v[114:117], v[136:139], v[214:217], v[114:117]
	v_mfma_f32_16x16x32_bf16 v[82:85], v[144:147], v[214:217], v[82:85]
	v_mfma_f32_16x16x32_bf16 v[126:129], v[140:143], v[178:181], v[126:129]
	v_mfma_f32_16x16x32_bf16 v[94:97], v[148:151], v[178:181], v[94:97]
	v_mfma_f32_16x16x32_bf16 v[122:125], v[140:143], v[186:189], v[122:125]
	v_mfma_f32_16x16x32_bf16 v[90:93], v[148:151], v[186:189], v[90:93]
	v_mfma_f32_16x16x32_bf16 v[118:121], v[140:143], v[210:213], v[118:121]
	v_mfma_f32_16x16x32_bf16 v[86:89], v[148:151], v[210:213], v[86:89]
	v_mfma_f32_16x16x32_bf16 v[114:117], v[140:143], v[218:221], v[114:117]
	v_mfma_f32_16x16x32_bf16 v[82:85], v[148:151], v[218:221], v[82:85]
	v_mfma_f32_16x16x32_bf16 v[62:65], v[152:155], v[168:171], v[62:65]
	v_mfma_f32_16x16x32_bf16 v[38:41], v[160:163], v[168:171], v[38:41]
	v_mfma_f32_16x16x32_bf16 v[58:61], v[152:155], v[182:185], v[58:61]
	v_mfma_f32_16x16x32_bf16 v[30:33], v[160:163], v[182:185], v[30:33]
	v_mfma_f32_16x16x32_bf16 v[54:57], v[152:155], v[190:193], v[54:57]
	v_mfma_f32_16x16x32_bf16 v[22:25], v[160:163], v[190:193], v[22:25]
	v_mfma_f32_16x16x32_bf16 v[50:53], v[152:155], v[214:217], v[50:53]
	v_mfma_f32_16x16x32_bf16 v[18:21], v[160:163], v[214:217], v[18:21]
	v_mfma_f32_16x16x32_bf16 v[62:65], v[156:159], v[178:181], v[62:65]
	v_mfma_f32_16x16x32_bf16 v[38:41], v[164:167], v[178:181], v[38:41]
	v_mfma_f32_16x16x32_bf16 v[58:61], v[156:159], v[186:189], v[58:61]
	v_mfma_f32_16x16x32_bf16 v[30:33], v[164:167], v[186:189], v[30:33]
	v_mfma_f32_16x16x32_bf16 v[54:57], v[156:159], v[210:213], v[54:57]
	v_mfma_f32_16x16x32_bf16 v[22:25], v[164:167], v[210:213], v[22:25]
	v_mfma_f32_16x16x32_bf16 v[50:53], v[156:159], v[218:221], v[50:53]
	v_mfma_f32_16x16x32_bf16 v[18:21], v[164:167], v[218:221], v[18:21]
	s_barrier
	s_add_i32 s91, s91, s29
	v_lshl_add_u64 v[172:173], s[54:55], 0, v[0:1]
	s_mov_b32 m0, s91
	ds_read_b128 v[168:171], v177 offset:16384
	ds_read_b128 v[178:181], v177 offset:17408
	ds_read_b128 v[182:185], v177 offset:18432
	ds_read_b128 v[186:189], v177 offset:19456
	ds_read_b128 v[190:193], v177 offset:20480
	ds_read_b128 v[210:213], v177 offset:21504
	ds_read_b128 v[214:217], v177 offset:22528
	ds_read_b128 v[218:221], v177 offset:23552
	global_load_lds_dwordx4 v[172:173], off
	s_add_i32 m0, s91, 0x2000
	s_add_u32 s94, s54, 0x4000
	v_lshl_add_u64 v[172:173], s[54:55], 0, v[130:131]
	s_addc_u32 s95, s55, 0
	s_add_i32 s91, s96, s29
	global_load_lds_dwordx4 v[172:173], off
	v_lshl_add_u64 v[172:173], s[94:95], 0, v[0:1]
	s_mov_b32 m0, s91
	s_nop 0
	global_load_lds_dwordx4 v[172:173], off
	v_lshl_add_u64 v[172:173], s[94:95], 0, v[130:131]
	s_add_i32 m0, s91, 0x2000
	s_nop 0
	global_load_lds_dwordx4 v[172:173], off
	s_waitcnt vmcnt(4)
	s_waitcnt lgkmcnt(0)
	s_barrier
; #define PG8_STAGE(bufoff, gbase, voff) do { _Pragma("unroll") for (int _i = 0; _i < 2; ++_i) \
;         __builtin_amdgcn_global_load_lds((const unsigned*)((const char*)(gbase) + (voff)[_i]), (LAS unsigned*)(lds + (bufoff) + ldsw + _i * 8192), 16, 0, 0); } while (0)
; #define PG8_LDA(dst, b, h) do { _Pragma("unroll") for (int m = 0; m < 4; ++m) _Pragma("unroll") for (int k = 0; k < 2; ++k) dst[m][k] = *(const LAS bf16x8*)(lds + PG8_SA(b, h) + aoff + m * 2048 + k * 1024); } while (0)
; #define PG8_LDB(dst, b, h) do { _Pragma("unroll") for (int n = 0; n < 2; ++n) _Pragma("unroll") for (int k = 0; k < 2; ++k) dst[n][k] = *(const LAS bf16x8*)(lds + PG8_SB(b, h) + boff + n * 2048 + k * 1024); } while (0)
; #define PG8_MMA(ai, bj, At, Bt) do { __builtin_amdgcn_s_setprio(1); _Pragma("unroll") for (int m = 0; m < 4; ++m) _Pragma("unroll") for (int n = 0; n < 2; ++n) _Pragma("unroll") for (int k = 0; k < 2; ++k) \
;         acc[ai][bj][m][n] = __builtin_amdgcn_mfma_f32_16x16x32_bf16(Bt[n][k], At[m][k], acc[ai][bj][m][n], 0, 0, 0); __builtin_amdgcn_s_setprio(0); } while (0)
; #define PG8_WAIT_V(n) asm volatile("s_waitcnt vmcnt(" #n ")" ::: "memory")
; #define PG8_WAIT_L(n) asm volatile("s_waitcnt lgkmcnt(" #n ")" ::: "memory")
; #define PG8_BAR __builtin_amdgcn_s_barrier()
; template <class Epi, bool ALIGN_EPI>
; __device__ __forceinline__ void gemm_phase(LAS unsigned char* lds, const int tid, const Gemm g, const StaticOrder& S, const Epi& E) {
;     ...
;             PG8_WAIT_V(8); PG8_WAIT_L(0); PG8_BAR; PG8_MMA(0, 0, At, B0); PG8_MMA(0, 1, At, B1); PG8_BAR; PG8_SCHED;
;             PG8_LDA(At, 0, 1); PG8_STAGE(PG8_SB(0, 0), b2, voffB); PG8_STAGE(PG8_SB(0, 1), b2 + hstepB, voffB); PG8_STAGE(PG8_SA(0, 0), a2, voffA);
;             PG8_WAIT_V(8); PG8_WAIT_L(0); PG8_BAR; PG8_MMA(1, 0, At, B0); PG8_MMA(1, 1, At, B1); PG8_BAR; PG8_SCHED;
;             PG8_LDB(B0, 1, 0); PG8_LDB(B1, 1, 1); PG8_SCHED; PG8_LDA(At, 1, 0); PG8_STAGE(PG8_SA(0, 1), a2 + hstepA, voffA);
;             PG8_WAIT_V(8); PG8_WAIT_L(0); PG8_BAR; PG8_MMA(0, 0, At, B0); PG8_MMA(0, 1, At, B1); PG8_BAR; PG8_SCHED;
;             PG8_LDA(At, 1, 1); PG8_STAGE(PG8_SB(1, 0), b3, voffB); PG8_STAGE(PG8_SB(1, 1), b3 + hstepB, voffB); PG8_STAGE(PG8_SA(1, 0), a3, voffA);
;             PG8_WAIT_V(8); PG8_WAIT_L(0); PG8_BAR; PG8_MMA(1, 0, At, B0); PG8_MMA(1, 1, At, B1); PG8_BAR; PG8_SCHED;
	s_waitcnt lgkmcnt(0)
	v_mfma_f32_16x16x32_bf16 v[110:113], v[136:139], v[168:171], v[110:113]
	v_mfma_f32_16x16x32_bf16 v[78:81], v[144:147], v[168:171], v[78:81]
	v_mfma_f32_16x16x32_bf16 v[106:109], v[136:139], v[182:185], v[106:109]
	v_mfma_f32_16x16x32_bf16 v[74:77], v[144:147], v[182:185], v[74:77]
	v_mfma_f32_16x16x32_bf16 v[102:105], v[136:139], v[190:193], v[102:105]
	v_mfma_f32_16x16x32_bf16 v[70:73], v[144:147], v[190:193], v[70:73]
	v_mfma_f32_16x16x32_bf16 v[98:101], v[136:139], v[214:217], v[98:101]
	v_mfma_f32_16x16x32_bf16 v[66:69], v[144:147], v[214:217], v[66:69]
	v_mfma_f32_16x16x32_bf16 v[110:113], v[140:143], v[178:181], v[110:113]
	v_mfma_f32_16x16x32_bf16 v[78:81], v[148:151], v[178:181], v[78:81]
	v_mfma_f32_16x16x32_bf16 v[106:109], v[140:143], v[186:189], v[106:109]
	v_mfma_f32_16x16x32_bf16 v[74:77], v[148:151], v[186:189], v[74:77]
	v_mfma_f32_16x16x32_bf16 v[102:105], v[140:143], v[210:213], v[102:105]
	v_mfma_f32_16x16x32_bf16 v[70:73], v[148:151], v[210:213], v[70:73]
	v_mfma_f32_16x16x32_bf16 v[98:101], v[140:143], v[218:221], v[98:101]
	v_mfma_f32_16x16x32_bf16 v[66:69], v[148:151], v[218:221], v[66:69]
	v_mfma_f32_16x16x32_bf16 v[46:49], v[152:155], v[168:171], v[46:49]
	v_mfma_f32_16x16x32_bf16 v[14:17], v[160:163], v[168:171], v[14:17]
	v_mfma_f32_16x16x32_bf16 v[42:45], v[152:155], v[182:185], v[42:45]
	v_mfma_f32_16x16x32_bf16 v[10:13], v[160:163], v[182:185], v[10:13]
	v_mfma_f32_16x16x32_bf16 v[34:37], v[152:155], v[190:193], v[34:37]
	v_mfma_f32_16x16x32_bf16 v[6:9], v[160:163], v[190:193], v[6:9]
	v_mfma_f32_16x16x32_bf16 v[26:29], v[152:155], v[214:217], v[26:29]
	v_mfma_f32_16x16x32_bf16 v[2:5], v[160:163], v[214:217], v[2:5]
	v_mfma_f32_16x16x32_bf16 v[46:49], v[156:159], v[178:181], v[46:49]
	v_mfma_f32_16x16x32_bf16 v[14:17], v[164:167], v[178:181], v[14:17]
	v_mfma_f32_16x16x32_bf16 v[42:45], v[156:159], v[186:189], v[42:45]
	v_mfma_f32_16x16x32_bf16 v[10:13], v[164:167], v[186:189], v[10:13]
	v_mfma_f32_16x16x32_bf16 v[34:37], v[156:159], v[210:213], v[34:37]
	v_mfma_f32_16x16x32_bf16 v[6:9], v[164:167], v[210:213], v[6:9]
	v_mfma_f32_16x16x32_bf16 v[26:29], v[156:159], v[218:221], v[26:29]
	v_mfma_f32_16x16x32_bf16 v[2:5], v[164:167], v[218:221], v[2:5]
	s_barrier
	s_add_i32 s91, 0, 0x18000
	s_add_i32 s94, 0, 0x1c000
	v_add_u32_e32 v148, s91, v175
	v_add_u32_e32 v164, s94, v175
	ds_read_b128 v[136:139], v148
	ds_read_b128 v[140:143], v148 offset:1024
	ds_read_b128 v[144:147], v148 offset:2048
	ds_read_b128 v[148:151], v148 offset:3072
	ds_read_b128 v[152:155], v164
	ds_read_b128 v[156:159], v164 offset:1024
	ds_read_b128 v[160:163], v164 offset:2048
	ds_read_b128 v[164:167], v164 offset:3072
	v_lshl_add_u64 v[172:173], s[92:93], 0, v[0:1]
	s_mov_b32 m0, s56
	s_nop 0
	global_load_lds_dwordx4 v[172:173], off
	v_lshl_add_u64 v[172:173], s[92:93], 0, v[130:131]
	s_mov_b32 m0, s58
	s_nop 0
	global_load_lds_dwordx4 v[172:173], off
	s_add_u32 s92, s92, 0x4000
	s_addc_u32 s93, s93, 0
	s_mov_b32 m0, s63
	v_lshl_add_u64 v[172:173], s[92:93], 0, v[0:1]
	ds_read_b128 v[168:171], v177 offset:32768
	ds_read_b128 v[178:181], v177 offset:33792
	ds_read_b128 v[182:185], v177 offset:34816
	ds_read_b128 v[186:189], v177 offset:35840
	ds_read_b128 v[190:193], v177 offset:36864
	ds_read_b128 v[210:213], v177 offset:37888
	ds_read_b128 v[214:217], v177 offset:38912
	ds_read_b128 v[218:221], v177 offset:39936
	global_load_lds_dwordx4 v[172:173], off
	v_lshl_add_u64 v[172:173], s[92:93], 0, v[130:131]
	s_mov_b32 m0, s64
	s_nop 0
	global_load_lds_dwordx4 v[172:173], off
	s_waitcnt vmcnt(8)
	s_waitcnt lgkmcnt(0)
	s_barrier
; #define PG8_STAGE(bufoff, gbase, voff) do { _Pragma("unroll") for (int _i = 0; _i < 2; ++_i) \
;         __builtin_amdgcn_global_load_lds((const unsigned*)((const char*)(gbase) + (voff)[_i]), (LAS unsigned*)(lds + (bufoff) + ldsw + _i * 8192), 16, 0, 0); } while (0)
; #define PG8_LDA(dst, b, h) do { _Pragma("unroll") for (int m = 0; m < 4; ++m) _Pragma("unroll") for (int k = 0; k < 2; ++k) dst[m][k] = *(const LAS bf16x8*)(lds + PG8_SA(b, h) + aoff + m * 2048 + k * 1024); } while (0)
; #define PG8_LDB(dst, b, h) do { _Pragma("unroll") for (int n = 0; n < 2; ++n) _Pragma("unroll") for (int k = 0; k < 2; ++k) dst[n][k] = *(const LAS bf16x8*)(lds + PG8_SB(b, h) + boff + n * 2048 + k * 1024); } while (0)
; #define PG8_MMA(ai, bj, At, Bt) do { __builtin_amdgcn_s_setprio(1); _Pragma("unroll") for (int m = 0; m < 4; ++m) _Pragma("unroll") for (int n = 0; n < 2; ++n) _Pragma("unroll") for (int k = 0; k < 2; ++k) \
;         acc[ai][bj][m][n] = __builtin_amdgcn_mfma_f32_16x16x32_bf16(Bt[n][k], At[m][k], acc[ai][bj][m][n], 0, 0, 0); __builtin_amdgcn_s_setprio(0); } while (0)
; #define PG8_WAIT_V(n) asm volatile("s_waitcnt vmcnt(" #n ")" ::: "memory")
; #define PG8_WAIT_L(n) asm volatile("s_waitcnt lgkmcnt(" #n ")" ::: "memory")
; #define PG8_BAR __builtin_amdgcn_s_barrier()
; template <class Epi, bool ALIGN_EPI>
; __device__ __forceinline__ void gemm_phase(LAS unsigned char* lds, const int tid, const Gemm g, const StaticOrder& S, const Epi& E) {
;     ...
;             PG8_WAIT_V(8); PG8_WAIT_L(0); PG8_BAR; PG8_MMA(0, 0, At, B0); PG8_MMA(0, 1, At, B1); PG8_BAR; PG8_SCHED;
;             PG8_LDA(At, 0, 1); PG8_STAGE(PG8_SB(0, 0), b2, voffB); PG8_STAGE(PG8_SB(0, 1), b2 + hstepB, voffB); PG8_STAGE(PG8_SA(0, 0), a2, voffA);
;             PG8_WAIT_V(8); PG8_WAIT_L(0); PG8_BAR; PG8_MMA(1, 0, At, B0); PG8_MMA(1, 1, At, B1); PG8_BAR; PG8_SCHED;
;             PG8_LDB(B0, 1, 0); PG8_LDB(B1, 1, 1); PG8_SCHED; PG8_LDA(At, 1, 0); PG8_STAGE(PG8_SA(0, 1), a2 + hstepA, voffA);
;             PG8_WAIT_V(8); PG8_WAIT_L(0); PG8_BAR; PG8_MMA(0, 0, At, B0); PG8_MMA(0, 1, At, B1); PG8_BAR; PG8_SCHED;
;             PG8_LDA(At, 1, 1); PG8_STAGE(PG8_SB(1, 0), b3, voffB); PG8_STAGE(PG8_SB(1, 1), b3 + hstepB, voffB); PG8_STAGE(PG8_SA(1, 0), a3, voffA);
;             PG8_WAIT_V(8); PG8_WAIT_L(0); PG8_BAR; PG8_MMA(1, 0, At, B0); PG8_MMA(1, 1, At, B1); PG8_BAR; PG8_SCHED;
;         }
	s_waitcnt lgkmcnt(0)
	v_mfma_f32_16x16x32_bf16 v[126:129], v[136:139], v[168:171], v[126:129]
	v_mfma_f32_16x16x32_bf16 v[94:97], v[144:147], v[168:171], v[94:97]
	v_mfma_f32_16x16x32_bf16 v[122:125], v[136:139], v[182:185], v[122:125]
	v_mfma_f32_16x16x32_bf16 v[90:93], v[144:147], v[182:185], v[90:93]
	v_mfma_f32_16x16x32_bf16 v[118:121], v[136:139], v[190:193], v[118:121]
	v_mfma_f32_16x16x32_bf16 v[86:89], v[144:147], v[190:193], v[86:89]
	v_mfma_f32_16x16x32_bf16 v[114:117], v[136:139], v[214:217], v[114:117]
	v_mfma_f32_16x16x32_bf16 v[82:85], v[144:147], v[214:217], v[82:85]
	v_mfma_f32_16x16x32_bf16 v[126:129], v[140:143], v[178:181], v[126:129]
	v_mfma_f32_16x16x32_bf16 v[94:97], v[148:151], v[178:181], v[94:97]
	v_mfma_f32_16x16x32_bf16 v[122:125], v[140:143], v[186:189], v[122:125]
	v_mfma_f32_16x16x32_bf16 v[90:93], v[148:151], v[186:189], v[90:93]
	v_mfma_f32_16x16x32_bf16 v[118:121], v[140:143], v[210:213], v[118:121]
	v_mfma_f32_16x16x32_bf16 v[86:89], v[148:151], v[210:213], v[86:89]
	v_mfma_f32_16x16x32_bf16 v[114:117], v[140:143], v[218:221], v[114:117]
	v_mfma_f32_16x16x32_bf16 v[82:85], v[148:151], v[218:221], v[82:85]
	v_mfma_f32_16x16x32_bf16 v[62:65], v[152:155], v[168:171], v[62:65]
	v_mfma_f32_16x16x32_bf16 v[38:41], v[160:163], v[168:171], v[38:41]
	v_mfma_f32_16x16x32_bf16 v[58:61], v[152:155], v[182:185], v[58:61]
	v_mfma_f32_16x16x32_bf16 v[30:33], v[160:163], v[182:185], v[30:33]
	v_mfma_f32_16x16x32_bf16 v[54:57], v[152:155], v[190:193], v[54:57]
	v_mfma_f32_16x16x32_bf16 v[22:25], v[160:163], v[190:193], v[22:25]
	v_mfma_f32_16x16x32_bf16 v[50:53], v[152:155], v[214:217], v[50:53]
	v_mfma_f32_16x16x32_bf16 v[18:21], v[160:163], v[214:217], v[18:21]
	v_mfma_f32_16x16x32_bf16 v[62:65], v[156:159], v[178:181], v[62:65]
	v_mfma_f32_16x16x32_bf16 v[38:41], v[164:167], v[178:181], v[38:41]
	v_mfma_f32_16x16x32_bf16 v[58:61], v[156:159], v[186:189], v[58:61]
	v_mfma_f32_16x16x32_bf16 v[30:33], v[164:167], v[186:189], v[30:33]
	v_mfma_f32_16x16x32_bf16 v[54:57], v[156:159], v[210:213], v[54:57]
	v_mfma_f32_16x16x32_bf16 v[22:25], v[164:167], v[210:213], v[22:25]
	v_mfma_f32_16x16x32_bf16 v[50:53], v[156:159], v[218:221], v[50:53]
	v_mfma_f32_16x16x32_bf16 v[18:21], v[164:167], v[218:221], v[18:21]
	s_barrier
	s_add_u32 s92, s54, 0x40000
	s_addc_u32 s93, s55, 0
	s_add_i32 s91, s91, s29
	v_lshl_add_u64 v[172:173], s[92:93], 0, v[0:1]
	s_mov_b32 m0, s91
	ds_read_b128 v[168:171], v177 offset:49152
	ds_read_b128 v[178:181], v177 offset:50176
	ds_read_b128 v[182:185], v177 offset:51200
	ds_read_b128 v[186:189], v177 offset:52224
	ds_read_b128 v[190:193], v177 offset:53248
	ds_read_b128 v[210:213], v177 offset:54272
	ds_read_b128 v[214:217], v177 offset:55296
	ds_read_b128 v[218:221], v177 offset:56320
	global_load_lds_dwordx4 v[172:173], off
	s_add_i32 m0, s91, 0x2000
	s_add_u32 s54, s54, 0x44000
	v_lshl_add_u64 v[172:173], s[92:93], 0, v[130:131]
	s_addc_u32 s55, s55, 0
	s_add_i32 s91, s94, s29
	global_load_lds_dwordx4 v[172:173], off
	v_lshl_add_u64 v[172:173], s[54:55], 0, v[0:1]
	s_mov_b32 m0, s91
	s_nop 0
	global_load_lds_dwordx4 v[172:173], off
	v_lshl_add_u64 v[172:173], s[54:55], 0, v[130:131]
	s_add_i32 m0, s91, 0x2000
	s_nop 0
	global_load_lds_dwordx4 v[172:173], off
	s_waitcnt vmcnt(4)
	s_waitcnt lgkmcnt(0)
	s_barrier
	s_waitcnt lgkmcnt(0)
	v_mfma_f32_16x16x32_bf16 v[110:113], v[136:139], v[168:171], v[110:113]
	v_mfma_f32_16x16x32_bf16 v[78:81], v[144:147], v[168:171], v[78:81]
	v_mfma_f32_16x16x32_bf16 v[106:109], v[136:139], v[182:185], v[106:109]
	v_mfma_f32_16x16x32_bf16 v[74:77], v[144:147], v[182:185], v[74:77]
	v_mfma_f32_16x16x32_bf16 v[102:105], v[136:139], v[190:193], v[102:105]
	v_mfma_f32_16x16x32_bf16 v[70:73], v[144:147], v[190:193], v[70:73]
	v_mfma_f32_16x16x32_bf16 v[98:101], v[136:139], v[214:217], v[98:101]
	v_mfma_f32_16x16x32_bf16 v[66:69], v[144:147], v[214:217], v[66:69]
	v_mfma_f32_16x16x32_bf16 v[110:113], v[140:143], v[178:181], v[110:113]
	v_mfma_f32_16x16x32_bf16 v[78:81], v[148:151], v[178:181], v[78:81]
	v_mfma_f32_16x16x32_bf16 v[106:109], v[140:143], v[186:189], v[106:109]
	v_mfma_f32_16x16x32_bf16 v[74:77], v[148:151], v[186:189], v[74:77]
	v_mfma_f32_16x16x32_bf16 v[102:105], v[140:143], v[210:213], v[102:105]
	v_mfma_f32_16x16x32_bf16 v[70:73], v[148:151], v[210:213], v[70:73]
	v_mfma_f32_16x16x32_bf16 v[98:101], v[140:143], v[218:221], v[98:101]
	v_mfma_f32_16x16x32_bf16 v[66:69], v[148:151], v[218:221], v[66:69]
	v_mfma_f32_16x16x32_bf16 v[46:49], v[152:155], v[168:171], v[46:49]
	v_mfma_f32_16x16x32_bf16 v[14:17], v[160:163], v[168:171], v[14:17]
	v_mfma_f32_16x16x32_bf16 v[42:45], v[152:155], v[182:185], v[42:45]
	v_mfma_f32_16x16x32_bf16 v[10:13], v[160:163], v[182:185], v[10:13]
	v_mfma_f32_16x16x32_bf16 v[34:37], v[152:155], v[190:193], v[34:37]
	v_mfma_f32_16x16x32_bf16 v[6:9], v[160:163], v[190:193], v[6:9]
	v_mfma_f32_16x16x32_bf16 v[26:29], v[152:155], v[214:217], v[26:29]
	v_mfma_f32_16x16x32_bf16 v[2:5], v[160:163], v[214:217], v[2:5]
	v_mfma_f32_16x16x32_bf16 v[46:49], v[156:159], v[178:181], v[46:49]
	v_mfma_f32_16x16x32_bf16 v[14:17], v[164:167], v[178:181], v[14:17]
	v_mfma_f32_16x16x32_bf16 v[42:45], v[156:159], v[186:189], v[42:45]
	v_mfma_f32_16x16x32_bf16 v[10:13], v[164:167], v[186:189], v[10:13]
	v_mfma_f32_16x16x32_bf16 v[34:37], v[156:159], v[210:213], v[34:37]
	v_mfma_f32_16x16x32_bf16 v[6:9], v[164:167], v[210:213], v[6:9]
	v_mfma_f32_16x16x32_bf16 v[26:29], v[156:159], v[218:221], v[26:29]
	v_mfma_f32_16x16x32_bf16 v[2:5], v[164:167], v[218:221], v[2:5]
	s_barrier
	s_add_u32 s25, s25, 0x80000
	s_addc_u32 s27, s27, 0
	s_add_u32 s30, s30, 0x240000
	s_addc_u32 s31, s31, 0
	s_cmp_ge_u32 s90, s17
	s_cbranch_scc1 .LBB0_116

; #define PG8_BAR __builtin_amdgcn_s_barrier()
;     __device__ bool next(int i, Unit& u) const {
;         const long L = (long)i * G + c;
;         if (L >= nwg) { const long j = L - nwg; if (j >= (long)nM2 * nN * nsplit) return false;
;             const int jj = (int)j; u.ks = jj % nsplit; const int tl = jj / nsplit; u.pn = tl % nN; u.pm = nM + tl / nN; return true; }
;         u.ks = -1;
;         int wgid = (int)L; { const int q = nwg / NXCD, r = nwg % NXCD, xcd = wgid % NXCD, off = wgid / NXCD; wgid = (xcd < r ? xcd * (q + 1) : r * (q + 1) + (xcd - r) * q) + off; }
;         const int nig = WGM * nN, gid = wgid / nig, fm = gid * WGM, gsz = (nM - fm) < WGM ? (nM - fm) : WGM;
;         u.pm = fm + ((wgid % nig) % gsz); u.pn = (wgid % nig) / gsz; return true;
; template <class Epi, bool ALIGN_EPI>
; __device__ __forceinline__ void gemm_phase(LAS unsigned char* lds, const int tid, const Gemm g, const StaticOrder& S, const Epi& E) {
;     ...
;     for (int i = 0; i < 2; ++i) { int R, C; stage_rc(tid * 16 + i * 8192, R, C); const int Rb = Epi::PERM ? ((R & ~31) + perm32(R & 31)) : R;
;         voffA[i] = (unsigned)R * rsA + (unsigned)C * 2u; voffB[i] = (unsigned)Rb * rsB + (unsigned)C * 2u; }
;     const size_t hstepA = (size_t)HALF * rsA, hstepB = (size_t)HALF * rsB;
;     const size_t tstepA = 2 * hstepA, tstepB = 2 * hstepB;
;     const unsigned ldsw = (unsigned)wid * 1024u;
;     const int aoff = lds_byte(wr * 64 + fr, fq * 8), boff = lds_byte(wc * 32 + fr, fq * 8);
;     ...
;     Unit cur, nxt; int ui = 0;
;     if (!S.next(0, cur)) return;
;     f32x4 acc[2][2][4][2];
; #pragma unroll
;     for (int a = 0; a < 2; ++a)
; #pragma unroll
;         for (int b = 0; b < 2; ++b)
; #pragma unroll
;             for (int m = 0; m < 4; ++m)
; #pragma unroll
;                 for (int n = 0; n < 2; ++n) acc[a][b][m][n] = (f32x4){0.f, 0.f, 0.f, 0.f};
;     bf16x8 At[4][2], B0[2][2], B1[2][2];
;     ...
;     const char* cA = (const char*)g.A + (size_t)cur.pm * tstepA + PG8_KOFFA(cur); const char* cB = (const char*)g.Bt + (size_t)cur.pn * tstepB + PG8_KOFFB(cur);
;     PG8_STAGE(PG8_SB(0, 0), cB, voffB); PG8_STAGE(PG8_SB(0, 1), cB + hstepB, voffB); PG8_STAGE(PG8_SA(0, 0), cA, voffA); PG8_STAGE(PG8_SA(0, 1), cA + hstepA, voffA);
;     if (wr == 1) PG8_BAR;
.LBB0_133:
	s_andn2_b64 vcc, exec, s[0:1]
	s_cbranch_vccnz .LBB0_150
	s_lshr_b32 s36, s62, 3
	s_cmp_ge_i32 s51, s36
	v_readfirstlane_b32 s12, v208
	s_cbranch_scc1 .LBB0_150
	v_lshlrev_b32_e32 v0, 4, v208
	v_add_u32_e32 v2, 0x2000, v0
	v_ashrrev_i32_e32 v3, 31, v2
	v_lshrrev_b32_e32 v3, 22, v3
	v_add_u32_e32 v3, v2, v3
	v_ashrrev_i32_e32 v10, 10, v3
	v_mul_i32_i24_e32 v3, 0x400, v10
	v_sub_u32_e32 v2, v2, v3
	v_lshrrev_b32_e32 v3, 4, v2
	v_bitop3_b32 v2, v3, v2, 32 bitop3:0x6c
	v_ashrrev_i32_e32 v3, 31, v2
	v_lshrrev_b32_e32 v3, 26, v3
	s_ashr_i32 s1, s12, 6
	v_add_u32_e32 v3, v2, v3
	v_lshlrev_b32_e32 v4, 3, v10
	s_ashr_i32 s13, s12, 8
	s_lshl_b32 s30, s1, 10
	v_readlane_b32 s0, v249, 59
	v_ashrrev_i32_e32 v11, 6, v3
	v_and_b32_e32 v4, -16, v4
	s_add_u32 s31, s0, 0x4100000
	v_readlane_b32 s0, v249, 60
	v_add_u32_e32 v4, v11, v4
	s_addc_u32 s34, s0, 0
	v_and_b32_e32 v5, 3, v11
	s_mov_b32 s0, 0xfffe0
	v_lshrrev_b32_e32 v6, 2, v4
	v_lshlrev_b32_e32 v7, 1, v4
	v_and_b32_e32 v3, 0xc0, v3
	v_and_or_b32 v5, v4, s0, v5
	v_and_b32_e32 v6, 4, v6
	v_and_b32_e32 v7, 24, v7
	v_sub_u32_e32 v2, v2, v3
	v_or3_b32 v5, v5, v6, v7
	v_lshlrev_b32_e32 v6, 5, v10
	v_ashrrev_i16_sdwa v2, v226, sext(v2) dst_sel:DWORD dst_unused:UNUSED_PAD src0_sel:DWORD src1_sel:BYTE_0
	v_and_b32_e32 v6, 32, v6
	v_bfe_i32 v12, v2, 0, 16
	v_add_lshl_u32 v2, v6, v12, 1
	v_lshl_add_u32 v130, v5, 12, v2
	v_lshl_add_u32 v132, v4, 12, v2
	v_bfe_i32 v2, v208, 27, 1
	v_lshrrev_b32_e32 v2, 22, v2
	v_add_u32_e32 v2, v0, v2
	v_and_b32_e32 v2, 0xfffffc00, v2
	v_sub_u32_e32 v0, v0, v2
	v_lshrrev_b32_e32 v2, 4, v0
	v_ashrrev_i32_e32 v3, 31, v208
	v_bitop3_b32 v0, v2, v0, 32 bitop3:0x6c
	v_lshrrev_b32_e32 v3, 26, v3
	v_ashrrev_i32_e32 v2, 31, v0
	v_add_u32_e32 v3, v208, v3
	v_lshrrev_b32_e32 v2, 26, v2
	v_ashrrev_i32_e32 v14, 6, v3
	v_add_u32_e32 v2, v0, v2
	v_lshlrev_b32_e32 v3, 3, v14
	v_ashrrev_i32_e32 v13, 6, v2
	v_and_b32_e32 v3, -16, v3
	v_add_u32_e32 v3, v13, v3
	v_and_b32_e32 v4, 3, v13
	s_ashr_i32 s47, s51, 31
	v_and_or_b32 v4, v3, s0, v4
	s_lshr_b32 s0, s47, 29
	s_add_i32 s0, s51, s0
	s_ashr_i32 s10, s0, 3
	s_and_b32 s0, s0, -8
	s_sub_i32 s0, s51, s0
	s_lshr_b32 s41, s62, 6
	s_lshr_b32 s11, s0, 31
	s_or_b32 s11, s41, s11
	s_mul_i32 s0, s0, s11
	s_add_i32 s0, s0, s10
	s_ashr_i32 s10, s0, 31
	s_lshr_b32 s10, s10, 24
	s_add_i32 s10, s0, s10
	v_lshrrev_b32_e32 v5, 2, v3
	v_lshlrev_b32_e32 v6, 1, v3
	v_and_b32_e32 v2, 0xc0, v2
	s_ashr_i32 s11, s10, 8
	s_lshr_b32 s35, s62, 8
	v_and_b32_e32 v5, 4, v5
	v_and_b32_e32 v6, 24, v6
	v_sub_u32_e32 v0, v0, v2
	s_lshl_b32 s14, s11, 3
	v_or3_b32 v4, v4, v5, v6
	v_lshlrev_b32_e32 v5, 5, v14
	v_ashrrev_i16_sdwa v0, v226, sext(v0) dst_sel:DWORD dst_unused:UNUSED_PAD src0_sel:DWORD src1_sel:BYTE_0
	s_sub_i32 s11, s35, s14
	v_and_b32_e32 v5, 32, v5
	v_bfe_i32 v15, v0, 0, 16
	s_min_u32 s15, s11, 8
	s_and_b32 s10, s10, 0xffffff00
	v_add_lshl_u32 v2, v5, v15, 1
	s_sub_i32 s16, s0, s10
	v_cvt_f32_ubyte0_e32 v5, s15
	v_lshl_add_u32 v0, v4, 12, v2
	v_cvt_f32_i32_e32 v4, s16
	v_rcp_iflag_f32_e32 v6, v5
	v_lshl_add_u32 v134, v3, 12, v2
	s_ashr_i32 s0, s16, 30
	s_or_b32 s0, s0, 1
	v_mul_f32_e32 v2, v4, v6
	v_trunc_f32_e32 v2, v2
	v_fma_f32 v3, -v2, v5, v4
	v_cvt_i32_f32_e32 v2, v2
	v_cmp_ge_f32_e64 s[10:11], |v3|, v5
	s_and_b64 s[10:11], s[10:11], exec
	s_cselect_b32 s0, s0, 0
	v_readfirstlane_b32 s10, v2
	s_add_i32 s0, s10, s0
	s_mul_i32 s10, s0, s15
	s_sub_i32 s10, s16, s10
	s_sext_i32_i16 s10, s10
	s_add_i32 s22, s14, s10
	s_ashr_i32 s23, s22, 31
	s_lshl_b64 s[10:11], s[22:23], 20
	v_readlane_b32 s14, v248, 4
	s_add_u32 s24, s14, s10
	v_readlane_b32 s10, v249, 63
	s_addc_u32 s25, s10, s11
	s_bfe_i64 s[10:11], s[0:1], 0x100000
	s_lshl_b64 s[10:11], s[10:11], 20
	s_add_u32 s26, s31, s10
	s_addc_u32 s27, s34, s11
	s_add_i32 s23, s30, 0
	s_add_i32 m0, s23, 0x10000
	v_mov_b32_e32 v131, v1
	global_load_lds_dwordx4 v0, s[26:27]
	s_add_i32 m0, s23, 0x12000
	s_add_u32 s10, s26, 0x80000
	global_load_lds_dwordx4 v130, s[26:27]
	s_addc_u32 s11, s27, 0
	s_add_i32 m0, s23, 0x14000
	s_add_i32 s52, s23, 0x2000
	global_load_lds_dwordx4 v0, s[10:11]
	s_add_i32 m0, s23, 0x16000
	v_mov_b32_e32 v135, v1
	global_load_lds_dwordx4 v130, s[10:11]
	s_mov_b32 m0, s23
	s_add_u32 s10, s24, 0x80000
	global_load_lds_dwordx4 v134, s[24:25]
	s_mov_b32 m0, s52
	s_addc_u32 s11, s25, 0
	s_add_i32 s54, s23, 0x4000
	global_load_lds_dwordx4 v132, s[24:25]
	s_mov_b32 m0, s54
	s_add_i32 s55, s23, 0x6000
	global_load_lds_dwordx4 v134, s[10:11]
	s_mov_b32 m0, s55
	v_mov_b32_e32 v133, v1
	global_load_lds_dwordx4 v132, s[10:11]
	s_cmp_eq_u32 s13, 1
	s_mov_b32 s71, s56
	v_lshl_add_u64 v[8:9], s[26:27], 0, v[0:1]
	v_lshl_add_u64 v[6:7], s[26:27], 0, v[130:131]
	v_lshl_add_u64 v[2:3], s[24:25], 0, v[134:135]
	s_cselect_b64 s[10:11], -1, 0
	s_cmp_lg_u32 s13, 1
	v_lshl_add_u64 v[4:5], s[24:25], 0, v[132:133]
	s_cbranch_scc1 .LBB0_137
	s_setprio 1
	s_barrier

; #define PG8_STAGE(bufoff, gbase, voff) do { _Pragma("unroll") for (int _i = 0; _i < 2; ++_i) \
;         __builtin_amdgcn_global_load_lds((const unsigned*)((const char*)(gbase) + (voff)[_i]), (LAS unsigned*)(lds + (bufoff) + ldsw + _i * 8192), 16, 0, 0); } while (0)
; #define PG8_LDA(dst, b, h) do { _Pragma("unroll") for (int m = 0; m < 4; ++m) _Pragma("unroll") for (int k = 0; k < 2; ++k) dst[m][k] = *(const LAS bf16x8*)(lds + PG8_SA(b, h) + aoff + m * 2048 + k * 1024); } while (0)
; #define PG8_LDB(dst, b, h) do { _Pragma("unroll") for (int n = 0; n < 2; ++n) _Pragma("unroll") for (int k = 0; k < 2; ++k) dst[n][k] = *(const LAS bf16x8*)(lds + PG8_SB(b, h) + boff + n * 2048 + k * 1024); } while (0)
; #define PG8_MMA(ai, bj, At, Bt) do { __builtin_amdgcn_s_setprio(1); _Pragma("unroll") for (int m = 0; m < 4; ++m) _Pragma("unroll") for (int n = 0; n < 2; ++n) _Pragma("unroll") for (int k = 0; k < 2; ++k) \
;         acc[ai][bj][m][n] = __builtin_amdgcn_mfma_f32_16x16x32_bf16(Bt[n][k], At[m][k], acc[ai][bj][m][n], 0, 0, 0); __builtin_amdgcn_s_setprio(0); } while (0)
; #define PG8_WAIT_V(n) asm volatile("s_waitcnt vmcnt(" #n ")" ::: "memory")
; #define PG8_WAIT_L(n) asm volatile("s_waitcnt lgkmcnt(" #n ")" ::: "memory")
; #define PG8_BAR __builtin_amdgcn_s_barrier()
; #define PG8_SCHED __builtin_amdgcn_sched_barrier(0)
; template <class Epi, bool ALIGN_EPI>
; __device__ __forceinline__ void gemm_phase(LAS unsigned char* lds, const int tid, const Gemm g, const StaticOrder& S, const Epi& E) {
;     ...
;             const bool last = (t == nt - 2);
;             const char* a1 = cA + (size_t)(t + 1) * kstepA;
;             const char* a2 = last ? nA : cA + (size_t)(t + 2) * kstepA; const char* b2 = last ? nB : cB + (size_t)(t + 2) * kstepB;
;             const char* a3 = a2 + kstepA; const char* b3 = b2 + kstepB;
;             PG8_LDB(B0, 0, 0); PG8_LDB(B1, 0, 1); PG8_SCHED; PG8_LDA(At, 0, 0); PG8_STAGE(PG8_SA(1, 1), a1 + hstepA, voffA);
;             PG8_WAIT_V(8); PG8_WAIT_L(0); PG8_BAR; PG8_MMA(0, 0, At, B0); PG8_MMA(0, 1, At, B1); PG8_BAR; PG8_SCHED;
;             PG8_LDA(At, 0, 1); PG8_STAGE(PG8_SB(0, 0), b2, voffB); PG8_STAGE(PG8_SB(0, 1), b2 + hstepB, voffB); PG8_STAGE(PG8_SA(0, 0), a2, voffA);
;             PG8_WAIT_V(8); PG8_WAIT_L(0); PG8_BAR; PG8_MMA(1, 0, At, B0); PG8_MMA(1, 1, At, B1); PG8_BAR; PG8_SCHED;
.LBB0_143:
	s_add_u32 s26, s24, 0xfff80080
	s_addc_u32 s27, s25, -1
	s_add_i32 s68, 0, 0x10000
	s_cmp_eq_u32 s67, 28
	s_cselect_b32 s29, s19, s27
	s_cselect_b32 s28, s18, s26
	v_add_u32_e32 v142, s68, v145
	s_cselect_b32 s27, s21, s17
	s_cselect_b32 s26, s20, s15
	s_add_i32 s70, 0, 0x14000
	ds_read_b128 v[148:151], v142
	ds_read_b128 v[152:155], v142 offset:1024
	ds_read_b128 v[156:159], v142 offset:2048
	ds_read_b128 v[160:163], v142 offset:3072
	v_add_u32_e32 v142, s70, v145
	ds_read_b128 v[164:167], v142
	ds_read_b128 v[168:171], v142 offset:1024
	ds_read_b128 v[172:175], v142 offset:2048
	ds_read_b128 v[176:179], v142 offset:3072
	v_lshl_add_u64 v[142:143], s[24:25], 0, v[140:141]
	s_add_i32 m0, s23, 0xc000
	ds_read_b128 v[180:183], v146
	ds_read_b128 v[184:187], v146 offset:1024
	ds_read_b128 v[188:191], v146 offset:2048
	ds_read_b128 v[192:195], v146 offset:3072
	ds_read_b128 v[210:213], v146 offset:4096
	ds_read_b128 v[214:217], v146 offset:5120
	ds_read_b128 v[218:221], v146 offset:6144
	ds_read_b128 v[222:225], v146 offset:7168
	global_load_lds_dwordx4 v[142:143], off
	v_lshl_add_u64 v[142:143], s[24:25], 0, v[138:139]
	s_add_i32 m0, s23, 0xe000
	s_nop 0
	global_load_lds_dwordx4 v[142:143], off
	s_sub_u32 s98, s24, 0x80000
	s_subb_u32 s99, s25, 0
	v_lshl_add_u64 v[142:143], s[98:99], 0, v[140:141]
	s_mov_b32 m0, s56
	s_nop 0
	global_load_lds_dwordx4 v[142:143], off
	v_lshl_add_u64 v[142:143], s[98:99], 0, v[138:139]
	s_mov_b32 m0, s58
	s_nop 0
	global_load_lds_dwordx4 v[142:143], off
	s_waitcnt vmcnt(8)
	s_waitcnt lgkmcnt(0)
	s_barrier
	s_waitcnt lgkmcnt(0)
	v_mfma_f32_16x16x32_bf16 v[126:129], v[148:151], v[180:183], v[126:129]
	v_mfma_f32_16x16x32_bf16 v[122:125], v[156:159], v[180:183], v[122:125]
	v_mfma_f32_16x16x32_bf16 v[110:113], v[148:151], v[188:191], v[110:113]
	v_mfma_f32_16x16x32_bf16 v[106:109], v[156:159], v[188:191], v[106:109]
	v_mfma_f32_16x16x32_bf16 v[94:97], v[148:151], v[210:213], v[94:97]
	v_mfma_f32_16x16x32_bf16 v[90:93], v[156:159], v[210:213], v[90:93]
	v_mfma_f32_16x16x32_bf16 v[78:81], v[148:151], v[218:221], v[78:81]
	v_mfma_f32_16x16x32_bf16 v[74:77], v[156:159], v[218:221], v[74:77]
	v_mfma_f32_16x16x32_bf16 v[126:129], v[152:155], v[184:187], v[126:129]
	v_mfma_f32_16x16x32_bf16 v[122:125], v[160:163], v[184:187], v[122:125]
	v_mfma_f32_16x16x32_bf16 v[110:113], v[152:155], v[192:195], v[110:113]
	v_mfma_f32_16x16x32_bf16 v[106:109], v[160:163], v[192:195], v[106:109]
	v_mfma_f32_16x16x32_bf16 v[94:97], v[152:155], v[214:217], v[94:97]
	v_mfma_f32_16x16x32_bf16 v[90:93], v[160:163], v[214:217], v[90:93]
	v_mfma_f32_16x16x32_bf16 v[78:81], v[152:155], v[222:225], v[78:81]
	v_mfma_f32_16x16x32_bf16 v[74:77], v[160:163], v[222:225], v[74:77]
	v_mfma_f32_16x16x32_bf16 v[118:121], v[164:167], v[180:183], v[118:121]
	v_mfma_f32_16x16x32_bf16 v[114:117], v[172:175], v[180:183], v[114:117]
	v_mfma_f32_16x16x32_bf16 v[102:105], v[164:167], v[188:191], v[102:105]
	v_mfma_f32_16x16x32_bf16 v[98:101], v[172:175], v[188:191], v[98:101]
	v_mfma_f32_16x16x32_bf16 v[86:89], v[164:167], v[210:213], v[86:89]
	v_mfma_f32_16x16x32_bf16 v[82:85], v[172:175], v[210:213], v[82:85]
	v_mfma_f32_16x16x32_bf16 v[70:73], v[164:167], v[218:221], v[70:73]
	v_mfma_f32_16x16x32_bf16 v[66:69], v[172:175], v[218:221], v[66:69]
	v_mfma_f32_16x16x32_bf16 v[118:121], v[168:171], v[184:187], v[118:121]
	v_mfma_f32_16x16x32_bf16 v[114:117], v[176:179], v[184:187], v[114:117]
	v_mfma_f32_16x16x32_bf16 v[102:105], v[168:171], v[192:195], v[102:105]
	v_mfma_f32_16x16x32_bf16 v[98:101], v[176:179], v[192:195], v[98:101]
	v_mfma_f32_16x16x32_bf16 v[86:89], v[168:171], v[214:217], v[86:89]
	v_mfma_f32_16x16x32_bf16 v[82:85], v[176:179], v[214:217], v[82:85]
	v_mfma_f32_16x16x32_bf16 v[70:73], v[168:171], v[222:225], v[70:73]
	v_mfma_f32_16x16x32_bf16 v[66:69], v[176:179], v[222:225], v[66:69]
	s_barrier
	s_add_i32 s68, s68, s30
	v_lshl_add_u64 v[142:143], s[26:27], 0, v[0:1]
	s_mov_b32 m0, s68
	ds_read_b128 v[180:183], v146 offset:16384
	ds_read_b128 v[184:187], v146 offset:17408
	ds_read_b128 v[188:191], v146 offset:18432
	ds_read_b128 v[192:195], v146 offset:19456
	ds_read_b128 v[210:213], v146 offset:20480
	ds_read_b128 v[214:217], v146 offset:21504
	ds_read_b128 v[218:221], v146 offset:22528
	ds_read_b128 v[222:225], v146 offset:23552
	global_load_lds_dwordx4 v[142:143], off
	s_add_i32 m0, s68, 0x2000
	s_add_u32 s68, s26, 0x80000
	v_lshl_add_u64 v[240:241], s[26:27], 0, v[130:131]
	s_addc_u32 s69, s27, 0
	s_add_i32 s70, s70, s30
	global_load_lds_dwordx4 v[240:241], off
	v_lshl_add_u64 v[242:243], s[68:69], 0, v[0:1]
	s_mov_b32 m0, s70
	v_lshl_add_u64 v[244:245], s[28:29], 0, v[132:133]
	global_load_lds_dwordx4 v[242:243], off
	v_lshl_add_u64 v[242:243], s[68:69], 0, v[130:131]
	s_add_i32 m0, s70, 0x2000
	s_nop 0
	global_load_lds_dwordx4 v[242:243], off
	v_lshl_add_u64 v[242:243], s[28:29], 0, v[134:135]
	s_waitcnt vmcnt(4)
	s_waitcnt lgkmcnt(0)
	s_barrier
; #define PG8_STAGE(bufoff, gbase, voff) do { _Pragma("unroll") for (int _i = 0; _i < 2; ++_i) \
;         __builtin_amdgcn_global_load_lds((const unsigned*)((const char*)(gbase) + (voff)[_i]), (LAS unsigned*)(lds + (bufoff) + ldsw + _i * 8192), 16, 0, 0); } while (0)
; #define PG8_LDA(dst, b, h) do { _Pragma("unroll") for (int m = 0; m < 4; ++m) _Pragma("unroll") for (int k = 0; k < 2; ++k) dst[m][k] = *(const LAS bf16x8*)(lds + PG8_SA(b, h) + aoff + m * 2048 + k * 1024); } while (0)
; #define PG8_LDB(dst, b, h) do { _Pragma("unroll") for (int n = 0; n < 2; ++n) _Pragma("unroll") for (int k = 0; k < 2; ++k) dst[n][k] = *(const LAS bf16x8*)(lds + PG8_SB(b, h) + boff + n * 2048 + k * 1024); } while (0)
; #define PG8_MMA(ai, bj, At, Bt) do { __builtin_amdgcn_s_setprio(1); _Pragma("unroll") for (int m = 0; m < 4; ++m) _Pragma("unroll") for (int n = 0; n < 2; ++n) _Pragma("unroll") for (int k = 0; k < 2; ++k) \
;         acc[ai][bj][m][n] = __builtin_amdgcn_mfma_f32_16x16x32_bf16(Bt[n][k], At[m][k], acc[ai][bj][m][n], 0, 0, 0); __builtin_amdgcn_s_setprio(0); } while (0)
; #define PG8_WAIT_V(n) asm volatile("s_waitcnt vmcnt(" #n ")" ::: "memory")
; #define PG8_WAIT_L(n) asm volatile("s_waitcnt lgkmcnt(" #n ")" ::: "memory")
; #define PG8_BAR __builtin_amdgcn_s_barrier()
; #define PG8_SCHED __builtin_amdgcn_sched_barrier(0)
; template <class Epi, bool ALIGN_EPI>
; __device__ __forceinline__ void gemm_phase(LAS unsigned char* lds, const int tid, const Gemm g, const StaticOrder& S, const Epi& E) {
;     ...
;             PG8_WAIT_V(8); PG8_WAIT_L(0); PG8_BAR; PG8_MMA(1, 0, At, B0); PG8_MMA(1, 1, At, B1); PG8_BAR; PG8_SCHED;
;             PG8_LDB(B0, 1, 0); PG8_LDB(B1, 1, 1); PG8_SCHED; PG8_LDA(At, 1, 0); PG8_STAGE(PG8_SA(0, 1), a2 + hstepA, voffA);
;             PG8_WAIT_V(8); PG8_WAIT_L(0); PG8_BAR; PG8_MMA(0, 0, At, B0); PG8_MMA(0, 1, At, B1); PG8_BAR; PG8_SCHED;
	s_waitcnt lgkmcnt(0)
	v_mfma_f32_16x16x32_bf16 v[62:65], v[148:151], v[180:183], v[62:65]
	v_mfma_f32_16x16x32_bf16 v[58:61], v[156:159], v[180:183], v[58:61]
	v_mfma_f32_16x16x32_bf16 v[46:49], v[148:151], v[188:191], v[46:49]
	v_mfma_f32_16x16x32_bf16 v[42:45], v[156:159], v[188:191], v[42:45]
	v_mfma_f32_16x16x32_bf16 v[30:33], v[148:151], v[210:213], v[30:33]
	v_mfma_f32_16x16x32_bf16 v[26:29], v[156:159], v[210:213], v[26:29]
	v_mfma_f32_16x16x32_bf16 v[14:17], v[148:151], v[218:221], v[14:17]
	v_mfma_f32_16x16x32_bf16 v[10:13], v[156:159], v[218:221], v[10:13]
	v_mfma_f32_16x16x32_bf16 v[62:65], v[152:155], v[184:187], v[62:65]
	v_mfma_f32_16x16x32_bf16 v[58:61], v[160:163], v[184:187], v[58:61]
	v_mfma_f32_16x16x32_bf16 v[46:49], v[152:155], v[192:195], v[46:49]
	v_mfma_f32_16x16x32_bf16 v[42:45], v[160:163], v[192:195], v[42:45]
	v_mfma_f32_16x16x32_bf16 v[30:33], v[152:155], v[214:217], v[30:33]
	v_mfma_f32_16x16x32_bf16 v[26:29], v[160:163], v[214:217], v[26:29]
	v_mfma_f32_16x16x32_bf16 v[14:17], v[152:155], v[222:225], v[14:17]
	v_mfma_f32_16x16x32_bf16 v[10:13], v[160:163], v[222:225], v[10:13]
	v_mfma_f32_16x16x32_bf16 v[54:57], v[164:167], v[180:183], v[54:57]
	v_mfma_f32_16x16x32_bf16 v[50:53], v[172:175], v[180:183], v[50:53]
	v_mfma_f32_16x16x32_bf16 v[38:41], v[164:167], v[188:191], v[38:41]
	v_mfma_f32_16x16x32_bf16 v[34:37], v[172:175], v[188:191], v[34:37]
	v_mfma_f32_16x16x32_bf16 v[22:25], v[164:167], v[210:213], v[22:25]
	v_mfma_f32_16x16x32_bf16 v[18:21], v[172:175], v[210:213], v[18:21]
	v_mfma_f32_16x16x32_bf16 v[6:9], v[164:167], v[218:221], v[6:9]
	v_mfma_f32_16x16x32_bf16 v[2:5], v[172:175], v[218:221], v[2:5]
	v_mfma_f32_16x16x32_bf16 v[54:57], v[168:171], v[184:187], v[54:57]
	v_mfma_f32_16x16x32_bf16 v[50:53], v[176:179], v[184:187], v[50:53]
	v_mfma_f32_16x16x32_bf16 v[38:41], v[168:171], v[192:195], v[38:41]
	v_mfma_f32_16x16x32_bf16 v[34:37], v[176:179], v[192:195], v[34:37]
	v_mfma_f32_16x16x32_bf16 v[22:25], v[168:171], v[214:217], v[22:25]
	v_mfma_f32_16x16x32_bf16 v[18:21], v[176:179], v[214:217], v[18:21]
	v_mfma_f32_16x16x32_bf16 v[6:9], v[168:171], v[222:225], v[6:9]
	v_mfma_f32_16x16x32_bf16 v[2:5], v[176:179], v[222:225], v[2:5]
	s_barrier
	s_add_i32 s68, 0, 0x18000
	v_add_u32_e32 v147, s68, v145
	s_add_i32 s69, 0, 0x1c000
	ds_read_b128 v[148:151], v147
	ds_read_b128 v[152:155], v147 offset:1024
	ds_read_b128 v[156:159], v147 offset:2048
	ds_read_b128 v[160:163], v147 offset:3072
	v_add_u32_e32 v147, s69, v145
	ds_read_b128 v[164:167], v147
	ds_read_b128 v[168:171], v147 offset:1024
	ds_read_b128 v[172:175], v147 offset:2048
	ds_read_b128 v[176:179], v147 offset:3072
	s_mov_b32 m0, s23
	s_nop 0
	global_load_lds_dwordx4 v[242:243], off
	s_mov_b32 m0, s52
	s_nop 0
	global_load_lds_dwordx4 v[244:245], off
	s_add_u32 s28, s28, 0x80000
	s_addc_u32 s29, s29, 0
	s_mov_b32 m0, s54
	v_lshl_add_u64 v[246:247], s[28:29], 0, v[134:135]
	ds_read_b128 v[180:183], v146 offset:32768
	ds_read_b128 v[184:187], v146 offset:33792
	ds_read_b128 v[188:191], v146 offset:34816
	ds_read_b128 v[192:195], v146 offset:35840
	ds_read_b128 v[210:213], v146 offset:36864
	ds_read_b128 v[214:217], v146 offset:37888
	ds_read_b128 v[218:221], v146 offset:38912
	ds_read_b128 v[222:225], v146 offset:39936
	global_load_lds_dwordx4 v[246:247], off
	v_lshl_add_u64 v[246:247], s[28:29], 0, v[132:133]
	s_mov_b32 m0, s55
	s_nop 0
	global_load_lds_dwordx4 v[246:247], off
	s_waitcnt vmcnt(8)
	s_waitcnt lgkmcnt(0)
	s_barrier
; #define PG8_STAGE(bufoff, gbase, voff) do { _Pragma("unroll") for (int _i = 0; _i < 2; ++_i) \
;         __builtin_amdgcn_global_load_lds((const unsigned*)((const char*)(gbase) + (voff)[_i]), (LAS unsigned*)(lds + (bufoff) + ldsw + _i * 8192), 16, 0, 0); } while (0)
; #define PG8_LDA(dst, b, h) do { _Pragma("unroll") for (int m = 0; m < 4; ++m) _Pragma("unroll") for (int k = 0; k < 2; ++k) dst[m][k] = *(const LAS bf16x8*)(lds + PG8_SA(b, h) + aoff + m * 2048 + k * 1024); } while (0)
; #define PG8_LDB(dst, b, h) do { _Pragma("unroll") for (int n = 0; n < 2; ++n) _Pragma("unroll") for (int k = 0; k < 2; ++k) dst[n][k] = *(const LAS bf16x8*)(lds + PG8_SB(b, h) + boff + n * 2048 + k * 1024); } while (0)
; #define PG8_MMA(ai, bj, At, Bt) do { __builtin_amdgcn_s_setprio(1); _Pragma("unroll") for (int m = 0; m < 4; ++m) _Pragma("unroll") for (int n = 0; n < 2; ++n) _Pragma("unroll") for (int k = 0; k < 2; ++k) \
;         acc[ai][bj][m][n] = __builtin_amdgcn_mfma_f32_16x16x32_bf16(Bt[n][k], At[m][k], acc[ai][bj][m][n], 0, 0, 0); __builtin_amdgcn_s_setprio(0); } while (0)
; #define PG8_WAIT_V(n) asm volatile("s_waitcnt vmcnt(" #n ")" ::: "memory")
; #define PG8_WAIT_L(n) asm volatile("s_waitcnt lgkmcnt(" #n ")" ::: "memory")
; #define PG8_BAR __builtin_amdgcn_s_barrier()
; #define PG8_SCHED __builtin_amdgcn_sched_barrier(0)
; template <class Epi, bool ALIGN_EPI>
; __device__ __forceinline__ void gemm_phase(LAS unsigned char* lds, const int tid, const Gemm g, const StaticOrder& S, const Epi& E) {
;     ...
;             PG8_WAIT_V(8); PG8_WAIT_L(0); PG8_BAR; PG8_MMA(1, 0, At, B0); PG8_MMA(1, 1, At, B1); PG8_BAR; PG8_SCHED;
;             PG8_LDB(B0, 1, 0); PG8_LDB(B1, 1, 1); PG8_SCHED; PG8_LDA(At, 1, 0); PG8_STAGE(PG8_SA(0, 1), a2 + hstepA, voffA);
;             PG8_WAIT_V(8); PG8_WAIT_L(0); PG8_BAR; PG8_MMA(0, 0, At, B0); PG8_MMA(0, 1, At, B1); PG8_BAR; PG8_SCHED;
;             PG8_LDA(At, 1, 1); PG8_STAGE(PG8_SB(1, 0), b3, voffB); PG8_STAGE(PG8_SB(1, 1), b3 + hstepB, voffB); PG8_STAGE(PG8_SA(1, 0), a3, voffA);
;             PG8_WAIT_V(8); PG8_WAIT_L(0); PG8_BAR; PG8_MMA(1, 0, At, B0); PG8_MMA(1, 1, At, B1); PG8_BAR; PG8_SCHED;
;         }
;         if constexpr (ALIGN_EPI) { if (wr == 0) PG8_BAR; }
	s_waitcnt lgkmcnt(0)
	v_mfma_f32_16x16x32_bf16 v[126:129], v[148:151], v[180:183], v[126:129]
	v_mfma_f32_16x16x32_bf16 v[122:125], v[156:159], v[180:183], v[122:125]
	v_mfma_f32_16x16x32_bf16 v[110:113], v[148:151], v[188:191], v[110:113]
	v_mfma_f32_16x16x32_bf16 v[106:109], v[156:159], v[188:191], v[106:109]
	v_mfma_f32_16x16x32_bf16 v[94:97], v[148:151], v[210:213], v[94:97]
	v_mfma_f32_16x16x32_bf16 v[90:93], v[156:159], v[210:213], v[90:93]
	v_mfma_f32_16x16x32_bf16 v[78:81], v[148:151], v[218:221], v[78:81]
	v_mfma_f32_16x16x32_bf16 v[74:77], v[156:159], v[218:221], v[74:77]
	v_mfma_f32_16x16x32_bf16 v[126:129], v[152:155], v[184:187], v[126:129]
	v_mfma_f32_16x16x32_bf16 v[122:125], v[160:163], v[184:187], v[122:125]
	v_mfma_f32_16x16x32_bf16 v[110:113], v[152:155], v[192:195], v[110:113]
	v_mfma_f32_16x16x32_bf16 v[106:109], v[160:163], v[192:195], v[106:109]
	v_mfma_f32_16x16x32_bf16 v[94:97], v[152:155], v[214:217], v[94:97]
	v_mfma_f32_16x16x32_bf16 v[90:93], v[160:163], v[214:217], v[90:93]
	v_mfma_f32_16x16x32_bf16 v[78:81], v[152:155], v[222:225], v[78:81]
	v_mfma_f32_16x16x32_bf16 v[74:77], v[160:163], v[222:225], v[74:77]
	v_mfma_f32_16x16x32_bf16 v[118:121], v[164:167], v[180:183], v[118:121]
	v_mfma_f32_16x16x32_bf16 v[114:117], v[172:175], v[180:183], v[114:117]
	v_mfma_f32_16x16x32_bf16 v[102:105], v[164:167], v[188:191], v[102:105]
	v_mfma_f32_16x16x32_bf16 v[98:101], v[172:175], v[188:191], v[98:101]
	v_mfma_f32_16x16x32_bf16 v[86:89], v[164:167], v[210:213], v[86:89]
	v_mfma_f32_16x16x32_bf16 v[82:85], v[172:175], v[210:213], v[82:85]
	v_mfma_f32_16x16x32_bf16 v[70:73], v[164:167], v[218:221], v[70:73]
	v_mfma_f32_16x16x32_bf16 v[66:69], v[172:175], v[218:221], v[66:69]
	v_mfma_f32_16x16x32_bf16 v[118:121], v[168:171], v[184:187], v[118:121]
	v_mfma_f32_16x16x32_bf16 v[114:117], v[176:179], v[184:187], v[114:117]
	v_mfma_f32_16x16x32_bf16 v[102:105], v[168:171], v[192:195], v[102:105]
	v_mfma_f32_16x16x32_bf16 v[98:101], v[176:179], v[192:195], v[98:101]
	v_mfma_f32_16x16x32_bf16 v[86:89], v[168:171], v[214:217], v[86:89]
	v_mfma_f32_16x16x32_bf16 v[82:85], v[176:179], v[214:217], v[82:85]
	v_mfma_f32_16x16x32_bf16 v[70:73], v[168:171], v[222:225], v[70:73]
	v_mfma_f32_16x16x32_bf16 v[66:69], v[176:179], v[222:225], v[66:69]
	s_barrier
	s_add_i32 s28, s68, s30
	v_lshl_add_u64 v[142:143], v[142:143], 0, s[42:43]
	s_mov_b32 m0, s28
	ds_read_b128 v[180:183], v146 offset:49152
	ds_read_b128 v[184:187], v146 offset:50176
	ds_read_b128 v[188:191], v146 offset:51200
	ds_read_b128 v[192:195], v146 offset:52224
	ds_read_b128 v[210:213], v146 offset:53248
	ds_read_b128 v[214:217], v146 offset:54272
	ds_read_b128 v[218:221], v146 offset:55296
	ds_read_b128 v[222:225], v146 offset:56320
	global_load_lds_dwordx4 v[142:143], off
	s_add_i32 m0, s28, 0x2000
	s_add_u32 s26, s26, 0x80080
	v_lshl_add_u64 v[142:143], v[240:241], 0, s[42:43]
	s_addc_u32 s27, s27, 0
	s_add_i32 s28, s69, s30
	global_load_lds_dwordx4 v[142:143], off
	v_lshl_add_u64 v[142:143], s[26:27], 0, v[0:1]
	s_mov_b32 m0, s28
	s_nop 0
	global_load_lds_dwordx4 v[142:143], off
	v_lshl_add_u64 v[142:143], s[26:27], 0, v[130:131]
	s_add_i32 m0, s28, 0x2000
	s_nop 0
	global_load_lds_dwordx4 v[142:143], off
	s_waitcnt vmcnt(4)
	s_waitcnt lgkmcnt(0)
	s_barrier
	s_waitcnt lgkmcnt(0)
	v_mfma_f32_16x16x32_bf16 v[62:65], v[148:151], v[180:183], v[62:65]
	v_mfma_f32_16x16x32_bf16 v[58:61], v[156:159], v[180:183], v[58:61]
	v_mfma_f32_16x16x32_bf16 v[46:49], v[148:151], v[188:191], v[46:49]
	v_mfma_f32_16x16x32_bf16 v[42:45], v[156:159], v[188:191], v[42:45]
	v_mfma_f32_16x16x32_bf16 v[30:33], v[148:151], v[210:213], v[30:33]
	v_mfma_f32_16x16x32_bf16 v[26:29], v[156:159], v[210:213], v[26:29]
	v_mfma_f32_16x16x32_bf16 v[14:17], v[148:151], v[218:221], v[14:17]
	v_mfma_f32_16x16x32_bf16 v[10:13], v[156:159], v[218:221], v[10:13]
	v_mfma_f32_16x16x32_bf16 v[62:65], v[152:155], v[184:187], v[62:65]
	v_mfma_f32_16x16x32_bf16 v[58:61], v[160:163], v[184:187], v[58:61]
	v_mfma_f32_16x16x32_bf16 v[46:49], v[152:155], v[192:195], v[46:49]
	v_mfma_f32_16x16x32_bf16 v[42:45], v[160:163], v[192:195], v[42:45]
	v_mfma_f32_16x16x32_bf16 v[30:33], v[152:155], v[214:217], v[30:33]
	v_mfma_f32_16x16x32_bf16 v[26:29], v[160:163], v[214:217], v[26:29]
	v_mfma_f32_16x16x32_bf16 v[14:17], v[152:155], v[222:225], v[14:17]
	v_mfma_f32_16x16x32_bf16 v[10:13], v[160:163], v[222:225], v[10:13]
	v_mfma_f32_16x16x32_bf16 v[54:57], v[164:167], v[180:183], v[54:57]
	v_mfma_f32_16x16x32_bf16 v[50:53], v[172:175], v[180:183], v[50:53]
	v_mfma_f32_16x16x32_bf16 v[38:41], v[164:167], v[188:191], v[38:41]
	v_mfma_f32_16x16x32_bf16 v[34:37], v[172:175], v[188:191], v[34:37]
	v_mfma_f32_16x16x32_bf16 v[22:25], v[164:167], v[210:213], v[22:25]
	v_mfma_f32_16x16x32_bf16 v[18:21], v[172:175], v[210:213], v[18:21]
	v_mfma_f32_16x16x32_bf16 v[6:9], v[164:167], v[218:221], v[6:9]
	v_mfma_f32_16x16x32_bf16 v[2:5], v[172:175], v[218:221], v[2:5]
	v_mfma_f32_16x16x32_bf16 v[54:57], v[168:171], v[184:187], v[54:57]
	v_mfma_f32_16x16x32_bf16 v[50:53], v[176:179], v[184:187], v[50:53]
	v_mfma_f32_16x16x32_bf16 v[38:41], v[168:171], v[192:195], v[38:41]
	v_mfma_f32_16x16x32_bf16 v[34:37], v[176:179], v[192:195], v[34:37]
	v_mfma_f32_16x16x32_bf16 v[22:25], v[168:171], v[214:217], v[22:25]
	v_mfma_f32_16x16x32_bf16 v[18:21], v[176:179], v[214:217], v[18:21]
	v_mfma_f32_16x16x32_bf16 v[6:9], v[168:171], v[222:225], v[6:9]
	v_mfma_f32_16x16x32_bf16 v[2:5], v[176:179], v[222:225], v[2:5]
	s_barrier
	s_add_i32 s67, s67, 2
	s_add_u32 s15, s15, 0x100
	s_addc_u32 s17, s17, 0
	s_add_u32 s24, s24, 0x100
	s_addc_u32 s25, s25, 0
	s_cmp_gt_u32 s67, 29
	s_cbranch_scc0 .LBB0_143
	s_and_b64 vcc, exec, s[12:13]
	s_cbranch_vccz .LBB0_146
	s_barrier

; #define PG8_STAGE(bufoff, gbase, voff) do { _Pragma("unroll") for (int _i = 0; _i < 2; ++_i) \
;         __builtin_amdgcn_global_load_lds((const unsigned*)((const char*)(gbase) + (voff)[_i]), (LAS unsigned*)(lds + (bufoff) + ldsw + _i * 8192), 16, 0, 0); } while (0)
; #define PG8_BAR __builtin_amdgcn_s_barrier()
; template <class Epi, bool ALIGN_EPI>
; __device__ __forceinline__ void gemm_phase(LAS unsigned char* lds, const int tid, const Gemm g, const StaticOrder& S, const Epi& E) {
;     ...
;     for (int i = 0; i < 2; ++i) { int R, C; stage_rc(tid * 16 + i * 8192, R, C); const int Rb = Epi::PERM ? ((R & ~31) + perm32(R & 31)) : R;
;         voffA[i] = (unsigned)R * rsA + (unsigned)C * 2u; voffB[i] = (unsigned)Rb * rsB + (unsigned)C * 2u; }
;     const size_t hstepA = (size_t)HALF * rsA, hstepB = (size_t)HALF * rsB;
;     const size_t tstepA = 2 * hstepA, tstepB = 2 * hstepB;
;     const unsigned ldsw = (unsigned)wid * 1024u;
;     const int aoff = lds_byte(wr * 64 + fr, fq * 8), boff = lds_byte(wc * 32 + fr, fq * 8);
;     ...
;     Unit cur, nxt; int ui = 0;
;     if (!S.next(0, cur)) return;
;     f32x4 acc[2][2][4][2];
; #pragma unroll
;     for (int a = 0; a < 2; ++a)
; #pragma unroll
;         for (int b = 0; b < 2; ++b)
; #pragma unroll
;             for (int m = 0; m < 4; ++m)
; #pragma unroll
;                 for (int n = 0; n < 2; ++n) acc[a][b][m][n] = (f32x4){0.f, 0.f, 0.f, 0.f};
;     bf16x8 At[4][2], B0[2][2], B1[2][2];
;     ...
;     const char* cA = (const char*)g.A + (size_t)cur.pm * tstepA + PG8_KOFFA(cur); const char* cB = (const char*)g.Bt + (size_t)cur.pn * tstepB + PG8_KOFFB(cur);
;     PG8_STAGE(PG8_SB(0, 0), cB, voffB); PG8_STAGE(PG8_SB(0, 1), cB + hstepB, voffB); PG8_STAGE(PG8_SA(0, 0), cA, voffA); PG8_STAGE(PG8_SA(0, 1), cA + hstepA, voffA);
;     if (wr == 1) PG8_BAR;
.LBB0_184:
	v_ashrrev_i32_e32 v0, 31, v208
	v_lshrrev_b32_e32 v0, 26, v0
	v_add_u32_e32 v0, v208, v0
	v_ashrrev_i32_e32 v10, 6, v0
	v_bfe_i32 v0, v208, 27, 1
	v_lshlrev_b32_e32 v2, 4, v208
	v_lshrrev_b32_e32 v0, 22, v0
	v_add_u32_e32 v0, v2, v0
	v_and_b32_e32 v0, 0xfffffc00, v0
	v_sub_u32_e32 v0, v2, v0
	v_lshrrev_b32_e32 v3, 4, v0
	v_bitop3_b32 v0, v3, v0, 32 bitop3:0x6c
	v_ashrrev_i32_e32 v4, 31, v0
	v_lshrrev_b32_e32 v4, 26, v4
	v_add_u32_e32 v4, v0, v4
	v_ashrrev_i32_e32 v11, 6, v4
	v_and_b32_e32 v4, 0xc0, v4
	v_sub_u32_e32 v0, v0, v4
	v_lshlrev_b32_e32 v3, 3, v10
	v_lshlrev_b32_e32 v5, 5, v10
	v_ashrrev_i16_sdwa v0, v226, sext(v0) dst_sel:DWORD dst_unused:UNUSED_PAD src0_sel:DWORD src1_sel:BYTE_0
	v_and_b32_e32 v3, 0xffff0, v3
	v_and_b32_e32 v5, 32, v5
	v_bfe_i32 v12, v0, 0, 16
	v_add_u32_e32 v0, v5, v12
	v_add_lshl_u32 v3, v11, v3, 12
	v_add_u32_e32 v2, 0x2000, v2
	s_ashr_i32 s29, s28, 31
	v_lshl_add_u32 v0, v0, 1, v3
	v_ashrrev_i32_e32 v3, 31, v2
	s_lshl_b64 s[16:17], s[28:29], 20
	v_lshrrev_b32_e32 v3, 22, v3
	s_add_u32 s16, s10, s16
	v_add_u32_e32 v3, v2, v3
	s_addc_u32 s17, s11, s17
	v_readlane_b32 s18, v249, 59
	v_ashrrev_i32_e32 v13, 10, v3
	s_add_u32 s29, s18, 0x3900000
	v_readlane_b32 s18, v249, 60
	v_mul_i32_i24_e32 v3, 0x400, v13
	s_addc_u32 s52, s18, 0
	v_sub_u32_e32 v2, v2, v3
	s_add_u32 s30, s16, s14
	v_lshrrev_b32_e32 v3, 4, v2
	s_addc_u32 s31, s17, s15
	s_ashr_i32 s27, s26, 31
	v_bitop3_b32 v2, v3, v2, 32 bitop3:0x6c
	s_lshl_b64 s[14:15], s[26:27], 20
	v_ashrrev_i32_e32 v4, 31, v2
	s_add_u32 s14, s29, s14
	v_lshrrev_b32_e32 v4, 26, v4
	s_addc_u32 s15, s52, s15
	s_ashr_i32 s16, s20, 6
	v_add_u32_e32 v4, v2, v4
	s_ashr_i32 s17, s20, 8
	v_ashrrev_i32_e32 v14, 6, v4
	v_and_b32_e32 v4, 0xc0, v4
	s_lshl_b32 s56, s16, 10
	v_sub_u32_e32 v2, v2, v4
	s_add_u32 s92, s14, s4
	v_lshlrev_b32_e32 v3, 3, v13
	v_lshlrev_b32_e32 v5, 5, v13
	v_ashrrev_i16_sdwa v2, v226, sext(v2) dst_sel:DWORD dst_unused:UNUSED_PAD src0_sel:DWORD src1_sel:BYTE_0
	s_addc_u32 s93, s15, s5
	s_add_i32 s58, s56, 0
	v_and_b32_e32 v3, 0xffff0, v3
	v_and_b32_e32 v5, 32, v5
	v_bfe_i32 v15, v2, 0, 16
	s_add_i32 m0, s58, 0x10000
	v_add_u32_e32 v2, v5, v15
	v_add_lshl_u32 v3, v14, v3, 12
	global_load_lds_dwordx4 v0, s[92:93]
	s_add_i32 m0, s58, 0x12000
	v_lshl_add_u32 v130, v2, 1, v3
	s_add_u32 s4, s92, 0x80000
	global_load_lds_dwordx4 v130, s[92:93]
	s_addc_u32 s5, s93, 0
	s_add_i32 m0, s58, 0x14000
	s_add_i32 s60, s58, 0x2000
	global_load_lds_dwordx4 v0, s[4:5]
	s_add_i32 m0, s58, 0x16000
	v_mov_b32_e32 v131, v1
	global_load_lds_dwordx4 v130, s[4:5]
	s_mov_b32 m0, s58
	s_add_u32 s4, s30, 0x80000
	global_load_lds_dwordx4 v0, s[30:31]
	s_mov_b32 m0, s60
	s_addc_u32 s5, s31, 0
	s_add_i32 s61, s58, 0x4000
	global_load_lds_dwordx4 v130, s[30:31]
	s_mov_b32 m0, s61
	s_add_i32 s62, s58, 0x6000
	global_load_lds_dwordx4 v0, s[4:5]
	s_mov_b32 m0, s62
	s_cmp_eq_u32 s17, 1
	global_load_lds_dwordx4 v130, s[4:5]
	v_lshl_add_u64 v[8:9], s[92:93], 0, v[0:1]
	v_lshl_add_u64 v[6:7], s[92:93], 0, v[130:131]
	v_lshl_add_u64 v[2:3], s[30:31], 0, v[0:1]
	s_cselect_b64 s[14:15], -1, 0
	s_cmp_lg_u32 s17, 1
	v_lshl_add_u64 v[4:5], s[30:31], 0, v[130:131]
	s_cbranch_scc1 .LBB0_186
	s_setprio 1
	s_barrier

; #define PG8_STAGE(bufoff, gbase, voff) do { _Pragma("unroll") for (int _i = 0; _i < 2; ++_i) \
;         __builtin_amdgcn_global_load_lds((const unsigned*)((const char*)(gbase) + (voff)[_i]), (LAS unsigned*)(lds + (bufoff) + ldsw + _i * 8192), 16, 0, 0); } while (0)
; #define PG8_LDA(dst, b, h) do { _Pragma("unroll") for (int m = 0; m < 4; ++m) _Pragma("unroll") for (int k = 0; k < 2; ++k) dst[m][k] = *(const LAS bf16x8*)(lds + PG8_SA(b, h) + aoff + m * 2048 + k * 1024); } while (0)
; #define PG8_LDB(dst, b, h) do { _Pragma("unroll") for (int n = 0; n < 2; ++n) _Pragma("unroll") for (int k = 0; k < 2; ++k) dst[n][k] = *(const LAS bf16x8*)(lds + PG8_SB(b, h) + boff + n * 2048 + k * 1024); } while (0)
; #define PG8_MMA(ai, bj, At, Bt) do { __builtin_amdgcn_s_setprio(1); _Pragma("unroll") for (int m = 0; m < 4; ++m) _Pragma("unroll") for (int n = 0; n < 2; ++n) _Pragma("unroll") for (int k = 0; k < 2; ++k) \
;         acc[ai][bj][m][n] = __builtin_amdgcn_mfma_f32_16x16x32_bf16(Bt[n][k], At[m][k], acc[ai][bj][m][n], 0, 0, 0); __builtin_amdgcn_s_setprio(0); } while (0)
; #define PG8_WAIT_V(n) asm volatile("s_waitcnt vmcnt(" #n ")" ::: "memory")
; #define PG8_WAIT_L(n) asm volatile("s_waitcnt lgkmcnt(" #n ")" ::: "memory")
; #define PG8_BAR __builtin_amdgcn_s_barrier()
; #define PG8_SCHED __builtin_amdgcn_sched_barrier(0)
; template <class Epi, bool ALIGN_EPI>
; __device__ __forceinline__ void gemm_phase(LAS unsigned char* lds, const int tid, const Gemm g, const StaticOrder& S, const Epi& E) {
;     ...
;             const bool last = (t == nt - 2);
;             const char* a1 = cA + (size_t)(t + 1) * kstepA;
;             const char* a2 = last ? nA : cA + (size_t)(t + 2) * kstepA; const char* b2 = last ? nB : cB + (size_t)(t + 2) * kstepB;
;             const char* a3 = a2 + kstepA; const char* b3 = b2 + kstepB;
;             PG8_LDB(B0, 0, 0); PG8_LDB(B1, 0, 1); PG8_SCHED; PG8_LDA(At, 0, 0); PG8_STAGE(PG8_SA(1, 1), a1 + hstepA, voffA);
;             PG8_WAIT_V(8); PG8_WAIT_L(0); PG8_BAR; PG8_MMA(0, 0, At, B0); PG8_MMA(0, 1, At, B1); PG8_BAR; PG8_SCHED;
;             PG8_LDA(At, 0, 1); PG8_STAGE(PG8_SB(0, 0), b2, voffB); PG8_STAGE(PG8_SB(0, 1), b2 + hstepB, voffB); PG8_STAGE(PG8_SA(0, 0), a2, voffA);
;             PG8_WAIT_V(8); PG8_WAIT_L(0); PG8_BAR; PG8_MMA(1, 0, At, B0); PG8_MMA(1, 1, At, B1); PG8_BAR; PG8_SCHED;
.LBB0_209:
	s_add_i32 s72, s34, 2
	s_add_u32 s35, s30, 0xfff80080
	s_addc_u32 s54, s31, -1
	s_cmp_eq_u32 s21, s34
	s_cselect_b32 s55, s23, s54
	s_cselect_b32 s54, s22, s35
	s_cselect_b32 s35, s25, s71
	s_cselect_b32 s34, s24, s27
	s_add_i32 s73, 0, 0x10000
	s_add_i32 s85, 0, 0x14000
	v_add_u32_e32 v148, s73, v175
	v_add_u32_e32 v164, s85, v175
	ds_read_b128 v[136:139], v148
	ds_read_b128 v[140:143], v148 offset:1024
	ds_read_b128 v[144:147], v148 offset:2048
	ds_read_b128 v[148:151], v148 offset:3072
	ds_read_b128 v[152:155], v164
	ds_read_b128 v[156:159], v164 offset:1024
	ds_read_b128 v[160:163], v164 offset:2048
	ds_read_b128 v[164:167], v164 offset:3072
	v_lshl_add_u64 v[172:173], s[30:31], 0, v[134:135]
	s_add_i32 m0, s58, 0xc000
	ds_read_b128 v[168:171], v177
	ds_read_b128 v[178:181], v177 offset:1024
	ds_read_b128 v[182:185], v177 offset:2048
	ds_read_b128 v[186:189], v177 offset:3072
	ds_read_b128 v[190:193], v177 offset:4096
	ds_read_b128 v[210:213], v177 offset:5120
	ds_read_b128 v[214:217], v177 offset:6144
	ds_read_b128 v[218:221], v177 offset:7168
	global_load_lds_dwordx4 v[172:173], off
	v_lshl_add_u64 v[172:173], s[30:31], 0, v[132:133]
	s_add_i32 m0, s58, 0xe000
	s_nop 0
	global_load_lds_dwordx4 v[172:173], off
	s_sub_u32 s98, s30, 0x80000
	s_subb_u32 s99, s31, 0
	v_lshl_add_u64 v[172:173], s[98:99], 0, v[134:135]
	s_mov_b32 m0, s65
	s_nop 0
	global_load_lds_dwordx4 v[172:173], off
	v_lshl_add_u64 v[172:173], s[98:99], 0, v[132:133]
	s_mov_b32 m0, s66
	s_nop 0
	global_load_lds_dwordx4 v[172:173], off
	s_waitcnt vmcnt(8)
	s_waitcnt lgkmcnt(0)
	s_barrier
	s_waitcnt lgkmcnt(0)
	v_mfma_f32_16x16x32_bf16 v[126:129], v[136:139], v[168:171], v[126:129]
	v_mfma_f32_16x16x32_bf16 v[94:97], v[144:147], v[168:171], v[94:97]
	v_mfma_f32_16x16x32_bf16 v[122:125], v[136:139], v[182:185], v[122:125]
	v_mfma_f32_16x16x32_bf16 v[90:93], v[144:147], v[182:185], v[90:93]
	v_mfma_f32_16x16x32_bf16 v[118:121], v[136:139], v[190:193], v[118:121]
	v_mfma_f32_16x16x32_bf16 v[86:89], v[144:147], v[190:193], v[86:89]
	v_mfma_f32_16x16x32_bf16 v[114:117], v[136:139], v[214:217], v[114:117]
	v_mfma_f32_16x16x32_bf16 v[82:85], v[144:147], v[214:217], v[82:85]
	v_mfma_f32_16x16x32_bf16 v[126:129], v[140:143], v[178:181], v[126:129]
	v_mfma_f32_16x16x32_bf16 v[94:97], v[148:151], v[178:181], v[94:97]
	v_mfma_f32_16x16x32_bf16 v[122:125], v[140:143], v[186:189], v[122:125]
	v_mfma_f32_16x16x32_bf16 v[90:93], v[148:151], v[186:189], v[90:93]
	v_mfma_f32_16x16x32_bf16 v[118:121], v[140:143], v[210:213], v[118:121]
	v_mfma_f32_16x16x32_bf16 v[86:89], v[148:151], v[210:213], v[86:89]
	v_mfma_f32_16x16x32_bf16 v[114:117], v[140:143], v[218:221], v[114:117]
	v_mfma_f32_16x16x32_bf16 v[82:85], v[148:151], v[218:221], v[82:85]
	v_mfma_f32_16x16x32_bf16 v[62:65], v[152:155], v[168:171], v[62:65]
	v_mfma_f32_16x16x32_bf16 v[42:45], v[160:163], v[168:171], v[42:45]
	v_mfma_f32_16x16x32_bf16 v[58:61], v[152:155], v[182:185], v[58:61]
	v_mfma_f32_16x16x32_bf16 v[34:37], v[160:163], v[182:185], v[34:37]
	v_mfma_f32_16x16x32_bf16 v[54:57], v[152:155], v[190:193], v[54:57]
	v_mfma_f32_16x16x32_bf16 v[26:29], v[160:163], v[190:193], v[26:29]
	v_mfma_f32_16x16x32_bf16 v[50:53], v[152:155], v[214:217], v[50:53]
	v_mfma_f32_16x16x32_bf16 v[18:21], v[160:163], v[214:217], v[18:21]
	v_mfma_f32_16x16x32_bf16 v[62:65], v[156:159], v[178:181], v[62:65]
	v_mfma_f32_16x16x32_bf16 v[42:45], v[164:167], v[178:181], v[42:45]
	v_mfma_f32_16x16x32_bf16 v[58:61], v[156:159], v[186:189], v[58:61]
	v_mfma_f32_16x16x32_bf16 v[34:37], v[164:167], v[186:189], v[34:37]
	v_mfma_f32_16x16x32_bf16 v[54:57], v[156:159], v[210:213], v[54:57]
	v_mfma_f32_16x16x32_bf16 v[26:29], v[164:167], v[210:213], v[26:29]
	v_mfma_f32_16x16x32_bf16 v[50:53], v[156:159], v[218:221], v[50:53]
	v_mfma_f32_16x16x32_bf16 v[18:21], v[164:167], v[218:221], v[18:21]
	s_barrier
	s_add_i32 s73, s73, s56
	v_lshl_add_u64 v[172:173], s[34:35], 0, v[0:1]
	s_mov_b32 m0, s73
	ds_read_b128 v[168:171], v177 offset:16384
	ds_read_b128 v[178:181], v177 offset:17408
	ds_read_b128 v[182:185], v177 offset:18432
	ds_read_b128 v[186:189], v177 offset:19456
	ds_read_b128 v[190:193], v177 offset:20480
	ds_read_b128 v[210:213], v177 offset:21504
	ds_read_b128 v[214:217], v177 offset:22528
	ds_read_b128 v[218:221], v177 offset:23552
	global_load_lds_dwordx4 v[172:173], off
	s_add_i32 m0, s73, 0x2000
	s_add_u32 s90, s34, 0x80000
	v_lshl_add_u64 v[194:195], s[34:35], 0, v[130:131]
	s_addc_u32 s91, s35, 0
	s_add_i32 s73, s85, s56
	global_load_lds_dwordx4 v[194:195], off
	v_lshl_add_u64 v[222:223], s[90:91], 0, v[0:1]
	s_mov_b32 m0, s73
	v_lshl_add_u64 v[224:225], s[54:55], 0, v[130:131]
	global_load_lds_dwordx4 v[222:223], off
	v_lshl_add_u64 v[222:223], s[90:91], 0, v[130:131]
	s_add_i32 m0, s73, 0x2000
	s_nop 0
	global_load_lds_dwordx4 v[222:223], off
	v_lshl_add_u64 v[222:223], s[54:55], 0, v[0:1]
	s_waitcnt vmcnt(4)
	s_waitcnt lgkmcnt(0)
	s_barrier
; #define PG8_STAGE(bufoff, gbase, voff) do { _Pragma("unroll") for (int _i = 0; _i < 2; ++_i) \
;         __builtin_amdgcn_global_load_lds((const unsigned*)((const char*)(gbase) + (voff)[_i]), (LAS unsigned*)(lds + (bufoff) + ldsw + _i * 8192), 16, 0, 0); } while (0)
; #define PG8_LDA(dst, b, h) do { _Pragma("unroll") for (int m = 0; m < 4; ++m) _Pragma("unroll") for (int k = 0; k < 2; ++k) dst[m][k] = *(const LAS bf16x8*)(lds + PG8_SA(b, h) + aoff + m * 2048 + k * 1024); } while (0)
; #define PG8_LDB(dst, b, h) do { _Pragma("unroll") for (int n = 0; n < 2; ++n) _Pragma("unroll") for (int k = 0; k < 2; ++k) dst[n][k] = *(const LAS bf16x8*)(lds + PG8_SB(b, h) + boff + n * 2048 + k * 1024); } while (0)
; #define PG8_MMA(ai, bj, At, Bt) do { __builtin_amdgcn_s_setprio(1); _Pragma("unroll") for (int m = 0; m < 4; ++m) _Pragma("unroll") for (int n = 0; n < 2; ++n) _Pragma("unroll") for (int k = 0; k < 2; ++k) \
;         acc[ai][bj][m][n] = __builtin_amdgcn_mfma_f32_16x16x32_bf16(Bt[n][k], At[m][k], acc[ai][bj][m][n], 0, 0, 0); __builtin_amdgcn_s_setprio(0); } while (0)
; #define PG8_WAIT_V(n) asm volatile("s_waitcnt vmcnt(" #n ")" ::: "memory")
; #define PG8_WAIT_L(n) asm volatile("s_waitcnt lgkmcnt(" #n ")" ::: "memory")
; #define PG8_BAR __builtin_amdgcn_s_barrier()
; #define PG8_SCHED __builtin_amdgcn_sched_barrier(0)
; template <class Epi, bool ALIGN_EPI>
; __device__ __forceinline__ void gemm_phase(LAS unsigned char* lds, const int tid, const Gemm g, const StaticOrder& S, const Epi& E) {
;     ...
;             PG8_WAIT_V(8); PG8_WAIT_L(0); PG8_BAR; PG8_MMA(1, 0, At, B0); PG8_MMA(1, 1, At, B1); PG8_BAR; PG8_SCHED;
;             PG8_LDB(B0, 1, 0); PG8_LDB(B1, 1, 1); PG8_SCHED; PG8_LDA(At, 1, 0); PG8_STAGE(PG8_SA(0, 1), a2 + hstepA, voffA);
;             PG8_WAIT_V(8); PG8_WAIT_L(0); PG8_BAR; PG8_MMA(0, 0, At, B0); PG8_MMA(0, 1, At, B1); PG8_BAR; PG8_SCHED;
	s_waitcnt lgkmcnt(0)
	v_mfma_f32_16x16x32_bf16 v[110:113], v[136:139], v[168:171], v[110:113]
	v_mfma_f32_16x16x32_bf16 v[78:81], v[144:147], v[168:171], v[78:81]
	v_mfma_f32_16x16x32_bf16 v[106:109], v[136:139], v[182:185], v[106:109]
	v_mfma_f32_16x16x32_bf16 v[74:77], v[144:147], v[182:185], v[74:77]
	v_mfma_f32_16x16x32_bf16 v[102:105], v[136:139], v[190:193], v[102:105]
	v_mfma_f32_16x16x32_bf16 v[70:73], v[144:147], v[190:193], v[70:73]
	v_mfma_f32_16x16x32_bf16 v[98:101], v[136:139], v[214:217], v[98:101]
	v_mfma_f32_16x16x32_bf16 v[66:69], v[144:147], v[214:217], v[66:69]
	v_mfma_f32_16x16x32_bf16 v[110:113], v[140:143], v[178:181], v[110:113]
	v_mfma_f32_16x16x32_bf16 v[78:81], v[148:151], v[178:181], v[78:81]
	v_mfma_f32_16x16x32_bf16 v[106:109], v[140:143], v[186:189], v[106:109]
	v_mfma_f32_16x16x32_bf16 v[74:77], v[148:151], v[186:189], v[74:77]
	v_mfma_f32_16x16x32_bf16 v[102:105], v[140:143], v[210:213], v[102:105]
	v_mfma_f32_16x16x32_bf16 v[70:73], v[148:151], v[210:213], v[70:73]
	v_mfma_f32_16x16x32_bf16 v[98:101], v[140:143], v[218:221], v[98:101]
	v_mfma_f32_16x16x32_bf16 v[66:69], v[148:151], v[218:221], v[66:69]
	v_mfma_f32_16x16x32_bf16 v[46:49], v[152:155], v[168:171], v[46:49]
	v_mfma_f32_16x16x32_bf16 v[14:17], v[160:163], v[168:171], v[14:17]
	v_mfma_f32_16x16x32_bf16 v[38:41], v[152:155], v[182:185], v[38:41]
	v_mfma_f32_16x16x32_bf16 v[10:13], v[160:163], v[182:185], v[10:13]
	v_mfma_f32_16x16x32_bf16 v[30:33], v[152:155], v[190:193], v[30:33]
	v_mfma_f32_16x16x32_bf16 v[6:9], v[160:163], v[190:193], v[6:9]
	v_mfma_f32_16x16x32_bf16 v[22:25], v[152:155], v[214:217], v[22:25]
	v_mfma_f32_16x16x32_bf16 v[2:5], v[160:163], v[214:217], v[2:5]
	v_mfma_f32_16x16x32_bf16 v[46:49], v[156:159], v[178:181], v[46:49]
	v_mfma_f32_16x16x32_bf16 v[14:17], v[164:167], v[178:181], v[14:17]
	v_mfma_f32_16x16x32_bf16 v[38:41], v[156:159], v[186:189], v[38:41]
	v_mfma_f32_16x16x32_bf16 v[10:13], v[164:167], v[186:189], v[10:13]
	v_mfma_f32_16x16x32_bf16 v[30:33], v[156:159], v[210:213], v[30:33]
	v_mfma_f32_16x16x32_bf16 v[6:9], v[164:167], v[210:213], v[6:9]
	v_mfma_f32_16x16x32_bf16 v[22:25], v[156:159], v[218:221], v[22:25]
	v_mfma_f32_16x16x32_bf16 v[2:5], v[164:167], v[218:221], v[2:5]
	s_barrier
	s_add_i32 s73, 0, 0x18000
	s_add_i32 s85, 0, 0x1c000
	v_add_u32_e32 v148, s73, v175
	v_add_u32_e32 v164, s85, v175
	ds_read_b128 v[136:139], v148
	ds_read_b128 v[140:143], v148 offset:1024
	ds_read_b128 v[144:147], v148 offset:2048
	ds_read_b128 v[148:151], v148 offset:3072
	ds_read_b128 v[152:155], v164
	ds_read_b128 v[156:159], v164 offset:1024
	ds_read_b128 v[160:163], v164 offset:2048
	ds_read_b128 v[164:167], v164 offset:3072
	s_mov_b32 m0, s58
	s_nop 0
	global_load_lds_dwordx4 v[222:223], off
	s_mov_b32 m0, s60
	s_nop 0
	global_load_lds_dwordx4 v[224:225], off
	s_add_u32 s54, s54, 0x80000
	s_addc_u32 s55, s55, 0
	s_mov_b32 m0, s61
	v_lshl_add_u64 v[240:241], s[54:55], 0, v[0:1]
	ds_read_b128 v[168:171], v177 offset:32768
	ds_read_b128 v[178:181], v177 offset:33792
	ds_read_b128 v[182:185], v177 offset:34816
	ds_read_b128 v[186:189], v177 offset:35840
	ds_read_b128 v[190:193], v177 offset:36864
	ds_read_b128 v[210:213], v177 offset:37888
	ds_read_b128 v[214:217], v177 offset:38912
	ds_read_b128 v[218:221], v177 offset:39936
	global_load_lds_dwordx4 v[240:241], off
	v_lshl_add_u64 v[240:241], s[54:55], 0, v[130:131]
	s_mov_b32 m0, s62
	s_nop 0
	global_load_lds_dwordx4 v[240:241], off
	s_waitcnt vmcnt(8)
	s_waitcnt lgkmcnt(0)
	s_barrier
; #define PG8_STAGE(bufoff, gbase, voff) do { _Pragma("unroll") for (int _i = 0; _i < 2; ++_i) \
;         __builtin_amdgcn_global_load_lds((const unsigned*)((const char*)(gbase) + (voff)[_i]), (LAS unsigned*)(lds + (bufoff) + ldsw + _i * 8192), 16, 0, 0); } while (0)
; #define PG8_LDA(dst, b, h) do { _Pragma("unroll") for (int m = 0; m < 4; ++m) _Pragma("unroll") for (int k = 0; k < 2; ++k) dst[m][k] = *(const LAS bf16x8*)(lds + PG8_SA(b, h) + aoff + m * 2048 + k * 1024); } while (0)
; #define PG8_LDB(dst, b, h) do { _Pragma("unroll") for (int n = 0; n < 2; ++n) _Pragma("unroll") for (int k = 0; k < 2; ++k) dst[n][k] = *(const LAS bf16x8*)(lds + PG8_SB(b, h) + boff + n * 2048 + k * 1024); } while (0)
; #define PG8_MMA(ai, bj, At, Bt) do { __builtin_amdgcn_s_setprio(1); _Pragma("unroll") for (int m = 0; m < 4; ++m) _Pragma("unroll") for (int n = 0; n < 2; ++n) _Pragma("unroll") for (int k = 0; k < 2; ++k) \
;         acc[ai][bj][m][n] = __builtin_amdgcn_mfma_f32_16x16x32_bf16(Bt[n][k], At[m][k], acc[ai][bj][m][n], 0, 0, 0); __builtin_amdgcn_s_setprio(0); } while (0)
; #define PG8_WAIT_V(n) asm volatile("s_waitcnt vmcnt(" #n ")" ::: "memory")
; #define PG8_WAIT_L(n) asm volatile("s_waitcnt lgkmcnt(" #n ")" ::: "memory")
; #define PG8_BAR __builtin_amdgcn_s_barrier()
; #define PG8_SCHED __builtin_amdgcn_sched_barrier(0)
; template <class Epi, bool ALIGN_EPI>
; __device__ __forceinline__ void gemm_phase(LAS unsigned char* lds, const int tid, const Gemm g, const StaticOrder& S, const Epi& E) {
;     ...
;             PG8_WAIT_V(8); PG8_WAIT_L(0); PG8_BAR; PG8_MMA(1, 0, At, B0); PG8_MMA(1, 1, At, B1); PG8_BAR; PG8_SCHED;
;             PG8_LDB(B0, 1, 0); PG8_LDB(B1, 1, 1); PG8_SCHED; PG8_LDA(At, 1, 0); PG8_STAGE(PG8_SA(0, 1), a2 + hstepA, voffA);
;             PG8_WAIT_V(8); PG8_WAIT_L(0); PG8_BAR; PG8_MMA(0, 0, At, B0); PG8_MMA(0, 1, At, B1); PG8_BAR; PG8_SCHED;
;             PG8_LDA(At, 1, 1); PG8_STAGE(PG8_SB(1, 0), b3, voffB); PG8_STAGE(PG8_SB(1, 1), b3 + hstepB, voffB); PG8_STAGE(PG8_SA(1, 0), a3, voffA);
;             PG8_WAIT_V(8); PG8_WAIT_L(0); PG8_BAR; PG8_MMA(1, 0, At, B0); PG8_MMA(1, 1, At, B1); PG8_BAR; PG8_SCHED;
;         }
;         if constexpr (ALIGN_EPI) { if (wr == 0) PG8_BAR; }
	s_waitcnt lgkmcnt(0)
	v_mfma_f32_16x16x32_bf16 v[126:129], v[136:139], v[168:171], v[126:129]
	v_mfma_f32_16x16x32_bf16 v[94:97], v[144:147], v[168:171], v[94:97]
	v_mfma_f32_16x16x32_bf16 v[122:125], v[136:139], v[182:185], v[122:125]
	v_mfma_f32_16x16x32_bf16 v[90:93], v[144:147], v[182:185], v[90:93]
	v_mfma_f32_16x16x32_bf16 v[118:121], v[136:139], v[190:193], v[118:121]
	v_mfma_f32_16x16x32_bf16 v[86:89], v[144:147], v[190:193], v[86:89]
	v_mfma_f32_16x16x32_bf16 v[114:117], v[136:139], v[214:217], v[114:117]
	v_mfma_f32_16x16x32_bf16 v[82:85], v[144:147], v[214:217], v[82:85]
	v_mfma_f32_16x16x32_bf16 v[126:129], v[140:143], v[178:181], v[126:129]
	v_mfma_f32_16x16x32_bf16 v[94:97], v[148:151], v[178:181], v[94:97]
	v_mfma_f32_16x16x32_bf16 v[122:125], v[140:143], v[186:189], v[122:125]
	v_mfma_f32_16x16x32_bf16 v[90:93], v[148:151], v[186:189], v[90:93]
	v_mfma_f32_16x16x32_bf16 v[118:121], v[140:143], v[210:213], v[118:121]
	v_mfma_f32_16x16x32_bf16 v[86:89], v[148:151], v[210:213], v[86:89]
	v_mfma_f32_16x16x32_bf16 v[114:117], v[140:143], v[218:221], v[114:117]
	v_mfma_f32_16x16x32_bf16 v[82:85], v[148:151], v[218:221], v[82:85]
	v_mfma_f32_16x16x32_bf16 v[62:65], v[152:155], v[168:171], v[62:65]
	v_mfma_f32_16x16x32_bf16 v[42:45], v[160:163], v[168:171], v[42:45]
	v_mfma_f32_16x16x32_bf16 v[58:61], v[152:155], v[182:185], v[58:61]
	v_mfma_f32_16x16x32_bf16 v[34:37], v[160:163], v[182:185], v[34:37]
	v_mfma_f32_16x16x32_bf16 v[54:57], v[152:155], v[190:193], v[54:57]
	v_mfma_f32_16x16x32_bf16 v[26:29], v[160:163], v[190:193], v[26:29]
	v_mfma_f32_16x16x32_bf16 v[50:53], v[152:155], v[214:217], v[50:53]
	v_mfma_f32_16x16x32_bf16 v[18:21], v[160:163], v[214:217], v[18:21]
	v_mfma_f32_16x16x32_bf16 v[62:65], v[156:159], v[178:181], v[62:65]
	v_mfma_f32_16x16x32_bf16 v[42:45], v[164:167], v[178:181], v[42:45]
	v_mfma_f32_16x16x32_bf16 v[58:61], v[156:159], v[186:189], v[58:61]
	v_mfma_f32_16x16x32_bf16 v[34:37], v[164:167], v[186:189], v[34:37]
	v_mfma_f32_16x16x32_bf16 v[54:57], v[156:159], v[210:213], v[54:57]
	v_mfma_f32_16x16x32_bf16 v[26:29], v[164:167], v[210:213], v[26:29]
	v_mfma_f32_16x16x32_bf16 v[50:53], v[156:159], v[218:221], v[50:53]
	v_mfma_f32_16x16x32_bf16 v[18:21], v[164:167], v[218:221], v[18:21]
	s_barrier
	s_add_i32 s54, s73, s56
	v_lshl_add_u64 v[172:173], v[172:173], 0, s[42:43]
	s_mov_b32 m0, s54
	ds_read_b128 v[168:171], v177 offset:49152
	ds_read_b128 v[178:181], v177 offset:50176
	ds_read_b128 v[182:185], v177 offset:51200
	ds_read_b128 v[186:189], v177 offset:52224
	ds_read_b128 v[190:193], v177 offset:53248
	ds_read_b128 v[210:213], v177 offset:54272
	ds_read_b128 v[214:217], v177 offset:55296
	ds_read_b128 v[218:221], v177 offset:56320
	global_load_lds_dwordx4 v[172:173], off
	s_add_i32 m0, s54, 0x2000
	s_add_u32 s34, s34, 0x80080
	v_lshl_add_u64 v[172:173], v[194:195], 0, s[42:43]
	s_addc_u32 s35, s35, 0
	s_add_i32 s54, s85, s56
	global_load_lds_dwordx4 v[172:173], off
	v_lshl_add_u64 v[172:173], s[34:35], 0, v[0:1]
	s_mov_b32 m0, s54
	s_nop 0
	global_load_lds_dwordx4 v[172:173], off
	v_lshl_add_u64 v[172:173], s[34:35], 0, v[130:131]
	s_add_i32 m0, s54, 0x2000
	s_nop 0
	global_load_lds_dwordx4 v[172:173], off
	s_waitcnt vmcnt(4)
	s_waitcnt lgkmcnt(0)
	s_barrier
	s_waitcnt lgkmcnt(0)
	v_mfma_f32_16x16x32_bf16 v[110:113], v[136:139], v[168:171], v[110:113]
	v_mfma_f32_16x16x32_bf16 v[78:81], v[144:147], v[168:171], v[78:81]
	v_mfma_f32_16x16x32_bf16 v[106:109], v[136:139], v[182:185], v[106:109]
	v_mfma_f32_16x16x32_bf16 v[74:77], v[144:147], v[182:185], v[74:77]
	v_mfma_f32_16x16x32_bf16 v[102:105], v[136:139], v[190:193], v[102:105]
	v_mfma_f32_16x16x32_bf16 v[70:73], v[144:147], v[190:193], v[70:73]
	v_mfma_f32_16x16x32_bf16 v[98:101], v[136:139], v[214:217], v[98:101]
	v_mfma_f32_16x16x32_bf16 v[66:69], v[144:147], v[214:217], v[66:69]
	v_mfma_f32_16x16x32_bf16 v[110:113], v[140:143], v[178:181], v[110:113]
	v_mfma_f32_16x16x32_bf16 v[78:81], v[148:151], v[178:181], v[78:81]
	v_mfma_f32_16x16x32_bf16 v[106:109], v[140:143], v[186:189], v[106:109]
	v_mfma_f32_16x16x32_bf16 v[74:77], v[148:151], v[186:189], v[74:77]
	v_mfma_f32_16x16x32_bf16 v[102:105], v[140:143], v[210:213], v[102:105]
	v_mfma_f32_16x16x32_bf16 v[70:73], v[148:151], v[210:213], v[70:73]
	v_mfma_f32_16x16x32_bf16 v[98:101], v[140:143], v[218:221], v[98:101]
	v_mfma_f32_16x16x32_bf16 v[66:69], v[148:151], v[218:221], v[66:69]
	v_mfma_f32_16x16x32_bf16 v[46:49], v[152:155], v[168:171], v[46:49]
	v_mfma_f32_16x16x32_bf16 v[14:17], v[160:163], v[168:171], v[14:17]
	v_mfma_f32_16x16x32_bf16 v[38:41], v[152:155], v[182:185], v[38:41]
	v_mfma_f32_16x16x32_bf16 v[10:13], v[160:163], v[182:185], v[10:13]
	v_mfma_f32_16x16x32_bf16 v[30:33], v[152:155], v[190:193], v[30:33]
	v_mfma_f32_16x16x32_bf16 v[6:9], v[160:163], v[190:193], v[6:9]
	v_mfma_f32_16x16x32_bf16 v[22:25], v[152:155], v[214:217], v[22:25]
	v_mfma_f32_16x16x32_bf16 v[2:5], v[160:163], v[214:217], v[2:5]
	v_mfma_f32_16x16x32_bf16 v[46:49], v[156:159], v[178:181], v[46:49]
	v_mfma_f32_16x16x32_bf16 v[14:17], v[164:167], v[178:181], v[14:17]
	v_mfma_f32_16x16x32_bf16 v[38:41], v[156:159], v[186:189], v[38:41]
	v_mfma_f32_16x16x32_bf16 v[10:13], v[164:167], v[186:189], v[10:13]
	v_mfma_f32_16x16x32_bf16 v[30:33], v[156:159], v[210:213], v[30:33]
	v_mfma_f32_16x16x32_bf16 v[6:9], v[164:167], v[210:213], v[6:9]
	v_mfma_f32_16x16x32_bf16 v[22:25], v[156:159], v[218:221], v[22:25]
	v_mfma_f32_16x16x32_bf16 v[2:5], v[164:167], v[218:221], v[2:5]
	s_barrier
	s_add_u32 s27, s27, 0x100
	s_addc_u32 s71, s71, 0
	s_add_u32 s30, s30, 0x100
	s_addc_u32 s31, s31, 0
	s_cmp_ge_u32 s72, s19
	s_mov_b32 s34, s72
	s_cbranch_scc0 .LBB0_209
	s_and_b64 vcc, exec, s[16:17]
	s_cbranch_vccz .LBB0_212
	s_barrier

; #define PG8_STAGE(bufoff, gbase, voff) do { _Pragma("unroll") for (int _i = 0; _i < 2; ++_i) \
;         __builtin_amdgcn_global_load_lds((const unsigned*)((const char*)(gbase) + (voff)[_i]), (LAS unsigned*)(lds + (bufoff) + ldsw + _i * 8192), 16, 0, 0); } while (0)
; #define PG8_BAR __builtin_amdgcn_s_barrier()
; template <class Epi, bool ALIGN_EPI>
; __device__ __forceinline__ void gemm_phase(LAS unsigned char* lds, const int tid, const Gemm g, const StaticOrder& S, const Epi& E) {
;     ...
;     for (int i = 0; i < 2; ++i) { int R, C; stage_rc(tid * 16 + i * 8192, R, C); const int Rb = Epi::PERM ? ((R & ~31) + perm32(R & 31)) : R;
;         voffA[i] = (unsigned)R * rsA + (unsigned)C * 2u; voffB[i] = (unsigned)Rb * rsB + (unsigned)C * 2u; }
;     const size_t hstepA = (size_t)HALF * rsA, hstepB = (size_t)HALF * rsB;
;     const size_t tstepA = 2 * hstepA, tstepB = 2 * hstepB;
;     const unsigned ldsw = (unsigned)wid * 1024u;
;     const int aoff = lds_byte(wr * 64 + fr, fq * 8), boff = lds_byte(wc * 32 + fr, fq * 8);
;     ...
;     Unit cur, nxt; int ui = 0;
;     if (!S.next(0, cur)) return;
;     f32x4 acc[2][2][4][2];
; #pragma unroll
;     for (int a = 0; a < 2; ++a)
; #pragma unroll
;         for (int b = 0; b < 2; ++b)
; #pragma unroll
;             for (int m = 0; m < 4; ++m)
; #pragma unroll
;                 for (int n = 0; n < 2; ++n) acc[a][b][m][n] = (f32x4){0.f, 0.f, 0.f, 0.f};
;     bf16x8 At[4][2], B0[2][2], B1[2][2];
;     ...
;     const char* cA = (const char*)g.A + (size_t)cur.pm * tstepA + PG8_KOFFA(cur); const char* cB = (const char*)g.Bt + (size_t)cur.pn * tstepB + PG8_KOFFB(cur);
;     PG8_STAGE(PG8_SB(0, 0), cB, voffB); PG8_STAGE(PG8_SB(0, 1), cB + hstepB, voffB); PG8_STAGE(PG8_SA(0, 0), cA, voffA); PG8_STAGE(PG8_SA(0, 1), cA + hstepA, voffA);
;     if (wr == 1) PG8_BAR;
.Lmerge_nodelay:
	v_bfe_i32 v3, v208, 27, 1
	v_lshlrev_b32_e32 v2, 4, v208
	v_lshrrev_b32_e32 v3, 22, v3
	v_add_u32_e32 v3, v2, v3
	v_and_b32_e32 v3, 0xfffffc00, v3
	v_sub_u32_e32 v3, v2, v3
	v_lshrrev_b32_e32 v4, 4, v3
	v_ashrrev_i32_e32 v0, 31, v208
	v_bitop3_b32 v3, v4, v3, 32 bitop3:0x6c
	s_add_u32 s63, s57, 0x17000000
	v_lshrrev_b32_e32 v0, 26, v0
	v_ashrrev_i32_e32 v5, 31, v3
	s_addc_u32 s64, s49, 0
	s_ashr_i32 s93, s92, 31
	v_add_u32_e32 v0, v208, v0
	v_lshrrev_b32_e32 v5, 26, v5
	s_lshl_b64 s[8:9], s[92:93], 20
	v_ashrrev_i32_e32 v0, 6, v0
	v_add_u32_e32 v5, v3, v5
	s_add_u32 s8, s63, s8
	v_lshlrev_b32_e32 v4, 3, v0
	v_ashrrev_i32_e32 v10, 6, v5
	v_and_b32_e32 v5, 0xc0, v5
	s_addc_u32 s9, s64, s9
	v_readlane_b32 s14, v249, 59
	v_and_b32_e32 v4, -16, v4
	v_sub_u32_e32 v3, v3, v5
	s_add_u32 s65, s14, 0x3100000
	v_readlane_b32 s14, v249, 60
	v_add_u32_e32 v4, v10, v4
	v_ashrrev_i16_sdwa v3, v226, sext(v3) dst_sel:DWORD dst_unused:UNUSED_PAD src0_sel:DWORD src1_sel:BYTE_0
	s_addc_u32 s66, s14, 0
	v_lshlrev_b32_e32 v6, 5, v0
	v_bfe_i32 v11, v3, 0, 16
	v_lshlrev_b32_e32 v3, 1, v4
	v_lshrrev_b32_e32 v5, 2, v4
	v_and_b32_e32 v7, 3, v10
	s_mov_b32 s14, 0xfffe0
	v_and_b32_e32 v6, 32, v6
	v_and_b32_e32 v3, 24, v3
	v_and_b32_e32 v5, 4, v5
	v_and_or_b32 v7, v4, s14, v7
	v_or3_b32 v3, v7, v5, v3
	v_add_lshl_u32 v5, v6, v11, 1
	v_add_u32_e32 v2, 0x2000, v2
	v_lshl_add_u32 v212, v3, 12, v5
	v_ashrrev_i32_e32 v3, 31, v2
	v_lshrrev_b32_e32 v3, 22, v3
	v_add_u32_e32 v3, v2, v3
	v_ashrrev_i32_e32 v12, 10, v3
	v_mul_i32_i24_e32 v3, 0x400, v12
	v_sub_u32_e32 v2, v2, v3
	v_lshrrev_b32_e32 v3, 4, v2
	s_add_u32 s94, s8, s12
	v_bitop3_b32 v2, v3, v2, 32 bitop3:0x6c
	s_addc_u32 s95, s9, s13
	s_ashr_i32 s31, s30, 31
	v_lshl_add_u32 v210, v4, 12, v5
	v_ashrrev_i32_e32 v4, 31, v2
	s_lshl_b64 s[8:9], s[30:31], 20
	v_lshrrev_b32_e32 v4, 26, v4
	s_add_u32 s12, s65, s8
	v_add_u32_e32 v4, v2, v4
	s_addc_u32 s13, s66, s9
	s_ashr_i32 s8, s7, 6
	v_lshlrev_b32_e32 v3, 3, v12
	v_ashrrev_i32_e32 v13, 6, v4
	v_and_b32_e32 v4, 0xc0, v4
	s_ashr_i32 s9, s7, 8
	v_and_b32_e32 v3, -16, v3
	v_sub_u32_e32 v2, v2, v4
	s_lshl_b32 s67, s8, 10
	v_add_u32_e32 v3, v13, v3
	v_ashrrev_i16_sdwa v2, v226, sext(v2) dst_sel:DWORD dst_unused:UNUSED_PAD src0_sel:DWORD src1_sel:BYTE_0
	s_add_u32 s96, s12, s0
	v_lshlrev_b32_e32 v5, 5, v12
	v_bfe_i32 v14, v2, 0, 16
	v_lshlrev_b32_e32 v2, 1, v3
	v_lshrrev_b32_e32 v4, 2, v3
	v_and_b32_e32 v6, 3, v13
	s_addc_u32 s97, s13, s1
	s_add_i32 s68, s67, 0
	v_and_b32_e32 v5, 32, v5
	v_and_b32_e32 v2, 24, v2
	v_and_b32_e32 v4, 4, v4
	v_and_or_b32 v6, v3, s14, v6
	s_add_i32 m0, s68, 0x10000
	v_or3_b32 v2, v6, v4, v2
	v_add_lshl_u32 v4, v5, v14, 1
	global_load_lds_dwordx4 v212, s[96:97]
	s_add_i32 m0, s68, 0x12000
	v_lshl_add_u32 v216, v2, 12, v4
	s_add_u32 s0, s96, 0x80000
	global_load_lds_dwordx4 v216, s[96:97]
	s_addc_u32 s1, s97, 0
	s_add_i32 m0, s68, 0x14000
	s_add_i32 s69, s68, 0x2000
	global_load_lds_dwordx4 v212, s[0:1]
	s_add_i32 m0, s68, 0x16000
	v_lshl_add_u32 v214, v3, 12, v4
	global_load_lds_dwordx4 v216, s[0:1]
	s_mov_b32 m0, s68
	s_add_u32 s0, s94, 0x80000
	global_load_lds_dwordx4 v210, s[94:95]
	s_mov_b32 m0, s69
	s_addc_u32 s1, s95, 0
	s_add_i32 s70, s68, 0x4000
	global_load_lds_dwordx4 v214, s[94:95]
	s_mov_b32 m0, s70
	s_add_i32 s71, s68, 0x6000
	global_load_lds_dwordx4 v210, s[0:1]
	s_mov_b32 m0, s71
	v_mov_b32_e32 v213, v1
	global_load_lds_dwordx4 v214, s[0:1]
	v_mov_b32_e32 v217, v1
	v_mov_b32_e32 v211, v1
	v_mov_b32_e32 v215, v1
	s_cmp_eq_u32 s9, 1
	v_writelane_b32 v248, s16, 5
	s_mov_b32 s81, s56
	v_lshl_add_u64 v[8:9], s[96:97], 0, v[212:213]
	v_lshl_add_u64 v[6:7], s[96:97], 0, v[216:217]
	v_lshl_add_u64 v[2:3], s[94:95], 0, v[210:211]
	s_cselect_b64 s[12:13], -1, 0
	s_cmp_lg_u32 s9, 1
	v_lshl_add_u64 v[4:5], s[94:95], 0, v[214:215]
	v_writelane_b32 v248, s17, 6
	s_cbranch_scc1 .LBB0_244
	s_setprio 1
	s_barrier

; #define PG8_STAGE(bufoff, gbase, voff) do { _Pragma("unroll") for (int _i = 0; _i < 2; ++_i) \
;         __builtin_amdgcn_global_load_lds((const unsigned*)((const char*)(gbase) + (voff)[_i]), (LAS unsigned*)(lds + (bufoff) + ldsw + _i * 8192), 16, 0, 0); } while (0)
; #define PG8_LDA(dst, b, h) do { _Pragma("unroll") for (int m = 0; m < 4; ++m) _Pragma("unroll") for (int k = 0; k < 2; ++k) dst[m][k] = *(const LAS bf16x8*)(lds + PG8_SA(b, h) + aoff + m * 2048 + k * 1024); } while (0)
; #define PG8_LDB(dst, b, h) do { _Pragma("unroll") for (int n = 0; n < 2; ++n) _Pragma("unroll") for (int k = 0; k < 2; ++k) dst[n][k] = *(const LAS bf16x8*)(lds + PG8_SB(b, h) + boff + n * 2048 + k * 1024); } while (0)
; #define PG8_MMA(ai, bj, At, Bt) do { __builtin_amdgcn_s_setprio(1); _Pragma("unroll") for (int m = 0; m < 4; ++m) _Pragma("unroll") for (int n = 0; n < 2; ++n) _Pragma("unroll") for (int k = 0; k < 2; ++k) \
;         acc[ai][bj][m][n] = __builtin_amdgcn_mfma_f32_16x16x32_bf16(Bt[n][k], At[m][k], acc[ai][bj][m][n], 0, 0, 0); __builtin_amdgcn_s_setprio(0); } while (0)
; #define PG8_WAIT_V(n) asm volatile("s_waitcnt vmcnt(" #n ")" ::: "memory")
; #define PG8_WAIT_L(n) asm volatile("s_waitcnt lgkmcnt(" #n ")" ::: "memory")
; #define PG8_BAR __builtin_amdgcn_s_barrier()
; #define PG8_SCHED __builtin_amdgcn_sched_barrier(0)
; template <class Epi, bool ALIGN_EPI>
; __device__ __forceinline__ void gemm_phase(LAS unsigned char* lds, const int tid, const Gemm g, const StaticOrder& S, const Epi& E) {
;     ...
;             const bool last = (t == nt - 2);
;             const char* a1 = cA + (size_t)(t + 1) * kstepA;
;             const char* a2 = last ? nA : cA + (size_t)(t + 2) * kstepA; const char* b2 = last ? nB : cB + (size_t)(t + 2) * kstepB;
;             const char* a3 = a2 + kstepA; const char* b3 = b2 + kstepB;
;             PG8_LDB(B0, 0, 0); PG8_LDB(B1, 0, 1); PG8_SCHED; PG8_LDA(At, 0, 0); PG8_STAGE(PG8_SA(1, 1), a1 + hstepA, voffA);
;             PG8_WAIT_V(8); PG8_WAIT_L(0); PG8_BAR; PG8_MMA(0, 0, At, B0); PG8_MMA(0, 1, At, B1); PG8_BAR; PG8_SCHED;
;             PG8_LDA(At, 0, 1); PG8_STAGE(PG8_SB(0, 0), b2, voffB); PG8_STAGE(PG8_SB(0, 1), b2 + hstepB, voffB); PG8_STAGE(PG8_SA(0, 0), a2, voffA);
;             PG8_WAIT_V(8); PG8_WAIT_L(0); PG8_BAR; PG8_MMA(1, 0, At, B0); PG8_MMA(1, 1, At, B1); PG8_BAR; PG8_SCHED;
.LBB0_263:
	s_add_i32 s5, s5, 2
	s_add_u32 s34, s30, 0xfff80080
	s_addc_u32 s35, s31, -1
	s_add_i32 s94, 0, 0x10000
	s_cmp_eq_u32 s91, s92
	s_cselect_b32 s55, s23, s35
	s_cselect_b32 s54, s22, s34
	v_add_u32_e32 v0, s94, v205
	s_cselect_b32 s35, s25, s36
	s_cselect_b32 s34, s24, s21
	s_add_i32 s96, 0, 0x14000
	ds_read_b128 v[132:135], v0
	ds_read_b128 v[136:139], v0 offset:1024
	ds_read_b128 v[140:143], v0 offset:2048
	ds_read_b128 v[144:147], v0 offset:3072
	v_add_u32_e32 v0, s96, v205
	ds_read_b128 v[148:151], v0
	ds_read_b128 v[152:155], v0 offset:1024
	ds_read_b128 v[156:159], v0 offset:2048
	ds_read_b128 v[160:163], v0 offset:3072
	v_lshl_add_u64 v[2:3], s[30:31], 0, v[220:221]
	s_add_i32 m0, s68, 0xc000
	ds_read_b128 v[164:167], v209
	ds_read_b128 v[168:171], v209 offset:1024
	ds_read_b128 v[172:175], v209 offset:2048
	ds_read_b128 v[176:179], v209 offset:3072
	ds_read_b128 v[180:183], v209 offset:4096
	ds_read_b128 v[184:187], v209 offset:5120
	ds_read_b128 v[188:191], v209 offset:6144
	ds_read_b128 v[192:195], v209 offset:7168
	global_load_lds_dwordx4 v[2:3], off
	v_lshl_add_u64 v[2:3], s[30:31], 0, v[218:219]
	s_add_i32 m0, s68, 0xe000
	s_nop 0
	global_load_lds_dwordx4 v[2:3], off
	s_sub_u32 s98, s30, 0x80000
	s_subb_u32 s99, s31, 0
	v_lshl_add_u64 v[2:3], s[98:99], 0, v[220:221]
	s_mov_b32 m0, s72
	s_nop 0
	global_load_lds_dwordx4 v[2:3], off
	v_lshl_add_u64 v[2:3], s[98:99], 0, v[218:219]
	s_mov_b32 m0, s73
	s_nop 0
	global_load_lds_dwordx4 v[2:3], off
	s_waitcnt vmcnt(8)
	s_waitcnt lgkmcnt(0)
	s_barrier
	s_waitcnt lgkmcnt(0)
	v_mfma_f32_16x16x32_bf16 v[128:131], v[132:135], v[164:167], v[128:131]
	v_mfma_f32_16x16x32_bf16 v[124:127], v[140:143], v[164:167], v[124:127]
	v_mfma_f32_16x16x32_bf16 v[112:115], v[132:135], v[172:175], v[112:115]
	v_mfma_f32_16x16x32_bf16 v[108:111], v[140:143], v[172:175], v[108:111]
	v_mfma_f32_16x16x32_bf16 v[96:99], v[132:135], v[180:183], v[96:99]
	v_mfma_f32_16x16x32_bf16 v[92:95], v[140:143], v[180:183], v[92:95]
	v_mfma_f32_16x16x32_bf16 v[80:83], v[132:135], v[188:191], v[80:83]
	v_mfma_f32_16x16x32_bf16 v[76:79], v[140:143], v[188:191], v[76:79]
	v_mfma_f32_16x16x32_bf16 v[128:131], v[136:139], v[168:171], v[128:131]
	v_mfma_f32_16x16x32_bf16 v[124:127], v[144:147], v[168:171], v[124:127]
	v_mfma_f32_16x16x32_bf16 v[112:115], v[136:139], v[176:179], v[112:115]
	v_mfma_f32_16x16x32_bf16 v[108:111], v[144:147], v[176:179], v[108:111]
	v_mfma_f32_16x16x32_bf16 v[96:99], v[136:139], v[184:187], v[96:99]
	v_mfma_f32_16x16x32_bf16 v[92:95], v[144:147], v[184:187], v[92:95]
	v_mfma_f32_16x16x32_bf16 v[80:83], v[136:139], v[192:195], v[80:83]
	v_mfma_f32_16x16x32_bf16 v[76:79], v[144:147], v[192:195], v[76:79]
	v_mfma_f32_16x16x32_bf16 v[120:123], v[148:151], v[164:167], v[120:123]
	v_mfma_f32_16x16x32_bf16 v[116:119], v[156:159], v[164:167], v[116:119]
	v_mfma_f32_16x16x32_bf16 v[104:107], v[148:151], v[172:175], v[104:107]
	v_mfma_f32_16x16x32_bf16 v[100:103], v[156:159], v[172:175], v[100:103]
	v_mfma_f32_16x16x32_bf16 v[88:91], v[148:151], v[180:183], v[88:91]
	v_mfma_f32_16x16x32_bf16 v[84:87], v[156:159], v[180:183], v[84:87]
	v_mfma_f32_16x16x32_bf16 v[72:75], v[148:151], v[188:191], v[72:75]
	v_mfma_f32_16x16x32_bf16 v[68:71], v[156:159], v[188:191], v[68:71]
	v_mfma_f32_16x16x32_bf16 v[120:123], v[152:155], v[168:171], v[120:123]
	v_mfma_f32_16x16x32_bf16 v[116:119], v[160:163], v[168:171], v[116:119]
	v_mfma_f32_16x16x32_bf16 v[104:107], v[152:155], v[176:179], v[104:107]
	v_mfma_f32_16x16x32_bf16 v[100:103], v[160:163], v[176:179], v[100:103]
	v_mfma_f32_16x16x32_bf16 v[88:91], v[152:155], v[184:187], v[88:91]
	v_mfma_f32_16x16x32_bf16 v[84:87], v[160:163], v[184:187], v[84:87]
	v_mfma_f32_16x16x32_bf16 v[72:75], v[152:155], v[192:195], v[72:75]
	v_mfma_f32_16x16x32_bf16 v[68:71], v[160:163], v[192:195], v[68:71]
	s_barrier
	s_add_i32 s94, s94, s67
	v_lshl_add_u64 v[240:241], s[34:35], 0, v[212:213]
	s_mov_b32 m0, s94
	ds_read_b128 v[164:167], v209 offset:16384
	ds_read_b128 v[168:171], v209 offset:17408
	ds_read_b128 v[172:175], v209 offset:18432
	ds_read_b128 v[176:179], v209 offset:19456
	ds_read_b128 v[180:183], v209 offset:20480
	ds_read_b128 v[184:187], v209 offset:21504
	ds_read_b128 v[188:191], v209 offset:22528
	ds_read_b128 v[192:195], v209 offset:23552
	global_load_lds_dwordx4 v[240:241], off
	s_add_i32 m0, s94, 0x2000
	s_add_u32 s94, s34, 0x80000
	v_lshl_add_u64 v[242:243], s[34:35], 0, v[216:217]
	s_addc_u32 s95, s35, 0
	s_add_i32 s96, s96, s67
	global_load_lds_dwordx4 v[242:243], off
	v_lshl_add_u64 v[2:3], s[94:95], 0, v[212:213]
	s_mov_b32 m0, s96
	v_lshl_add_u64 v[244:245], s[54:55], 0, v[210:211]
	global_load_lds_dwordx4 v[2:3], off
	v_lshl_add_u64 v[2:3], s[94:95], 0, v[216:217]
	s_add_i32 m0, s96, 0x2000
	v_lshl_add_u64 v[246:247], s[54:55], 0, v[214:215]
	global_load_lds_dwordx4 v[2:3], off
	s_waitcnt vmcnt(4)
	s_waitcnt lgkmcnt(0)
	s_barrier
; #define PG8_STAGE(bufoff, gbase, voff) do { _Pragma("unroll") for (int _i = 0; _i < 2; ++_i) \
;         __builtin_amdgcn_global_load_lds((const unsigned*)((const char*)(gbase) + (voff)[_i]), (LAS unsigned*)(lds + (bufoff) + ldsw + _i * 8192), 16, 0, 0); } while (0)
; #define PG8_LDA(dst, b, h) do { _Pragma("unroll") for (int m = 0; m < 4; ++m) _Pragma("unroll") for (int k = 0; k < 2; ++k) dst[m][k] = *(const LAS bf16x8*)(lds + PG8_SA(b, h) + aoff + m * 2048 + k * 1024); } while (0)
; #define PG8_LDB(dst, b, h) do { _Pragma("unroll") for (int n = 0; n < 2; ++n) _Pragma("unroll") for (int k = 0; k < 2; ++k) dst[n][k] = *(const LAS bf16x8*)(lds + PG8_SB(b, h) + boff + n * 2048 + k * 1024); } while (0)
; #define PG8_MMA(ai, bj, At, Bt) do { __builtin_amdgcn_s_setprio(1); _Pragma("unroll") for (int m = 0; m < 4; ++m) _Pragma("unroll") for (int n = 0; n < 2; ++n) _Pragma("unroll") for (int k = 0; k < 2; ++k) \
;         acc[ai][bj][m][n] = __builtin_amdgcn_mfma_f32_16x16x32_bf16(Bt[n][k], At[m][k], acc[ai][bj][m][n], 0, 0, 0); __builtin_amdgcn_s_setprio(0); } while (0)
; #define PG8_WAIT_V(n) asm volatile("s_waitcnt vmcnt(" #n ")" ::: "memory")
; #define PG8_WAIT_L(n) asm volatile("s_waitcnt lgkmcnt(" #n ")" ::: "memory")
; #define PG8_BAR __builtin_amdgcn_s_barrier()
; #define PG8_SCHED __builtin_amdgcn_sched_barrier(0)
; template <class Epi, bool ALIGN_EPI>
; __device__ __forceinline__ void gemm_phase(LAS unsigned char* lds, const int tid, const Gemm g, const StaticOrder& S, const Epi& E) {
;     ...
;             PG8_WAIT_V(8); PG8_WAIT_L(0); PG8_BAR; PG8_MMA(1, 0, At, B0); PG8_MMA(1, 1, At, B1); PG8_BAR; PG8_SCHED;
;             PG8_LDB(B0, 1, 0); PG8_LDB(B1, 1, 1); PG8_SCHED; PG8_LDA(At, 1, 0); PG8_STAGE(PG8_SA(0, 1), a2 + hstepA, voffA);
;             PG8_WAIT_V(8); PG8_WAIT_L(0); PG8_BAR; PG8_MMA(0, 0, At, B0); PG8_MMA(0, 1, At, B1); PG8_BAR; PG8_SCHED;
	s_waitcnt lgkmcnt(0)
	v_mfma_f32_16x16x32_bf16 v[64:67], v[132:135], v[164:167], v[64:67]
	v_mfma_f32_16x16x32_bf16 v[60:63], v[140:143], v[164:167], v[60:63]
	v_mfma_f32_16x16x32_bf16 v[48:51], v[132:135], v[172:175], v[48:51]
	v_mfma_f32_16x16x32_bf16 v[44:47], v[140:143], v[172:175], v[44:47]
	v_mfma_f32_16x16x32_bf16 v[32:35], v[132:135], v[180:183], v[32:35]
	v_mfma_f32_16x16x32_bf16 v[28:31], v[140:143], v[180:183], v[28:31]
	v_mfma_f32_16x16x32_bf16 v[16:19], v[132:135], v[188:191], v[16:19]
	v_mfma_f32_16x16x32_bf16 v[12:15], v[140:143], v[188:191], v[12:15]
	v_mfma_f32_16x16x32_bf16 v[64:67], v[136:139], v[168:171], v[64:67]
	v_mfma_f32_16x16x32_bf16 v[60:63], v[144:147], v[168:171], v[60:63]
	v_mfma_f32_16x16x32_bf16 v[48:51], v[136:139], v[176:179], v[48:51]
	v_mfma_f32_16x16x32_bf16 v[44:47], v[144:147], v[176:179], v[44:47]
	v_mfma_f32_16x16x32_bf16 v[32:35], v[136:139], v[184:187], v[32:35]
	v_mfma_f32_16x16x32_bf16 v[28:31], v[144:147], v[184:187], v[28:31]
	v_mfma_f32_16x16x32_bf16 v[16:19], v[136:139], v[192:195], v[16:19]
	v_mfma_f32_16x16x32_bf16 v[12:15], v[144:147], v[192:195], v[12:15]
	v_mfma_f32_16x16x32_bf16 v[56:59], v[148:151], v[164:167], v[56:59]
	v_mfma_f32_16x16x32_bf16 v[52:55], v[156:159], v[164:167], v[52:55]
	v_mfma_f32_16x16x32_bf16 v[40:43], v[148:151], v[172:175], v[40:43]
	v_mfma_f32_16x16x32_bf16 v[36:39], v[156:159], v[172:175], v[36:39]
	v_mfma_f32_16x16x32_bf16 v[24:27], v[148:151], v[180:183], v[24:27]
	v_mfma_f32_16x16x32_bf16 v[20:23], v[156:159], v[180:183], v[20:23]
	v_mfma_f32_16x16x32_bf16 v[8:11], v[148:151], v[188:191], v[8:11]
	v_mfma_f32_16x16x32_bf16 v[2:5], v[156:159], v[188:191], v[4:7]
	v_mfma_f32_16x16x32_bf16 v[56:59], v[152:155], v[168:171], v[56:59]
	v_mfma_f32_16x16x32_bf16 v[52:55], v[160:163], v[168:171], v[52:55]
	v_mfma_f32_16x16x32_bf16 v[40:43], v[152:155], v[176:179], v[40:43]
	v_mfma_f32_16x16x32_bf16 v[36:39], v[160:163], v[176:179], v[36:39]
	v_mfma_f32_16x16x32_bf16 v[24:27], v[152:155], v[184:187], v[24:27]
	v_mfma_f32_16x16x32_bf16 v[20:23], v[160:163], v[184:187], v[20:23]
	v_mfma_f32_16x16x32_bf16 v[8:11], v[152:155], v[192:195], v[8:11]
	v_mfma_f32_16x16x32_bf16 v[2:5], v[160:163], v[192:195], v[2:5]
	s_barrier
	s_add_i32 s94, 0, 0x18000
	v_add_u32_e32 v0, s94, v205
	s_add_i32 s95, 0, 0x1c000
	ds_read_b128 v[132:135], v0
	ds_read_b128 v[136:139], v0 offset:1024
	ds_read_b128 v[140:143], v0 offset:2048
	ds_read_b128 v[144:147], v0 offset:3072
	v_add_u32_e32 v0, s95, v205
	ds_read_b128 v[148:151], v0
	ds_read_b128 v[152:155], v0 offset:1024
	ds_read_b128 v[156:159], v0 offset:2048
	ds_read_b128 v[160:163], v0 offset:3072
	s_mov_b32 m0, s68
	s_nop 0
	global_load_lds_dwordx4 v[244:245], off
	s_mov_b32 m0, s69
	s_nop 0
	global_load_lds_dwordx4 v[246:247], off
	s_add_u32 s54, s54, 0x80000
	s_addc_u32 s55, s55, 0
	s_mov_b32 m0, s70
	v_lshl_add_u64 v[6:7], s[54:55], 0, v[210:211]
	ds_read_b128 v[164:167], v209 offset:32768
	ds_read_b128 v[168:171], v209 offset:33792
	ds_read_b128 v[172:175], v209 offset:34816
	ds_read_b128 v[176:179], v209 offset:35840
	ds_read_b128 v[180:183], v209 offset:36864
	ds_read_b128 v[184:187], v209 offset:37888
	ds_read_b128 v[188:191], v209 offset:38912
	ds_read_b128 v[192:195], v209 offset:39936
	global_load_lds_dwordx4 v[6:7], off
	v_lshl_add_u64 v[6:7], s[54:55], 0, v[214:215]
	s_mov_b32 m0, s71
	s_nop 0
	global_load_lds_dwordx4 v[6:7], off
	s_waitcnt vmcnt(8)
	s_waitcnt lgkmcnt(0)
	s_barrier
; #define PG8_STAGE(bufoff, gbase, voff) do { _Pragma("unroll") for (int _i = 0; _i < 2; ++_i) \
;         __builtin_amdgcn_global_load_lds((const unsigned*)((const char*)(gbase) + (voff)[_i]), (LAS unsigned*)(lds + (bufoff) + ldsw + _i * 8192), 16, 0, 0); } while (0)
; #define PG8_LDA(dst, b, h) do { _Pragma("unroll") for (int m = 0; m < 4; ++m) _Pragma("unroll") for (int k = 0; k < 2; ++k) dst[m][k] = *(const LAS bf16x8*)(lds + PG8_SA(b, h) + aoff + m * 2048 + k * 1024); } while (0)
; #define PG8_LDB(dst, b, h) do { _Pragma("unroll") for (int n = 0; n < 2; ++n) _Pragma("unroll") for (int k = 0; k < 2; ++k) dst[n][k] = *(const LAS bf16x8*)(lds + PG8_SB(b, h) + boff + n * 2048 + k * 1024); } while (0)
; #define PG8_MMA(ai, bj, At, Bt) do { __builtin_amdgcn_s_setprio(1); _Pragma("unroll") for (int m = 0; m < 4; ++m) _Pragma("unroll") for (int n = 0; n < 2; ++n) _Pragma("unroll") for (int k = 0; k < 2; ++k) \
;         acc[ai][bj][m][n] = __builtin_amdgcn_mfma_f32_16x16x32_bf16(Bt[n][k], At[m][k], acc[ai][bj][m][n], 0, 0, 0); __builtin_amdgcn_s_setprio(0); } while (0)
; #define PG8_WAIT_V(n) asm volatile("s_waitcnt vmcnt(" #n ")" ::: "memory")
; #define PG8_WAIT_L(n) asm volatile("s_waitcnt lgkmcnt(" #n ")" ::: "memory")
; #define PG8_BAR __builtin_amdgcn_s_barrier()
; #define PG8_SCHED __builtin_amdgcn_sched_barrier(0)
; template <class Epi, bool ALIGN_EPI>
; __device__ __forceinline__ void gemm_phase(LAS unsigned char* lds, const int tid, const Gemm g, const StaticOrder& S, const Epi& E) {
;     ...
;             PG8_WAIT_V(8); PG8_WAIT_L(0); PG8_BAR; PG8_MMA(1, 0, At, B0); PG8_MMA(1, 1, At, B1); PG8_BAR; PG8_SCHED;
;             PG8_LDB(B0, 1, 0); PG8_LDB(B1, 1, 1); PG8_SCHED; PG8_LDA(At, 1, 0); PG8_STAGE(PG8_SA(0, 1), a2 + hstepA, voffA);
;             PG8_WAIT_V(8); PG8_WAIT_L(0); PG8_BAR; PG8_MMA(0, 0, At, B0); PG8_MMA(0, 1, At, B1); PG8_BAR; PG8_SCHED;
;             PG8_LDA(At, 1, 1); PG8_STAGE(PG8_SB(1, 0), b3, voffB); PG8_STAGE(PG8_SB(1, 1), b3 + hstepB, voffB); PG8_STAGE(PG8_SA(1, 0), a3, voffA);
;             PG8_WAIT_V(8); PG8_WAIT_L(0); PG8_BAR; PG8_MMA(1, 0, At, B0); PG8_MMA(1, 1, At, B1); PG8_BAR; PG8_SCHED;
;         }
	s_waitcnt lgkmcnt(0)
	v_mfma_f32_16x16x32_bf16 v[128:131], v[132:135], v[164:167], v[128:131]
	v_mfma_f32_16x16x32_bf16 v[124:127], v[140:143], v[164:167], v[124:127]
	v_mfma_f32_16x16x32_bf16 v[112:115], v[132:135], v[172:175], v[112:115]
	v_mfma_f32_16x16x32_bf16 v[108:111], v[140:143], v[172:175], v[108:111]
	v_mfma_f32_16x16x32_bf16 v[96:99], v[132:135], v[180:183], v[96:99]
	v_mfma_f32_16x16x32_bf16 v[92:95], v[140:143], v[180:183], v[92:95]
	v_mfma_f32_16x16x32_bf16 v[80:83], v[132:135], v[188:191], v[80:83]
	v_mfma_f32_16x16x32_bf16 v[76:79], v[140:143], v[188:191], v[76:79]
	v_mfma_f32_16x16x32_bf16 v[128:131], v[136:139], v[168:171], v[128:131]
	v_mfma_f32_16x16x32_bf16 v[124:127], v[144:147], v[168:171], v[124:127]
	v_mfma_f32_16x16x32_bf16 v[112:115], v[136:139], v[176:179], v[112:115]
	v_mfma_f32_16x16x32_bf16 v[108:111], v[144:147], v[176:179], v[108:111]
	v_mfma_f32_16x16x32_bf16 v[96:99], v[136:139], v[184:187], v[96:99]
	v_mfma_f32_16x16x32_bf16 v[92:95], v[144:147], v[184:187], v[92:95]
	v_mfma_f32_16x16x32_bf16 v[80:83], v[136:139], v[192:195], v[80:83]
	v_mfma_f32_16x16x32_bf16 v[76:79], v[144:147], v[192:195], v[76:79]
	v_mfma_f32_16x16x32_bf16 v[120:123], v[148:151], v[164:167], v[120:123]
	v_mfma_f32_16x16x32_bf16 v[116:119], v[156:159], v[164:167], v[116:119]
	v_mfma_f32_16x16x32_bf16 v[104:107], v[148:151], v[172:175], v[104:107]
	v_mfma_f32_16x16x32_bf16 v[100:103], v[156:159], v[172:175], v[100:103]
	v_mfma_f32_16x16x32_bf16 v[88:91], v[148:151], v[180:183], v[88:91]
	v_mfma_f32_16x16x32_bf16 v[84:87], v[156:159], v[180:183], v[84:87]
	v_mfma_f32_16x16x32_bf16 v[72:75], v[148:151], v[188:191], v[72:75]
	v_mfma_f32_16x16x32_bf16 v[68:71], v[156:159], v[188:191], v[68:71]
	v_mfma_f32_16x16x32_bf16 v[120:123], v[152:155], v[168:171], v[120:123]
	v_mfma_f32_16x16x32_bf16 v[116:119], v[160:163], v[168:171], v[116:119]
	v_mfma_f32_16x16x32_bf16 v[104:107], v[152:155], v[176:179], v[104:107]
	v_mfma_f32_16x16x32_bf16 v[100:103], v[160:163], v[176:179], v[100:103]
	v_mfma_f32_16x16x32_bf16 v[88:91], v[152:155], v[184:187], v[88:91]
	v_mfma_f32_16x16x32_bf16 v[84:87], v[160:163], v[184:187], v[84:87]
	v_mfma_f32_16x16x32_bf16 v[72:75], v[152:155], v[192:195], v[72:75]
	v_mfma_f32_16x16x32_bf16 v[68:71], v[160:163], v[192:195], v[68:71]
	s_barrier
	s_add_i32 s54, s94, s67
	v_lshl_add_u64 v[6:7], v[240:241], 0, s[42:43]
	s_mov_b32 m0, s54
	ds_read_b128 v[164:167], v209 offset:49152
	ds_read_b128 v[168:171], v209 offset:50176
	ds_read_b128 v[172:175], v209 offset:51200
	ds_read_b128 v[176:179], v209 offset:52224
	ds_read_b128 v[180:183], v209 offset:53248
	ds_read_b128 v[184:187], v209 offset:54272
	ds_read_b128 v[188:191], v209 offset:55296
	ds_read_b128 v[192:195], v209 offset:56320
	global_load_lds_dwordx4 v[6:7], off
	s_add_i32 m0, s54, 0x2000
	s_add_u32 s34, s34, 0x80080
	v_lshl_add_u64 v[6:7], v[242:243], 0, s[42:43]
	s_addc_u32 s35, s35, 0
	s_add_i32 s54, s95, s67
	global_load_lds_dwordx4 v[6:7], off
	v_lshl_add_u64 v[6:7], s[34:35], 0, v[212:213]
	s_mov_b32 m0, s54
	s_nop 0
	global_load_lds_dwordx4 v[6:7], off
	v_lshl_add_u64 v[6:7], s[34:35], 0, v[216:217]
	s_add_i32 m0, s54, 0x2000
	s_nop 0
	global_load_lds_dwordx4 v[6:7], off
	s_waitcnt vmcnt(4)
	s_waitcnt lgkmcnt(0)
	s_barrier
	s_waitcnt lgkmcnt(0)
	v_mfma_f32_16x16x32_bf16 v[64:67], v[132:135], v[164:167], v[64:67]
	v_mfma_f32_16x16x32_bf16 v[60:63], v[140:143], v[164:167], v[60:63]
	v_mfma_f32_16x16x32_bf16 v[48:51], v[132:135], v[172:175], v[48:51]
	v_mfma_f32_16x16x32_bf16 v[44:47], v[140:143], v[172:175], v[44:47]
	v_mfma_f32_16x16x32_bf16 v[32:35], v[132:135], v[180:183], v[32:35]
	v_mfma_f32_16x16x32_bf16 v[28:31], v[140:143], v[180:183], v[28:31]
	v_mfma_f32_16x16x32_bf16 v[16:19], v[132:135], v[188:191], v[16:19]
	v_mfma_f32_16x16x32_bf16 v[12:15], v[140:143], v[188:191], v[12:15]
	v_mfma_f32_16x16x32_bf16 v[64:67], v[136:139], v[168:171], v[64:67]
	v_mfma_f32_16x16x32_bf16 v[60:63], v[144:147], v[168:171], v[60:63]
	v_mfma_f32_16x16x32_bf16 v[48:51], v[136:139], v[176:179], v[48:51]
	v_mfma_f32_16x16x32_bf16 v[44:47], v[144:147], v[176:179], v[44:47]
	v_mfma_f32_16x16x32_bf16 v[32:35], v[136:139], v[184:187], v[32:35]
	v_mfma_f32_16x16x32_bf16 v[28:31], v[144:147], v[184:187], v[28:31]
	v_mfma_f32_16x16x32_bf16 v[16:19], v[136:139], v[192:195], v[16:19]
	v_mfma_f32_16x16x32_bf16 v[12:15], v[144:147], v[192:195], v[12:15]
	v_mfma_f32_16x16x32_bf16 v[56:59], v[148:151], v[164:167], v[56:59]
	v_mfma_f32_16x16x32_bf16 v[52:55], v[156:159], v[164:167], v[52:55]
	v_mfma_f32_16x16x32_bf16 v[40:43], v[148:151], v[172:175], v[40:43]
	v_mfma_f32_16x16x32_bf16 v[36:39], v[156:159], v[172:175], v[36:39]
	v_mfma_f32_16x16x32_bf16 v[24:27], v[148:151], v[180:183], v[24:27]
	v_mfma_f32_16x16x32_bf16 v[20:23], v[156:159], v[180:183], v[20:23]
	v_mfma_f32_16x16x32_bf16 v[6:9], v[148:151], v[188:191], v[8:11]
	v_mfma_f32_16x16x32_bf16 v[2:5], v[156:159], v[188:191], v[2:5]
	v_mfma_f32_16x16x32_bf16 v[56:59], v[152:155], v[168:171], v[56:59]
	v_mfma_f32_16x16x32_bf16 v[52:55], v[160:163], v[168:171], v[52:55]
	v_mfma_f32_16x16x32_bf16 v[40:43], v[152:155], v[176:179], v[40:43]
	v_mfma_f32_16x16x32_bf16 v[36:39], v[160:163], v[176:179], v[36:39]
	v_mfma_f32_16x16x32_bf16 v[24:27], v[152:155], v[184:187], v[24:27]
	v_mfma_f32_16x16x32_bf16 v[20:23], v[160:163], v[184:187], v[20:23]
	v_mfma_f32_16x16x32_bf16 v[8:11], v[152:155], v[192:195], v[6:9]
	v_mfma_f32_16x16x32_bf16 v[4:7], v[160:163], v[192:195], v[2:5]
	s_barrier
	s_add_u32 s92, s92, 0x400
	s_addc_u32 s93, s93, 0
	s_add_u32 s21, s21, 0x100
	s_addc_u32 s36, s36, 0
	s_add_u32 s30, s30, 0x100
	s_addc_u32 s31, s31, 0
	s_cmp_ge_u32 s5, s19
	s_cbranch_scc1 .LBB0_266

; #define PG8_BAR __builtin_amdgcn_s_barrier()
;     __device__ bool next(int i, Unit& u) const {
;         const long L = (long)i * G + c;
;         if (L >= nwg) { const long j = L - nwg; if (j >= (long)nM2 * nN * nsplit) return false;
;             const int jj = (int)j; u.ks = jj % nsplit; const int tl = jj / nsplit; u.pn = tl % nN; u.pm = nM + tl / nN; return true; }
;         u.ks = -1;
;         int wgid = (int)L; { const int q = nwg / NXCD, r = nwg % NXCD, xcd = wgid % NXCD, off = wgid / NXCD; wgid = (xcd < r ? xcd * (q + 1) : r * (q + 1) + (xcd - r) * q) + off; }
;         const int nig = WGM * nN, gid = wgid / nig, fm = gid * WGM, gsz = (nM - fm) < WGM ? (nM - fm) : WGM;
;         u.pm = fm + ((wgid % nig) % gsz); u.pn = (wgid % nig) / gsz; return true;
; template <class Epi, bool ALIGN_EPI>
; __device__ __forceinline__ void gemm_phase(LAS unsigned char* lds, const int tid, const Gemm g, const StaticOrder& S, const Epi& E) {
;     ...
;     for (int i = 0; i < 2; ++i) { int R, C; stage_rc(tid * 16 + i * 8192, R, C); const int Rb = Epi::PERM ? ((R & ~31) + perm32(R & 31)) : R;
;         voffA[i] = (unsigned)R * rsA + (unsigned)C * 2u; voffB[i] = (unsigned)Rb * rsB + (unsigned)C * 2u; }
;     const size_t hstepA = (size_t)HALF * rsA, hstepB = (size_t)HALF * rsB;
;     const size_t tstepA = 2 * hstepA, tstepB = 2 * hstepB;
;     const unsigned ldsw = (unsigned)wid * 1024u;
;     const int aoff = lds_byte(wr * 64 + fr, fq * 8), boff = lds_byte(wc * 32 + fr, fq * 8);
;     ...
;     Unit cur, nxt; int ui = 0;
;     if (!S.next(0, cur)) return;
;     f32x4 acc[2][2][4][2];
; #pragma unroll
;     for (int a = 0; a < 2; ++a)
; #pragma unroll
;         for (int b = 0; b < 2; ++b)
; #pragma unroll
;             for (int m = 0; m < 4; ++m)
; #pragma unroll
;                 for (int n = 0; n < 2; ++n) acc[a][b][m][n] = (f32x4){0.f, 0.f, 0.f, 0.f};
;     bf16x8 At[4][2], B0[2][2], B1[2][2];
;     ...
;     const char* cA = (const char*)g.A + (size_t)cur.pm * tstepA + PG8_KOFFA(cur); const char* cB = (const char*)g.Bt + (size_t)cur.pn * tstepB + PG8_KOFFB(cur);
;     PG8_STAGE(PG8_SB(0, 0), cB, voffB); PG8_STAGE(PG8_SB(0, 1), cB + hstepB, voffB); PG8_STAGE(PG8_SA(0, 0), cA, voffA); PG8_STAGE(PG8_SA(0, 1), cA + hstepA, voffA);
;     if (wr == 1) PG8_BAR;
.LBB0_655:
	v_bfe_i32 v3, v208, 27, 1
	v_lshlrev_b32_e32 v2, 4, v208
	v_lshrrev_b32_e32 v3, 22, v3
	v_add_u32_e32 v3, v2, v3
	v_and_b32_e32 v3, 0xfffffc00, v3
	v_sub_u32_e32 v3, v2, v3
	v_lshrrev_b32_e32 v4, 4, v3
	v_ashrrev_i32_e32 v0, 31, v208
	v_bitop3_b32 v3, v4, v3, 32 bitop3:0x6c
	v_lshrrev_b32_e32 v0, 26, v0
	v_ashrrev_i32_e32 v5, 31, v3
	v_add_u32_e32 v0, v208, v0
	v_lshrrev_b32_e32 v5, 26, v5
	v_ashrrev_i32_e32 v0, 6, v0
	v_add_u32_e32 v5, v3, v5
	v_lshlrev_b32_e32 v4, 3, v0
	v_ashrrev_i32_e32 v10, 6, v5
	v_and_b32_e32 v5, 0xc0, v5
	v_and_b32_e32 v4, -16, v4
	v_sub_u32_e32 v3, v3, v5
	v_add_u32_e32 v4, v10, v4
	v_ashrrev_i16_sdwa v3, v226, sext(v3) dst_sel:DWORD dst_unused:UNUSED_PAD src0_sel:DWORD src1_sel:BYTE_0
	s_ashr_i32 s0, s5, 3
	v_lshlrev_b32_e32 v6, 5, v0
	v_bfe_i32 v11, v3, 0, 16
	v_lshlrev_b32_e32 v3, 1, v4
	v_lshrrev_b32_e32 v5, 2, v4
	v_and_b32_e32 v7, 3, v10
	s_mov_b32 s5, 0xfffe0
	v_and_b32_e32 v6, 32, v6
	v_and_b32_e32 v3, 24, v3
	v_and_b32_e32 v5, 4, v5
	v_and_or_b32 v7, v4, s5, v7
	v_or3_b32 v3, v7, v5, v3
	v_add_lshl_u32 v5, v6, v11, 1
	v_add_u32_e32 v2, 0x2000, v2
	s_waitcnt vmcnt(0)
	v_lshl_add_u32 v148, v3, 12, v5
	v_ashrrev_i32_e32 v3, 31, v2
	v_lshrrev_b32_e32 v3, 22, v3
	v_add_u32_e32 v3, v2, v3
	v_ashrrev_i32_e32 v12, 10, v3
	v_mul_i32_i24_e32 v3, 0x400, v12
	v_sub_u32_e32 v2, v2, v3
	v_lshrrev_b32_e32 v3, 4, v2
	v_bitop3_b32 v2, v3, v2, 32 bitop3:0x6c
	v_lshl_add_u32 v146, v4, 12, v5
	v_ashrrev_i32_e32 v4, 31, v2
	v_lshrrev_b32_e32 v4, 26, v4
	v_lshlrev_b32_e32 v3, 3, v12
	v_add_u32_e32 v4, v2, v4
	v_and_b32_e32 v3, -16, v3
	v_ashrrev_i32_e32 v13, 6, v4
	s_add_i32 s0, s4, s0
	v_add_u32_e32 v3, v13, v3
	v_and_b32_e32 v4, 0xc0, v4
	v_and_b32_e32 v6, 3, v13
	s_mul_hi_i32 s4, s0, 0x5397829d
	v_sub_u32_e32 v2, v2, v4
	v_and_or_b32 v6, v3, s5, v6
	s_lshr_b32 s5, s4, 31
	s_ashr_i32 s4, s4, 7
	v_ashrrev_i16_sdwa v2, v226, sext(v2) dst_sel:DWORD dst_unused:UNUSED_PAD src0_sel:DWORD src1_sel:BYTE_0
	s_add_i32 s4, s4, s5
	v_lshlrev_b32_e32 v5, 5, v12
	v_bfe_i32 v14, v2, 0, 16
	v_lshlrev_b32_e32 v2, 1, v3
	v_lshrrev_b32_e32 v4, 2, v3
	s_lshl_b32 s10, s4, 3
	v_and_b32_e32 v5, 32, v5
	v_and_b32_e32 v2, 24, v2
	v_and_b32_e32 v4, 4, v4
	s_sub_i32 s5, 36, s10
	v_or3_b32 v2, v6, v4, v2
	v_add_lshl_u32 v4, v5, v14, 1
	s_min_u32 s11, s5, 8
	s_mulk_i32 s4, 0x188
	v_lshl_add_u32 v150, v3, 12, v4
	s_sub_i32 s12, s0, s4
	v_cvt_f32_ubyte0_e32 v3, s11
	v_lshl_add_u32 v152, v2, 12, v4
	v_cvt_f32_i32_e32 v2, s12
	v_rcp_iflag_f32_e32 v4, v3
	s_ashr_i32 s1, s8, 6
	s_ashr_i32 s0, s12, 30
	s_ashr_i32 s9, s8, 8
	v_mul_f32_e32 v4, v2, v4
	v_trunc_f32_e32 v4, v4
	v_fma_f32 v2, -v4, v3, v2
	v_cvt_i32_f32_e32 v4, v4
	s_lshl_b32 s27, s1, 10
	s_or_b32 s0, s0, 1
	v_cmp_ge_f32_e64 s[4:5], |v2|, v3
	s_and_b64 s[4:5], s[4:5], exec
	s_cselect_b32 s0, s0, 0
	v_readfirstlane_b32 s4, v4
	s_add_i32 s0, s4, s0
	s_mul_i32 s4, s0, s11
	s_sub_i32 s4, s12, s4
	s_sext_i32_i16 s4, s4
	s_add_i32 s18, s10, s4
	s_ashr_i32 s19, s18, 31
	s_lshl_b64 s[4:5], s[18:19], 20
	s_add_u32 s20, s93, s4
	s_addc_u32 s21, s81, s5
	s_bfe_i64 s[4:5], s[0:1], 0x100000
	s_lshl_b64 s[4:5], s[4:5], 20
	s_add_u32 s22, s60, s4
	s_addc_u32 s23, s61, s5
	s_add_i32 s28, s27, 0
	s_add_i32 m0, s28, 0x10000
	v_mov_b32_e32 v149, v1
	global_load_lds_dwordx4 v148, s[22:23]
	s_add_i32 m0, s28, 0x12000
	s_add_u32 s4, s22, 0x80000
	global_load_lds_dwordx4 v152, s[22:23]
	s_addc_u32 s5, s23, 0
	s_add_i32 m0, s28, 0x14000
	s_add_i32 s29, s28, 0x2000
	global_load_lds_dwordx4 v148, s[4:5]
	s_add_i32 m0, s28, 0x16000
	v_mov_b32_e32 v153, v1
	global_load_lds_dwordx4 v152, s[4:5]
	s_mov_b32 m0, s28
	s_add_u32 s4, s20, 0x80000
	global_load_lds_dwordx4 v146, s[20:21]
	s_mov_b32 m0, s29
	s_addc_u32 s5, s21, 0
	s_add_i32 s30, s28, 0x4000
	global_load_lds_dwordx4 v150, s[20:21]
	s_mov_b32 m0, s30
	s_add_i32 s31, s28, 0x6000
	global_load_lds_dwordx4 v146, s[4:5]
	s_mov_b32 m0, s31
	v_mov_b32_e32 v147, v1
	global_load_lds_dwordx4 v150, s[4:5]
	v_mov_b32_e32 v151, v1
	s_cmp_eq_u32 s9, 1
	v_lshl_add_u64 v[8:9], s[22:23], 0, v[148:149]
	v_lshl_add_u64 v[6:7], s[22:23], 0, v[152:153]
	v_lshl_add_u64 v[2:3], s[20:21], 0, v[146:147]
	s_cselect_b64 s[4:5], -1, 0
	s_cmp_lg_u32 s9, 1
	v_lshl_add_u64 v[4:5], s[20:21], 0, v[150:151]
	s_cbranch_scc1 .LBB0_657
	s_setprio 1
	s_barrier

; #define PG8_STAGE(bufoff, gbase, voff) do { _Pragma("unroll") for (int _i = 0; _i < 2; ++_i) \
;         __builtin_amdgcn_global_load_lds((const unsigned*)((const char*)(gbase) + (voff)[_i]), (LAS unsigned*)(lds + (bufoff) + ldsw + _i * 8192), 16, 0, 0); } while (0)
; #define PG8_LDA(dst, b, h) do { _Pragma("unroll") for (int m = 0; m < 4; ++m) _Pragma("unroll") for (int k = 0; k < 2; ++k) dst[m][k] = *(const LAS bf16x8*)(lds + PG8_SA(b, h) + aoff + m * 2048 + k * 1024); } while (0)
; #define PG8_LDB(dst, b, h) do { _Pragma("unroll") for (int n = 0; n < 2; ++n) _Pragma("unroll") for (int k = 0; k < 2; ++k) dst[n][k] = *(const LAS bf16x8*)(lds + PG8_SB(b, h) + boff + n * 2048 + k * 1024); } while (0)
; #define PG8_MMA(ai, bj, At, Bt) do { __builtin_amdgcn_s_setprio(1); _Pragma("unroll") for (int m = 0; m < 4; ++m) _Pragma("unroll") for (int n = 0; n < 2; ++n) _Pragma("unroll") for (int k = 0; k < 2; ++k) \
;         acc[ai][bj][m][n] = __builtin_amdgcn_mfma_f32_16x16x32_bf16(Bt[n][k], At[m][k], acc[ai][bj][m][n], 0, 0, 0); __builtin_amdgcn_s_setprio(0); } while (0)
; #define PG8_WAIT_V(n) asm volatile("s_waitcnt vmcnt(" #n ")" ::: "memory")
; #define PG8_WAIT_L(n) asm volatile("s_waitcnt lgkmcnt(" #n ")" ::: "memory")
; #define PG8_BAR __builtin_amdgcn_s_barrier()
; #define PG8_SCHED __builtin_amdgcn_sched_barrier(0)
; template <class Epi, bool ALIGN_EPI>
; __device__ __forceinline__ void gemm_phase(LAS unsigned char* lds, const int tid, const Gemm g, const StaticOrder& S, const Epi& E) {
;     ...
;             const bool last = (t == nt - 2);
;             const char* a1 = cA + (size_t)(t + 1) * kstepA;
;             const char* a2 = last ? nA : cA + (size_t)(t + 2) * kstepA; const char* b2 = last ? nB : cB + (size_t)(t + 2) * kstepB;
;             const char* a3 = a2 + kstepA; const char* b3 = b2 + kstepB;
;             PG8_LDB(B0, 0, 0); PG8_LDB(B1, 0, 1); PG8_SCHED; PG8_LDA(At, 0, 0); PG8_STAGE(PG8_SA(1, 1), a1 + hstepA, voffA);
;             PG8_WAIT_V(8); PG8_WAIT_L(0); PG8_BAR; PG8_MMA(0, 0, At, B0); PG8_MMA(0, 1, At, B1); PG8_BAR; PG8_SCHED;
;             PG8_LDA(At, 0, 1); PG8_STAGE(PG8_SB(0, 0), b2, voffB); PG8_STAGE(PG8_SB(0, 1), b2 + hstepB, voffB); PG8_STAGE(PG8_SA(0, 0), a2, voffA);
;             PG8_WAIT_V(8); PG8_WAIT_L(0); PG8_BAR; PG8_MMA(1, 0, At, B0); PG8_MMA(1, 1, At, B1); PG8_BAR; PG8_SCHED;
.LBB0_667:
	s_add_u32 s22, s20, 0xfff80080
	s_addc_u32 s23, s21, -1
	s_add_i32 s49, 0, 0x10000
	s_cmp_eq_u32 s19, 28
	s_cselect_b32 s25, s15, s23
	s_cselect_b32 s24, s14, s22
	v_add_u32_e32 v0, s49, v173
	s_cselect_b32 s23, s17, s13
	s_cselect_b32 s22, s16, s11
	s_add_i32 s52, 0, 0x14000
	ds_read_b128 v[130:133], v0
	ds_read_b128 v[134:137], v0 offset:1024
	ds_read_b128 v[138:141], v0 offset:2048
	ds_read_b128 v[142:145], v0 offset:3072
	v_add_u32_e32 v0, s52, v173
	ds_read_b128 v[158:161], v0
	ds_read_b128 v[162:165], v0 offset:1024
	ds_read_b128 v[166:169], v0 offset:2048
	ds_read_b128 v[178:181], v0 offset:3072
	v_lshl_add_u64 v[170:171], s[20:21], 0, v[156:157]
	s_add_i32 m0, s28, 0xc000
	ds_read_b128 v[182:185], v176
	ds_read_b128 v[186:189], v176 offset:1024
	ds_read_b128 v[190:193], v176 offset:2048
	ds_read_b128 v[208:211], v176 offset:3072
	ds_read_b128 v[212:215], v176 offset:4096
	ds_read_b128 v[216:219], v176 offset:5120
	ds_read_b128 v[220:223], v176 offset:6144
	ds_read_b128 v[240:243], v176 offset:7168
	global_load_lds_dwordx4 v[170:171], off
	v_lshl_add_u64 v[170:171], s[20:21], 0, v[154:155]
	s_add_i32 m0, s28, 0xe000
	s_nop 0
	global_load_lds_dwordx4 v[170:171], off
	s_sub_u32 s98, s20, 0x80000
	s_subb_u32 s99, s21, 0
	v_lshl_add_u64 v[170:171], s[98:99], 0, v[156:157]
	s_mov_b32 m0, s34
	s_nop 0
	global_load_lds_dwordx4 v[170:171], off
	v_lshl_add_u64 v[170:171], s[98:99], 0, v[154:155]
	s_mov_b32 m0, s35
	s_nop 0
	global_load_lds_dwordx4 v[170:171], off
	s_waitcnt vmcnt(8)
	s_waitcnt lgkmcnt(0)
	s_barrier
	s_waitcnt lgkmcnt(0)
	v_mfma_f32_16x16x32_bf16 v[126:129], v[130:133], v[182:185], v[126:129]
	v_mfma_f32_16x16x32_bf16 v[122:125], v[138:141], v[182:185], v[122:125]
	v_mfma_f32_16x16x32_bf16 v[118:121], v[130:133], v[190:193], v[118:121]
	v_mfma_f32_16x16x32_bf16 v[114:117], v[138:141], v[190:193], v[114:117]
	v_mfma_f32_16x16x32_bf16 v[102:105], v[130:133], v[212:215], v[102:105]
	v_mfma_f32_16x16x32_bf16 v[98:101], v[138:141], v[212:215], v[98:101]
	v_mfma_f32_16x16x32_bf16 v[86:89], v[130:133], v[220:223], v[86:89]
	v_mfma_f32_16x16x32_bf16 v[82:85], v[138:141], v[220:223], v[82:85]
	v_mfma_f32_16x16x32_bf16 v[126:129], v[134:137], v[186:189], v[126:129]
	v_mfma_f32_16x16x32_bf16 v[122:125], v[142:145], v[186:189], v[122:125]
	v_mfma_f32_16x16x32_bf16 v[118:121], v[134:137], v[208:211], v[118:121]
	v_mfma_f32_16x16x32_bf16 v[114:117], v[142:145], v[208:211], v[114:117]
	v_mfma_f32_16x16x32_bf16 v[102:105], v[134:137], v[216:219], v[102:105]
	v_mfma_f32_16x16x32_bf16 v[98:101], v[142:145], v[216:219], v[98:101]
	v_mfma_f32_16x16x32_bf16 v[86:89], v[134:137], v[240:243], v[86:89]
	v_mfma_f32_16x16x32_bf16 v[82:85], v[142:145], v[240:243], v[82:85]
	v_mfma_f32_16x16x32_bf16 v[110:113], v[158:161], v[182:185], v[110:113]
	v_mfma_f32_16x16x32_bf16 v[106:109], v[166:169], v[182:185], v[106:109]
	v_mfma_f32_16x16x32_bf16 v[94:97], v[158:161], v[190:193], v[94:97]
	v_mfma_f32_16x16x32_bf16 v[90:93], v[166:169], v[190:193], v[90:93]
	v_mfma_f32_16x16x32_bf16 v[78:81], v[158:161], v[212:215], v[78:81]
	v_mfma_f32_16x16x32_bf16 v[74:77], v[166:169], v[212:215], v[74:77]
	v_mfma_f32_16x16x32_bf16 v[70:73], v[158:161], v[220:223], v[70:73]
	v_mfma_f32_16x16x32_bf16 v[66:69], v[166:169], v[220:223], v[66:69]
	v_mfma_f32_16x16x32_bf16 v[110:113], v[162:165], v[186:189], v[110:113]
	v_mfma_f32_16x16x32_bf16 v[106:109], v[178:181], v[186:189], v[106:109]
	v_mfma_f32_16x16x32_bf16 v[94:97], v[162:165], v[208:211], v[94:97]
	v_mfma_f32_16x16x32_bf16 v[90:93], v[178:181], v[208:211], v[90:93]
	v_mfma_f32_16x16x32_bf16 v[78:81], v[162:165], v[216:219], v[78:81]
	v_mfma_f32_16x16x32_bf16 v[74:77], v[178:181], v[216:219], v[74:77]
	v_mfma_f32_16x16x32_bf16 v[70:73], v[162:165], v[240:243], v[70:73]
	v_mfma_f32_16x16x32_bf16 v[66:69], v[178:181], v[240:243], v[66:69]
	s_barrier
	s_add_i32 s49, s49, s27
	v_lshl_add_u64 v[170:171], s[22:23], 0, v[148:149]
	s_mov_b32 m0, s49
	ds_read_b128 v[182:185], v176 offset:16384
	ds_read_b128 v[186:189], v176 offset:17408
	ds_read_b128 v[190:193], v176 offset:18432
	ds_read_b128 v[208:211], v176 offset:19456
	ds_read_b128 v[212:215], v176 offset:20480
	ds_read_b128 v[216:219], v176 offset:21504
	ds_read_b128 v[220:223], v176 offset:22528
	ds_read_b128 v[240:243], v176 offset:23552
	global_load_lds_dwordx4 v[170:171], off
	s_add_i32 m0, s49, 0x2000
	s_add_u32 s54, s22, 0x80000
	v_lshl_add_u64 v[194:195], s[22:23], 0, v[152:153]
	s_addc_u32 s55, s23, 0
	s_add_i32 s49, s52, s27
	global_load_lds_dwordx4 v[194:195], off
	v_lshl_add_u64 v[224:225], s[54:55], 0, v[148:149]
	s_mov_b32 m0, s49
	v_lshl_add_u64 v[244:245], s[24:25], 0, v[150:151]
	global_load_lds_dwordx4 v[224:225], off
	v_lshl_add_u64 v[224:225], s[54:55], 0, v[152:153]
	s_add_i32 m0, s49, 0x2000
	s_nop 0
	global_load_lds_dwordx4 v[224:225], off
	v_lshl_add_u64 v[224:225], s[24:25], 0, v[146:147]
	s_waitcnt vmcnt(4)
	s_waitcnt lgkmcnt(0)
	s_barrier
; #define PG8_STAGE(bufoff, gbase, voff) do { _Pragma("unroll") for (int _i = 0; _i < 2; ++_i) \
;         __builtin_amdgcn_global_load_lds((const unsigned*)((const char*)(gbase) + (voff)[_i]), (LAS unsigned*)(lds + (bufoff) + ldsw + _i * 8192), 16, 0, 0); } while (0)
; #define PG8_LDA(dst, b, h) do { _Pragma("unroll") for (int m = 0; m < 4; ++m) _Pragma("unroll") for (int k = 0; k < 2; ++k) dst[m][k] = *(const LAS bf16x8*)(lds + PG8_SA(b, h) + aoff + m * 2048 + k * 1024); } while (0)
; #define PG8_LDB(dst, b, h) do { _Pragma("unroll") for (int n = 0; n < 2; ++n) _Pragma("unroll") for (int k = 0; k < 2; ++k) dst[n][k] = *(const LAS bf16x8*)(lds + PG8_SB(b, h) + boff + n * 2048 + k * 1024); } while (0)
; #define PG8_MMA(ai, bj, At, Bt) do { __builtin_amdgcn_s_setprio(1); _Pragma("unroll") for (int m = 0; m < 4; ++m) _Pragma("unroll") for (int n = 0; n < 2; ++n) _Pragma("unroll") for (int k = 0; k < 2; ++k) \
;         acc[ai][bj][m][n] = __builtin_amdgcn_mfma_f32_16x16x32_bf16(Bt[n][k], At[m][k], acc[ai][bj][m][n], 0, 0, 0); __builtin_amdgcn_s_setprio(0); } while (0)
; #define PG8_WAIT_V(n) asm volatile("s_waitcnt vmcnt(" #n ")" ::: "memory")
; #define PG8_WAIT_L(n) asm volatile("s_waitcnt lgkmcnt(" #n ")" ::: "memory")
; #define PG8_BAR __builtin_amdgcn_s_barrier()
; #define PG8_SCHED __builtin_amdgcn_sched_barrier(0)
; template <class Epi, bool ALIGN_EPI>
; __device__ __forceinline__ void gemm_phase(LAS unsigned char* lds, const int tid, const Gemm g, const StaticOrder& S, const Epi& E) {
;     ...
;             PG8_WAIT_V(8); PG8_WAIT_L(0); PG8_BAR; PG8_MMA(1, 0, At, B0); PG8_MMA(1, 1, At, B1); PG8_BAR; PG8_SCHED;
;             PG8_LDB(B0, 1, 0); PG8_LDB(B1, 1, 1); PG8_SCHED; PG8_LDA(At, 1, 0); PG8_STAGE(PG8_SA(0, 1), a2 + hstepA, voffA);
;             PG8_WAIT_V(8); PG8_WAIT_L(0); PG8_BAR; PG8_MMA(0, 0, At, B0); PG8_MMA(0, 1, At, B1); PG8_BAR; PG8_SCHED;
	s_waitcnt lgkmcnt(0)
	v_mfma_f32_16x16x32_bf16 v[62:65], v[130:133], v[182:185], v[62:65]
	v_mfma_f32_16x16x32_bf16 v[58:61], v[138:141], v[182:185], v[58:61]
	v_mfma_f32_16x16x32_bf16 v[54:57], v[130:133], v[190:193], v[54:57]
	v_mfma_f32_16x16x32_bf16 v[50:53], v[138:141], v[190:193], v[50:53]
	v_mfma_f32_16x16x32_bf16 v[38:41], v[130:133], v[212:215], v[38:41]
	v_mfma_f32_16x16x32_bf16 v[34:37], v[138:141], v[212:215], v[34:37]
	v_mfma_f32_16x16x32_bf16 v[22:25], v[130:133], v[220:223], v[22:25]
	v_mfma_f32_16x16x32_bf16 v[18:21], v[138:141], v[220:223], v[18:21]
	v_mfma_f32_16x16x32_bf16 v[62:65], v[134:137], v[186:189], v[62:65]
	v_mfma_f32_16x16x32_bf16 v[58:61], v[142:145], v[186:189], v[58:61]
	v_mfma_f32_16x16x32_bf16 v[54:57], v[134:137], v[208:211], v[54:57]
	v_mfma_f32_16x16x32_bf16 v[50:53], v[142:145], v[208:211], v[50:53]
	v_mfma_f32_16x16x32_bf16 v[38:41], v[134:137], v[216:219], v[38:41]
	v_mfma_f32_16x16x32_bf16 v[34:37], v[142:145], v[216:219], v[34:37]
	v_mfma_f32_16x16x32_bf16 v[22:25], v[134:137], v[240:243], v[22:25]
	v_mfma_f32_16x16x32_bf16 v[18:21], v[142:145], v[240:243], v[18:21]
	v_mfma_f32_16x16x32_bf16 v[46:49], v[158:161], v[182:185], v[46:49]
	v_mfma_f32_16x16x32_bf16 v[42:45], v[166:169], v[182:185], v[42:45]
	v_mfma_f32_16x16x32_bf16 v[30:33], v[158:161], v[190:193], v[30:33]
	v_mfma_f32_16x16x32_bf16 v[26:29], v[166:169], v[190:193], v[26:29]
	v_mfma_f32_16x16x32_bf16 v[14:17], v[158:161], v[212:215], v[14:17]
	v_mfma_f32_16x16x32_bf16 v[10:13], v[166:169], v[212:215], v[10:13]
	v_mfma_f32_16x16x32_bf16 v[6:9], v[158:161], v[220:223], v[6:9]
	v_mfma_f32_16x16x32_bf16 v[2:5], v[166:169], v[220:223], v[2:5]
	v_mfma_f32_16x16x32_bf16 v[46:49], v[162:165], v[186:189], v[46:49]
	v_mfma_f32_16x16x32_bf16 v[42:45], v[178:181], v[186:189], v[42:45]
	v_mfma_f32_16x16x32_bf16 v[30:33], v[162:165], v[208:211], v[30:33]
	v_mfma_f32_16x16x32_bf16 v[26:29], v[178:181], v[208:211], v[26:29]
	v_mfma_f32_16x16x32_bf16 v[14:17], v[162:165], v[216:219], v[14:17]
	v_mfma_f32_16x16x32_bf16 v[10:13], v[178:181], v[216:219], v[10:13]
	v_mfma_f32_16x16x32_bf16 v[6:9], v[162:165], v[240:243], v[6:9]
	v_mfma_f32_16x16x32_bf16 v[2:5], v[178:181], v[240:243], v[2:5]
	s_barrier
	s_add_i32 s49, 0, 0x18000
	v_add_u32_e32 v0, s49, v173
	s_add_i32 s52, 0, 0x1c000
	ds_read_b128 v[130:133], v0
	ds_read_b128 v[134:137], v0 offset:1024
	ds_read_b128 v[138:141], v0 offset:2048
	ds_read_b128 v[142:145], v0 offset:3072
	v_add_u32_e32 v0, s52, v173
	ds_read_b128 v[158:161], v0
	ds_read_b128 v[162:165], v0 offset:1024
	ds_read_b128 v[166:169], v0 offset:2048
	ds_read_b128 v[178:181], v0 offset:3072
	s_mov_b32 m0, s28
	s_nop 0
	global_load_lds_dwordx4 v[224:225], off
	s_mov_b32 m0, s29
	s_nop 0
	global_load_lds_dwordx4 v[244:245], off
	s_add_u32 s24, s24, 0x80000
	s_addc_u32 s25, s25, 0
	s_mov_b32 m0, s30
	v_lshl_add_u64 v[246:247], s[24:25], 0, v[146:147]
	ds_read_b128 v[182:185], v176 offset:32768
	ds_read_b128 v[186:189], v176 offset:33792
	ds_read_b128 v[190:193], v176 offset:34816
	ds_read_b128 v[208:211], v176 offset:35840
	ds_read_b128 v[212:215], v176 offset:36864
	ds_read_b128 v[216:219], v176 offset:37888
	ds_read_b128 v[220:223], v176 offset:38912
	ds_read_b128 v[240:243], v176 offset:39936
	global_load_lds_dwordx4 v[246:247], off
	v_lshl_add_u64 v[246:247], s[24:25], 0, v[150:151]
	s_mov_b32 m0, s31
	s_nop 0
	global_load_lds_dwordx4 v[246:247], off
	s_waitcnt vmcnt(8)
	s_waitcnt lgkmcnt(0)
	s_barrier
; #define PG8_STAGE(bufoff, gbase, voff) do { _Pragma("unroll") for (int _i = 0; _i < 2; ++_i) \
;         __builtin_amdgcn_global_load_lds((const unsigned*)((const char*)(gbase) + (voff)[_i]), (LAS unsigned*)(lds + (bufoff) + ldsw + _i * 8192), 16, 0, 0); } while (0)
; #define PG8_LDA(dst, b, h) do { _Pragma("unroll") for (int m = 0; m < 4; ++m) _Pragma("unroll") for (int k = 0; k < 2; ++k) dst[m][k] = *(const LAS bf16x8*)(lds + PG8_SA(b, h) + aoff + m * 2048 + k * 1024); } while (0)
; #define PG8_LDB(dst, b, h) do { _Pragma("unroll") for (int n = 0; n < 2; ++n) _Pragma("unroll") for (int k = 0; k < 2; ++k) dst[n][k] = *(const LAS bf16x8*)(lds + PG8_SB(b, h) + boff + n * 2048 + k * 1024); } while (0)
; #define PG8_MMA(ai, bj, At, Bt) do { __builtin_amdgcn_s_setprio(1); _Pragma("unroll") for (int m = 0; m < 4; ++m) _Pragma("unroll") for (int n = 0; n < 2; ++n) _Pragma("unroll") for (int k = 0; k < 2; ++k) \
;         acc[ai][bj][m][n] = __builtin_amdgcn_mfma_f32_16x16x32_bf16(Bt[n][k], At[m][k], acc[ai][bj][m][n], 0, 0, 0); __builtin_amdgcn_s_setprio(0); } while (0)
; #define PG8_WAIT_V(n) asm volatile("s_waitcnt vmcnt(" #n ")" ::: "memory")
; #define PG8_WAIT_L(n) asm volatile("s_waitcnt lgkmcnt(" #n ")" ::: "memory")
; #define PG8_BAR __builtin_amdgcn_s_barrier()
; #define PG8_SCHED __builtin_amdgcn_sched_barrier(0)
; template <class Epi, bool ALIGN_EPI>
; __device__ __forceinline__ void gemm_phase(LAS unsigned char* lds, const int tid, const Gemm g, const StaticOrder& S, const Epi& E) {
;     ...
;             PG8_WAIT_V(8); PG8_WAIT_L(0); PG8_BAR; PG8_MMA(1, 0, At, B0); PG8_MMA(1, 1, At, B1); PG8_BAR; PG8_SCHED;
;             PG8_LDB(B0, 1, 0); PG8_LDB(B1, 1, 1); PG8_SCHED; PG8_LDA(At, 1, 0); PG8_STAGE(PG8_SA(0, 1), a2 + hstepA, voffA);
;             PG8_WAIT_V(8); PG8_WAIT_L(0); PG8_BAR; PG8_MMA(0, 0, At, B0); PG8_MMA(0, 1, At, B1); PG8_BAR; PG8_SCHED;
;             PG8_LDA(At, 1, 1); PG8_STAGE(PG8_SB(1, 0), b3, voffB); PG8_STAGE(PG8_SB(1, 1), b3 + hstepB, voffB); PG8_STAGE(PG8_SA(1, 0), a3, voffA);
;             PG8_WAIT_V(8); PG8_WAIT_L(0); PG8_BAR; PG8_MMA(1, 0, At, B0); PG8_MMA(1, 1, At, B1); PG8_BAR; PG8_SCHED;
;         }
;         if constexpr (ALIGN_EPI) { if (wr == 0) PG8_BAR; }
	s_waitcnt lgkmcnt(0)
	v_mfma_f32_16x16x32_bf16 v[126:129], v[130:133], v[182:185], v[126:129]
	v_mfma_f32_16x16x32_bf16 v[122:125], v[138:141], v[182:185], v[122:125]
	v_mfma_f32_16x16x32_bf16 v[118:121], v[130:133], v[190:193], v[118:121]
	v_mfma_f32_16x16x32_bf16 v[114:117], v[138:141], v[190:193], v[114:117]
	v_mfma_f32_16x16x32_bf16 v[102:105], v[130:133], v[212:215], v[102:105]
	v_mfma_f32_16x16x32_bf16 v[98:101], v[138:141], v[212:215], v[98:101]
	v_mfma_f32_16x16x32_bf16 v[86:89], v[130:133], v[220:223], v[86:89]
	v_mfma_f32_16x16x32_bf16 v[82:85], v[138:141], v[220:223], v[82:85]
	v_mfma_f32_16x16x32_bf16 v[126:129], v[134:137], v[186:189], v[126:129]
	v_mfma_f32_16x16x32_bf16 v[122:125], v[142:145], v[186:189], v[122:125]
	v_mfma_f32_16x16x32_bf16 v[118:121], v[134:137], v[208:211], v[118:121]
	v_mfma_f32_16x16x32_bf16 v[114:117], v[142:145], v[208:211], v[114:117]
	v_mfma_f32_16x16x32_bf16 v[102:105], v[134:137], v[216:219], v[102:105]
	v_mfma_f32_16x16x32_bf16 v[98:101], v[142:145], v[216:219], v[98:101]
	v_mfma_f32_16x16x32_bf16 v[86:89], v[134:137], v[240:243], v[86:89]
	v_mfma_f32_16x16x32_bf16 v[82:85], v[142:145], v[240:243], v[82:85]
	v_mfma_f32_16x16x32_bf16 v[110:113], v[158:161], v[182:185], v[110:113]
	v_mfma_f32_16x16x32_bf16 v[106:109], v[166:169], v[182:185], v[106:109]
	v_mfma_f32_16x16x32_bf16 v[94:97], v[158:161], v[190:193], v[94:97]
	v_mfma_f32_16x16x32_bf16 v[90:93], v[166:169], v[190:193], v[90:93]
	v_mfma_f32_16x16x32_bf16 v[78:81], v[158:161], v[212:215], v[78:81]
	v_mfma_f32_16x16x32_bf16 v[74:77], v[166:169], v[212:215], v[74:77]
	v_mfma_f32_16x16x32_bf16 v[70:73], v[158:161], v[220:223], v[70:73]
	v_mfma_f32_16x16x32_bf16 v[66:69], v[166:169], v[220:223], v[66:69]
	v_mfma_f32_16x16x32_bf16 v[110:113], v[162:165], v[186:189], v[110:113]
	v_mfma_f32_16x16x32_bf16 v[106:109], v[178:181], v[186:189], v[106:109]
	v_mfma_f32_16x16x32_bf16 v[94:97], v[162:165], v[208:211], v[94:97]
	v_mfma_f32_16x16x32_bf16 v[90:93], v[178:181], v[208:211], v[90:93]
	v_mfma_f32_16x16x32_bf16 v[78:81], v[162:165], v[216:219], v[78:81]
	v_mfma_f32_16x16x32_bf16 v[74:77], v[178:181], v[216:219], v[74:77]
	v_mfma_f32_16x16x32_bf16 v[70:73], v[162:165], v[240:243], v[70:73]
	v_mfma_f32_16x16x32_bf16 v[66:69], v[178:181], v[240:243], v[66:69]
	s_barrier
	s_add_i32 s24, s49, s27
	v_lshl_add_u64 v[170:171], v[170:171], 0, s[42:43]
	s_mov_b32 m0, s24
	ds_read_b128 v[182:185], v176 offset:49152
	ds_read_b128 v[186:189], v176 offset:50176
	ds_read_b128 v[190:193], v176 offset:51200
	ds_read_b128 v[208:211], v176 offset:52224
	ds_read_b128 v[212:215], v176 offset:53248
	ds_read_b128 v[216:219], v176 offset:54272
	ds_read_b128 v[220:223], v176 offset:55296
	ds_read_b128 v[240:243], v176 offset:56320
	global_load_lds_dwordx4 v[170:171], off
	s_add_i32 m0, s24, 0x2000
	s_add_u32 s22, s22, 0x80080
	v_lshl_add_u64 v[170:171], v[194:195], 0, s[42:43]
	s_addc_u32 s23, s23, 0
	s_add_i32 s24, s52, s27
	global_load_lds_dwordx4 v[170:171], off
	v_lshl_add_u64 v[170:171], s[22:23], 0, v[148:149]
	s_mov_b32 m0, s24
	s_nop 0
	global_load_lds_dwordx4 v[170:171], off
	v_lshl_add_u64 v[170:171], s[22:23], 0, v[152:153]
	s_add_i32 m0, s24, 0x2000
	s_nop 0
	global_load_lds_dwordx4 v[170:171], off
	s_waitcnt vmcnt(4)
	s_waitcnt lgkmcnt(0)
	s_barrier
	s_waitcnt lgkmcnt(0)
	v_mfma_f32_16x16x32_bf16 v[62:65], v[130:133], v[182:185], v[62:65]
	v_mfma_f32_16x16x32_bf16 v[58:61], v[138:141], v[182:185], v[58:61]
	v_mfma_f32_16x16x32_bf16 v[54:57], v[130:133], v[190:193], v[54:57]
	v_mfma_f32_16x16x32_bf16 v[50:53], v[138:141], v[190:193], v[50:53]
	v_mfma_f32_16x16x32_bf16 v[38:41], v[130:133], v[212:215], v[38:41]
	v_mfma_f32_16x16x32_bf16 v[34:37], v[138:141], v[212:215], v[34:37]
	v_mfma_f32_16x16x32_bf16 v[22:25], v[130:133], v[220:223], v[22:25]
	v_mfma_f32_16x16x32_bf16 v[18:21], v[138:141], v[220:223], v[18:21]
	v_mfma_f32_16x16x32_bf16 v[62:65], v[134:137], v[186:189], v[62:65]
	v_mfma_f32_16x16x32_bf16 v[58:61], v[142:145], v[186:189], v[58:61]
	v_mfma_f32_16x16x32_bf16 v[54:57], v[134:137], v[208:211], v[54:57]
	v_mfma_f32_16x16x32_bf16 v[50:53], v[142:145], v[208:211], v[50:53]
	v_mfma_f32_16x16x32_bf16 v[38:41], v[134:137], v[216:219], v[38:41]
	v_mfma_f32_16x16x32_bf16 v[34:37], v[142:145], v[216:219], v[34:37]
	v_mfma_f32_16x16x32_bf16 v[22:25], v[134:137], v[240:243], v[22:25]
	v_mfma_f32_16x16x32_bf16 v[18:21], v[142:145], v[240:243], v[18:21]
	v_mfma_f32_16x16x32_bf16 v[46:49], v[158:161], v[182:185], v[46:49]
	v_mfma_f32_16x16x32_bf16 v[42:45], v[166:169], v[182:185], v[42:45]
	v_mfma_f32_16x16x32_bf16 v[30:33], v[158:161], v[190:193], v[30:33]
	v_mfma_f32_16x16x32_bf16 v[26:29], v[166:169], v[190:193], v[26:29]
	v_mfma_f32_16x16x32_bf16 v[14:17], v[158:161], v[212:215], v[14:17]
	v_mfma_f32_16x16x32_bf16 v[10:13], v[166:169], v[212:215], v[10:13]
	v_mfma_f32_16x16x32_bf16 v[6:9], v[158:161], v[220:223], v[6:9]
	v_mfma_f32_16x16x32_bf16 v[2:5], v[166:169], v[220:223], v[2:5]
	v_mfma_f32_16x16x32_bf16 v[46:49], v[162:165], v[186:189], v[46:49]
	v_mfma_f32_16x16x32_bf16 v[42:45], v[178:181], v[186:189], v[42:45]
	v_mfma_f32_16x16x32_bf16 v[30:33], v[162:165], v[208:211], v[30:33]
	v_mfma_f32_16x16x32_bf16 v[26:29], v[178:181], v[208:211], v[26:29]
	v_mfma_f32_16x16x32_bf16 v[14:17], v[162:165], v[216:219], v[14:17]
	v_mfma_f32_16x16x32_bf16 v[10:13], v[178:181], v[216:219], v[10:13]
	v_mfma_f32_16x16x32_bf16 v[6:9], v[162:165], v[240:243], v[6:9]
	v_mfma_f32_16x16x32_bf16 v[2:5], v[178:181], v[240:243], v[2:5]
	s_barrier
	s_add_i32 s19, s19, 2
	s_add_u32 s11, s11, 0x100
	s_addc_u32 s13, s13, 0
	s_add_u32 s20, s20, 0x100
	s_addc_u32 s21, s21, 0
	s_cmp_gt_u32 s19, 29
	s_cbranch_scc0 .LBB0_667
	s_and_b64 vcc, exec, s[8:9]
	s_cbranch_vccz .LBB0_670
	s_barrier
